# ffn/ple rmsnorm fused: phases 7/10 epilogues (LDS-transposed, row-contiguous) write bf16(x*gain) + row sum-of-squares partials; phases 9/12 scale acc by rs; norm phases + 2 barriers removed
# speedup vs baseline: 1.1939x; 1.0228x over previous
.LBB0_2144:
	s_lshl_b32 s4, s5, 7
	s_ashr_i32 s5, s4, 31
	s_lshl_b32 s0, s6, 7
	s_lshl_b64 s[6:7], s[4:5], 11
	v_mov_b32_e32 v0, v161
	s_add_u32 s6, s10, s6
	s_waitcnt vmcnt(8)
	v_mov_b32_e32 v49, v186
	s_addc_u32 s7, s11, s7
	s_ashr_i32 s1, s0, 31
	s_lshl_b64 s[8:9], s[0:1], 11
	v_lshlrev_b32_e32 v16, 4, v49
	v_ashrrev_i32_e32 v50, 3, v49
	v_and_b32_e32 v48, 0x70, v16
	s_add_u32 s8, s12, s8
	v_lshl_or_b32 v168, v50, 11, v48
	s_addc_u32 s9, s13, s9
	v_add_u32_e32 v169, 0x10000, v168
	v_add_u32_e32 v170, 0x20000, v168
	v_add_u32_e32 v171, 0x30000, v168
	s_barrier
	global_load_dwordx4 v[16:19], v168, s[6:7]
	global_load_dwordx4 v[20:23], v169, s[6:7]
	global_load_dwordx4 v[24:27], v170, s[6:7]
	global_load_dwordx4 v[28:31], v171, s[6:7]
	global_load_dwordx4 v[32:35], v168, s[8:9]
	global_load_dwordx4 v[36:39], v169, s[8:9]
	global_load_dwordx4 v[40:43], v170, s[8:9]
	global_load_dwordx4 v[44:47], v171, s[8:9]
	v_mad_u64_u32 v[130:131], s[16:17], v50, s43, v[48:49]
	v_mov_b32_e32 v1, v0
	v_mov_b32_e32 v2, v0
	v_mov_b32_e32 v3, v0
	v_mov_b32_e32 v4, v0
	v_mov_b32_e32 v5, v0
	v_mov_b32_e32 v6, v0
	v_mov_b32_e32 v7, v0
	s_waitcnt vmcnt(8)
	v_mov_b32_e32 v8, v0
	v_mov_b32_e32 v9, v0
	v_mov_b32_e32 v10, v0
	v_mov_b32_e32 v11, v0
	v_mov_b32_e32 v12, v0
	v_mov_b32_e32 v13, v0
	v_mov_b32_e32 v14, v0
	v_mov_b32_e32 v15, v0
	s_waitcnt vmcnt(7)
	ds_write_b128 v130, v[16:19]
	s_waitcnt vmcnt(6)
	ds_write_b128 v130, v[20:23] offset:4608
	s_waitcnt vmcnt(5)
	ds_write_b128 v130, v[24:27] offset:9216
	s_waitcnt vmcnt(4)
	ds_write_b128 v130, v[28:31] offset:13824
	s_waitcnt vmcnt(3)
	ds_write_b128 v130, v[32:35] offset:36864
	s_waitcnt vmcnt(2)
	ds_write_b128 v130, v[36:39] offset:41472
	s_waitcnt vmcnt(1)
	ds_write_b128 v130, v[40:43] offset:46080
	s_waitcnt vmcnt(0)
	ds_write_b128 v130, v[44:47] offset:50688
	global_load_dwordx4 v[96:99], v168, s[6:7] offset:128
	global_load_dwordx4 v[100:103], v169, s[6:7] offset:128
	global_load_dwordx4 v[104:107], v170, s[6:7] offset:128
	global_load_dwordx4 v[108:111], v171, s[6:7] offset:128
	global_load_dwordx4 v[64:67], v168, s[8:9] offset:128
	global_load_dwordx4 v[68:71], v169, s[8:9] offset:128
	global_load_dwordx4 v[72:75], v170, s[8:9] offset:128
	global_load_dwordx4 v[76:79], v171, s[8:9] offset:128
	v_lshrrev_b32_e32 v18, 1, v49
	v_and_b32_e32 v17, 0x5f, v49
	v_and_b32_e32 v16, 16, v18
	v_mad_u32_u24 v131, v17, s43, v16
	v_and_b32_e32 v17, 31, v49
	v_and_or_b32 v17, v18, s44, v17
	v_mad_u64_u32 v[132:133], s[16:17], v17, s43, v[16:17]
	s_waitcnt lgkmcnt(0)
	s_barrier
	ds_read_b128 v[16:19], v132
	ds_read_b128 v[84:87], v131 offset:41472
	ds_read_b128 v[80:83], v132 offset:4608
	ds_read_b128 v[172:175], v132 offset:32
	s_waitcnt lgkmcnt(2)
	v_mfma_f32_32x32x16_bf16 v[32:47], v[84:87], v[16:19], v[0:15]
	ds_read_b128 v[88:91], v131 offset:36864
	ds_read_b128 v[176:179], v132 offset:4640
	ds_read_b128 v[180:183], v131 offset:36896
	ds_read_b128 v[196:199], v131 offset:41504
	v_add_u32_e32 v133, 0xd800, v130
	s_waitcnt lgkmcnt(3)
	v_mfma_f32_32x32x16_bf16 v[48:63], v[88:91], v[16:19], v[0:15]
	v_mfma_f32_32x32x16_bf16 v[16:31], v[88:91], v[80:83], v[0:15]
	v_mfma_f32_32x32x16_bf16 v[0:15], v[84:87], v[80:83], v[0:15]
	s_waitcnt lgkmcnt(1)
	v_mfma_f32_32x32x16_bf16 v[48:63], v[180:183], v[172:175], v[48:63]
	s_waitcnt lgkmcnt(0)
	v_mfma_f32_32x32x16_bf16 v[32:47], v[196:199], v[172:175], v[32:47]
	v_mfma_f32_32x32x16_bf16 v[16:31], v[180:183], v[176:179], v[16:31]
	v_mfma_f32_32x32x16_bf16 v[0:15], v[196:199], v[176:179], v[0:15]
	ds_read_b128 v[200:203], v132 offset:64
	ds_read_b128 v[210:213], v132 offset:4672
	ds_read_b128 v[214:217], v131 offset:36928
	ds_read_b128 v[218:221], v131 offset:41536
	s_waitcnt lgkmcnt(1)
	v_mfma_f32_32x32x16_bf16 v[48:63], v[214:217], v[200:203], v[48:63]
	s_waitcnt lgkmcnt(0)
	v_mfma_f32_32x32x16_bf16 v[32:47], v[218:221], v[200:203], v[32:47]
	v_mfma_f32_32x32x16_bf16 v[16:31], v[214:217], v[210:213], v[16:31]
	v_mfma_f32_32x32x16_bf16 v[0:15], v[218:221], v[210:213], v[0:15]
	global_load_dwordx4 v[112:115], v168, s[6:7] offset:256
	global_load_dwordx4 v[116:119], v169, s[6:7] offset:256
	global_load_dwordx4 v[120:123], v170, s[6:7] offset:256
	global_load_dwordx4 v[124:127], v171, s[6:7] offset:256
	global_load_dwordx4 v[80:83], v168, s[8:9] offset:256
	global_load_dwordx4 v[84:87], v169, s[8:9] offset:256
	global_load_dwordx4 v[88:91], v170, s[8:9] offset:256
	global_load_dwordx4 v[92:95], v171, s[8:9] offset:256
	s_waitcnt vmcnt(15)
	ds_write_b128 v130, v[96:99] offset:18432
	s_waitcnt vmcnt(14)
	ds_write_b128 v130, v[100:103] offset:23040
	s_waitcnt vmcnt(13)
	ds_write_b128 v130, v[104:107] offset:27648
	s_waitcnt vmcnt(12)
	ds_write_b128 v130, v[108:111] offset:32256
	ds_read_b128 v[96:99], v132 offset:96
	ds_read_b128 v[100:103], v132 offset:4704
	ds_read_b128 v[104:107], v131 offset:36960
	ds_read_b128 v[108:111], v131 offset:41568
	s_waitcnt vmcnt(11)
	ds_write_b128 v130, v[64:67] offset:55296
	s_waitcnt vmcnt(10)
	ds_write_b128 v130, v[68:71] offset:59904
	s_waitcnt vmcnt(9)
	ds_write_b128 v130, v[72:75] offset:64512
	s_waitcnt vmcnt(8)
	ds_write_b128 v133, v[76:79] offset:13824
	s_waitcnt lgkmcnt(5)
	v_mfma_f32_32x32x16_bf16 v[48:63], v[104:107], v[96:99], v[48:63]
	s_waitcnt lgkmcnt(0)
	s_barrier
	v_mfma_f32_32x32x16_bf16 v[32:47], v[108:111], v[96:99], v[32:47]
	v_mfma_f32_32x32x16_bf16 v[16:31], v[104:107], v[100:103], v[16:31]
	v_mfma_f32_32x32x16_bf16 v[0:15], v[108:111], v[100:103], v[0:15]
	ds_read_b128 v[64:67], v132 offset:23040
	ds_read_b128 v[72:75], v132 offset:18432
	ds_read_b128 v[68:71], v131 offset:59904
	ds_read_b128 v[100:103], v131 offset:55296
	ds_read_b128 v[76:79], v132 offset:18464
	ds_read_b128 v[96:99], v132 offset:23072
	ds_read_b128 v[104:107], v131 offset:55328
	ds_read_b128 v[108:111], v131 offset:59936
	s_waitcnt lgkmcnt(4)
	v_mfma_f32_32x32x16_bf16 v[48:63], v[100:103], v[72:75], v[48:63]
	v_mfma_f32_32x32x16_bf16 v[32:47], v[68:71], v[72:75], v[32:47]
	v_mfma_f32_32x32x16_bf16 v[16:31], v[100:103], v[64:67], v[16:31]
	v_mfma_f32_32x32x16_bf16 v[0:15], v[68:71], v[64:67], v[0:15]
	global_load_dwordx4 v[64:67], v168, s[6:7] offset:384
	global_load_dwordx4 v[68:71], v169, s[6:7] offset:384
	global_load_dwordx4 v[72:75], v170, s[6:7] offset:384
	global_load_dwordx4 v[100:103], v171, s[6:7] offset:384
	global_load_dwordx4 v[172:175], v168, s[8:9] offset:384
	global_load_dwordx4 v[176:179], v169, s[8:9] offset:384
	global_load_dwordx4 v[180:183], v170, s[8:9] offset:384
	global_load_dwordx4 v[196:199], v171, s[8:9] offset:384
	ds_read_b128 v[200:203], v132 offset:18496
	ds_read_b128 v[210:213], v132 offset:23104
	ds_read_b128 v[214:217], v131 offset:55360
	ds_read_b128 v[218:221], v131 offset:59968
	s_waitcnt vmcnt(15)
	ds_write_b128 v130, v[112:115]
	s_waitcnt vmcnt(14)
	ds_write_b128 v130, v[116:119] offset:4608
	s_waitcnt vmcnt(13)
	ds_write_b128 v130, v[120:123] offset:9216
	s_waitcnt vmcnt(12)
	ds_write_b128 v130, v[124:127] offset:13824
	s_waitcnt lgkmcnt(9)
	v_mfma_f32_32x32x16_bf16 v[48:63], v[104:107], v[76:79], v[48:63]
	s_waitcnt lgkmcnt(8)
	v_mfma_f32_32x32x16_bf16 v[32:47], v[108:111], v[76:79], v[32:47]
	v_mfma_f32_32x32x16_bf16 v[16:31], v[104:107], v[96:99], v[16:31]
	v_mfma_f32_32x32x16_bf16 v[0:15], v[108:111], v[96:99], v[0:15]
	ds_read_b128 v[76:79], v132 offset:18528
	ds_read_b128 v[96:99], v132 offset:23136
	ds_read_b128 v[104:107], v131 offset:55392
	ds_read_b128 v[108:111], v131 offset:60000
	s_waitcnt vmcnt(11)
	ds_write_b128 v130, v[80:83] offset:36864
	s_waitcnt vmcnt(10)
	ds_write_b128 v130, v[84:87] offset:41472
	s_waitcnt vmcnt(9)
	ds_write_b128 v130, v[88:91] offset:46080
	s_waitcnt vmcnt(8)
	ds_write_b128 v130, v[92:95] offset:50688
	s_waitcnt lgkmcnt(13)
	v_mfma_f32_32x32x16_bf16 v[48:63], v[214:217], v[200:203], v[48:63]
	s_waitcnt lgkmcnt(0)
	s_barrier
	v_mfma_f32_32x32x16_bf16 v[32:47], v[218:221], v[200:203], v[32:47]
	v_mfma_f32_32x32x16_bf16 v[16:31], v[214:217], v[210:213], v[16:31]
	v_mfma_f32_32x32x16_bf16 v[0:15], v[218:221], v[210:213], v[0:15]
	v_mfma_f32_32x32x16_bf16 v[48:63], v[104:107], v[76:79], v[48:63]
	v_mfma_f32_32x32x16_bf16 v[32:47], v[108:111], v[76:79], v[32:47]
	v_mfma_f32_32x32x16_bf16 v[16:31], v[104:107], v[96:99], v[16:31]
	v_mfma_f32_32x32x16_bf16 v[0:15], v[108:111], v[96:99], v[0:15]
	ds_read_b128 v[76:79], v132 offset:4608
	ds_read_b128 v[84:87], v132
	ds_read_b128 v[80:83], v131 offset:41472
	ds_read_b128 v[96:99], v131 offset:36864
	ds_read_b128 v[88:91], v132 offset:32
	ds_read_b128 v[92:95], v132 offset:4640
	ds_read_b128 v[104:107], v131 offset:36896
	ds_read_b128 v[108:111], v131 offset:41504
	s_waitcnt lgkmcnt(4)
	v_mfma_f32_32x32x16_bf16 v[48:63], v[96:99], v[84:87], v[48:63]
	v_mfma_f32_32x32x16_bf16 v[32:47], v[80:83], v[84:87], v[32:47]
	v_mfma_f32_32x32x16_bf16 v[16:31], v[96:99], v[76:79], v[16:31]
	v_mfma_f32_32x32x16_bf16 v[0:15], v[80:83], v[76:79], v[0:15]
	global_load_dwordx4 v[76:79], v168, s[6:7] offset:512
	global_load_dwordx4 v[80:83], v169, s[6:7] offset:512
	global_load_dwordx4 v[84:87], v170, s[6:7] offset:512
	global_load_dwordx4 v[96:99], v171, s[6:7] offset:512
	global_load_dwordx4 v[112:115], v168, s[8:9] offset:512
	global_load_dwordx4 v[116:119], v169, s[8:9] offset:512
	global_load_dwordx4 v[120:123], v170, s[8:9] offset:512
	global_load_dwordx4 v[124:127], v171, s[8:9] offset:512
	ds_read_b128 v[200:203], v132 offset:64
	ds_read_b128 v[210:213], v132 offset:4672
	ds_read_b128 v[214:217], v131 offset:36928
	ds_read_b128 v[218:221], v131 offset:41536
	s_waitcnt vmcnt(15)
	ds_write_b128 v130, v[64:67] offset:18432
	s_waitcnt vmcnt(14)
	ds_write_b128 v130, v[68:71] offset:23040
	s_waitcnt vmcnt(13)
	ds_write_b128 v130, v[72:75] offset:27648
	s_waitcnt vmcnt(12)
	ds_write_b128 v130, v[100:103] offset:32256
	s_waitcnt lgkmcnt(9)
	v_mfma_f32_32x32x16_bf16 v[48:63], v[104:107], v[88:91], v[48:63]
	s_waitcnt lgkmcnt(8)
	v_mfma_f32_32x32x16_bf16 v[32:47], v[108:111], v[88:91], v[32:47]
	v_mfma_f32_32x32x16_bf16 v[16:31], v[104:107], v[92:95], v[16:31]
	v_mfma_f32_32x32x16_bf16 v[0:15], v[108:111], v[92:95], v[0:15]
	ds_read_b128 v[64:67], v132 offset:96
	ds_read_b128 v[68:71], v132 offset:4704
	ds_read_b128 v[72:75], v131 offset:36960
	ds_read_b128 v[88:91], v131 offset:41568
	s_waitcnt vmcnt(11)
	ds_write_b128 v130, v[172:175] offset:55296
	s_waitcnt vmcnt(10)
	ds_write_b128 v130, v[176:179] offset:59904
	s_waitcnt vmcnt(9)
	ds_write_b128 v130, v[180:183] offset:64512
	s_waitcnt vmcnt(8)
	ds_write_b128 v133, v[196:199] offset:13824
	s_waitcnt lgkmcnt(13)
	v_mfma_f32_32x32x16_bf16 v[48:63], v[214:217], v[200:203], v[48:63]
	s_waitcnt lgkmcnt(0)
	s_barrier
	v_mfma_f32_32x32x16_bf16 v[32:47], v[218:221], v[200:203], v[32:47]
	v_mfma_f32_32x32x16_bf16 v[16:31], v[214:217], v[210:213], v[16:31]
	v_mfma_f32_32x32x16_bf16 v[0:15], v[218:221], v[210:213], v[0:15]
	v_mfma_f32_32x32x16_bf16 v[48:63], v[72:75], v[64:67], v[48:63]
	v_mfma_f32_32x32x16_bf16 v[32:47], v[88:91], v[64:67], v[32:47]
	v_mfma_f32_32x32x16_bf16 v[16:31], v[72:75], v[68:71], v[16:31]
	v_mfma_f32_32x32x16_bf16 v[0:15], v[88:91], v[68:71], v[0:15]
	ds_read_b128 v[64:67], v132 offset:23040
	ds_read_b128 v[72:75], v132 offset:18432
	ds_read_b128 v[68:71], v131 offset:59904
	ds_read_b128 v[100:103], v131 offset:55296
	ds_read_b128 v[88:91], v132 offset:18464
	ds_read_b128 v[92:95], v132 offset:23072
	ds_read_b128 v[104:107], v131 offset:55328
	ds_read_b128 v[108:111], v131 offset:59936
	s_waitcnt lgkmcnt(4)
	v_mfma_f32_32x32x16_bf16 v[48:63], v[100:103], v[72:75], v[48:63]
	v_mfma_f32_32x32x16_bf16 v[32:47], v[68:71], v[72:75], v[32:47]
	v_mfma_f32_32x32x16_bf16 v[16:31], v[100:103], v[64:67], v[16:31]
	v_mfma_f32_32x32x16_bf16 v[0:15], v[68:71], v[64:67], v[0:15]
	global_load_dwordx4 v[64:67], v168, s[6:7] offset:640
	global_load_dwordx4 v[68:71], v169, s[6:7] offset:640
	global_load_dwordx4 v[72:75], v170, s[6:7] offset:640
	global_load_dwordx4 v[100:103], v171, s[6:7] offset:640
	global_load_dwordx4 v[172:175], v168, s[8:9] offset:640
	global_load_dwordx4 v[176:179], v169, s[8:9] offset:640
	global_load_dwordx4 v[180:183], v170, s[8:9] offset:640
	global_load_dwordx4 v[196:199], v171, s[8:9] offset:640
	ds_read_b128 v[200:203], v132 offset:18496
	ds_read_b128 v[210:213], v132 offset:23104
	ds_read_b128 v[214:217], v131 offset:55360
	ds_read_b128 v[218:221], v131 offset:59968
	s_waitcnt vmcnt(15)
	ds_write_b128 v130, v[76:79]
	s_waitcnt vmcnt(14)
	ds_write_b128 v130, v[80:83] offset:4608
	s_waitcnt vmcnt(13)
	ds_write_b128 v130, v[84:87] offset:9216
	s_waitcnt vmcnt(12)
	ds_write_b128 v130, v[96:99] offset:13824
	s_waitcnt lgkmcnt(9)
	v_mfma_f32_32x32x16_bf16 v[48:63], v[104:107], v[88:91], v[48:63]
	s_waitcnt lgkmcnt(8)
	v_mfma_f32_32x32x16_bf16 v[32:47], v[108:111], v[88:91], v[32:47]
	v_mfma_f32_32x32x16_bf16 v[16:31], v[104:107], v[92:95], v[16:31]
	v_mfma_f32_32x32x16_bf16 v[0:15], v[108:111], v[92:95], v[0:15]
	ds_read_b128 v[76:79], v132 offset:18528
	ds_read_b128 v[80:83], v132 offset:23136
	ds_read_b128 v[84:87], v131 offset:55392
	ds_read_b128 v[88:91], v131 offset:60000
	s_waitcnt vmcnt(11)
	ds_write_b128 v130, v[112:115] offset:36864
	s_waitcnt vmcnt(10)
	ds_write_b128 v130, v[116:119] offset:41472
	s_waitcnt vmcnt(9)
	ds_write_b128 v130, v[120:123] offset:46080
	s_waitcnt vmcnt(8)
	ds_write_b128 v130, v[124:127] offset:50688
	s_waitcnt lgkmcnt(13)
	v_mfma_f32_32x32x16_bf16 v[48:63], v[214:217], v[200:203], v[48:63]
	s_waitcnt lgkmcnt(0)
	s_barrier
	v_mfma_f32_32x32x16_bf16 v[32:47], v[218:221], v[200:203], v[32:47]
	v_mfma_f32_32x32x16_bf16 v[16:31], v[214:217], v[210:213], v[16:31]
	v_mfma_f32_32x32x16_bf16 v[0:15], v[218:221], v[210:213], v[0:15]
	v_mfma_f32_32x32x16_bf16 v[48:63], v[84:87], v[76:79], v[48:63]
	v_mfma_f32_32x32x16_bf16 v[32:47], v[88:91], v[76:79], v[32:47]
	v_mfma_f32_32x32x16_bf16 v[16:31], v[84:87], v[80:83], v[16:31]
	v_mfma_f32_32x32x16_bf16 v[0:15], v[88:91], v[80:83], v[0:15]
	ds_read_b128 v[76:79], v132 offset:4608
	ds_read_b128 v[84:87], v132
	ds_read_b128 v[80:83], v131 offset:41472
	ds_read_b128 v[96:99], v131 offset:36864
	ds_read_b128 v[88:91], v132 offset:32
	ds_read_b128 v[92:95], v132 offset:4640
	ds_read_b128 v[104:107], v131 offset:36896
	ds_read_b128 v[108:111], v131 offset:41504
	s_waitcnt lgkmcnt(4)
	v_mfma_f32_32x32x16_bf16 v[48:63], v[96:99], v[84:87], v[48:63]
	v_mfma_f32_32x32x16_bf16 v[32:47], v[80:83], v[84:87], v[32:47]
	v_mfma_f32_32x32x16_bf16 v[16:31], v[96:99], v[76:79], v[16:31]
	v_mfma_f32_32x32x16_bf16 v[0:15], v[80:83], v[76:79], v[0:15]
	global_load_dwordx4 v[76:79], v168, s[6:7] offset:768
	global_load_dwordx4 v[80:83], v169, s[6:7] offset:768
	global_load_dwordx4 v[84:87], v170, s[6:7] offset:768
	global_load_dwordx4 v[96:99], v171, s[6:7] offset:768
	global_load_dwordx4 v[112:115], v168, s[8:9] offset:768
	global_load_dwordx4 v[116:119], v169, s[8:9] offset:768
	global_load_dwordx4 v[120:123], v170, s[8:9] offset:768
	global_load_dwordx4 v[124:127], v171, s[8:9] offset:768
	ds_read_b128 v[200:203], v132 offset:64
	ds_read_b128 v[210:213], v132 offset:4672
	ds_read_b128 v[214:217], v131 offset:36928
	ds_read_b128 v[218:221], v131 offset:41536
	s_waitcnt vmcnt(15)
	ds_write_b128 v130, v[64:67] offset:18432
	s_waitcnt vmcnt(14)
	ds_write_b128 v130, v[68:71] offset:23040
	s_waitcnt vmcnt(13)
	ds_write_b128 v130, v[72:75] offset:27648
	s_waitcnt vmcnt(12)
	ds_write_b128 v130, v[100:103] offset:32256
	s_waitcnt lgkmcnt(9)
	v_mfma_f32_32x32x16_bf16 v[48:63], v[104:107], v[88:91], v[48:63]
	s_waitcnt lgkmcnt(8)
	v_mfma_f32_32x32x16_bf16 v[32:47], v[108:111], v[88:91], v[32:47]
	v_mfma_f32_32x32x16_bf16 v[16:31], v[104:107], v[92:95], v[16:31]
	v_mfma_f32_32x32x16_bf16 v[0:15], v[108:111], v[92:95], v[0:15]
	ds_read_b128 v[64:67], v132 offset:96
	ds_read_b128 v[68:71], v132 offset:4704
	ds_read_b128 v[72:75], v131 offset:36960
	ds_read_b128 v[88:91], v131 offset:41568
	s_waitcnt vmcnt(11)
	ds_write_b128 v130, v[172:175] offset:55296
	s_waitcnt vmcnt(10)
	ds_write_b128 v130, v[176:179] offset:59904
	s_waitcnt vmcnt(9)
	ds_write_b128 v130, v[180:183] offset:64512
	s_waitcnt vmcnt(8)
	ds_write_b128 v133, v[196:199] offset:13824
	s_waitcnt lgkmcnt(13)
	v_mfma_f32_32x32x16_bf16 v[48:63], v[214:217], v[200:203], v[48:63]
	s_waitcnt lgkmcnt(0)
	s_barrier
	v_mfma_f32_32x32x16_bf16 v[32:47], v[218:221], v[200:203], v[32:47]
	v_mfma_f32_32x32x16_bf16 v[16:31], v[214:217], v[210:213], v[16:31]
	v_mfma_f32_32x32x16_bf16 v[0:15], v[218:221], v[210:213], v[0:15]
	v_mfma_f32_32x32x16_bf16 v[48:63], v[72:75], v[64:67], v[48:63]
	v_mfma_f32_32x32x16_bf16 v[32:47], v[88:91], v[64:67], v[32:47]
	v_mfma_f32_32x32x16_bf16 v[16:31], v[72:75], v[68:71], v[16:31]
	v_mfma_f32_32x32x16_bf16 v[0:15], v[88:91], v[68:71], v[0:15]
	ds_read_b128 v[64:67], v132 offset:23040
	ds_read_b128 v[72:75], v132 offset:18432
	ds_read_b128 v[68:71], v131 offset:59904
	ds_read_b128 v[100:103], v131 offset:55296
	ds_read_b128 v[88:91], v132 offset:18464
	ds_read_b128 v[92:95], v132 offset:23072
	ds_read_b128 v[104:107], v131 offset:55328
	ds_read_b128 v[108:111], v131 offset:59936
	s_waitcnt lgkmcnt(4)
	v_mfma_f32_32x32x16_bf16 v[48:63], v[100:103], v[72:75], v[48:63]
	v_mfma_f32_32x32x16_bf16 v[32:47], v[68:71], v[72:75], v[32:47]
	v_mfma_f32_32x32x16_bf16 v[16:31], v[100:103], v[64:67], v[16:31]
	v_mfma_f32_32x32x16_bf16 v[0:15], v[68:71], v[64:67], v[0:15]
	global_load_dwordx4 v[64:67], v168, s[6:7] offset:896
	global_load_dwordx4 v[68:71], v169, s[6:7] offset:896
	global_load_dwordx4 v[72:75], v170, s[6:7] offset:896
	global_load_dwordx4 v[100:103], v171, s[6:7] offset:896
	global_load_dwordx4 v[172:175], v168, s[8:9] offset:896
	global_load_dwordx4 v[176:179], v169, s[8:9] offset:896
	global_load_dwordx4 v[180:183], v170, s[8:9] offset:896
	global_load_dwordx4 v[196:199], v171, s[8:9] offset:896
	ds_read_b128 v[200:203], v132 offset:18496
	ds_read_b128 v[210:213], v132 offset:23104
	ds_read_b128 v[214:217], v131 offset:55360
	ds_read_b128 v[218:221], v131 offset:59968
	s_waitcnt vmcnt(15)
	ds_write_b128 v130, v[76:79]
	s_waitcnt vmcnt(14)
	ds_write_b128 v130, v[80:83] offset:4608
	s_waitcnt vmcnt(13)
	ds_write_b128 v130, v[84:87] offset:9216
	s_waitcnt vmcnt(12)
	ds_write_b128 v130, v[96:99] offset:13824
	s_waitcnt lgkmcnt(9)
	v_mfma_f32_32x32x16_bf16 v[48:63], v[104:107], v[88:91], v[48:63]
	s_waitcnt lgkmcnt(8)
	v_mfma_f32_32x32x16_bf16 v[32:47], v[108:111], v[88:91], v[32:47]
	v_mfma_f32_32x32x16_bf16 v[16:31], v[104:107], v[92:95], v[16:31]
	v_mfma_f32_32x32x16_bf16 v[0:15], v[108:111], v[92:95], v[0:15]
	ds_read_b128 v[76:79], v132 offset:18528
	ds_read_b128 v[80:83], v132 offset:23136
	ds_read_b128 v[84:87], v131 offset:55392
	ds_read_b128 v[88:91], v131 offset:60000
	s_waitcnt vmcnt(11)
	ds_write_b128 v130, v[112:115] offset:36864
	s_waitcnt vmcnt(10)
	ds_write_b128 v130, v[116:119] offset:41472
	s_waitcnt vmcnt(9)
	ds_write_b128 v130, v[120:123] offset:46080
	s_waitcnt vmcnt(8)
	ds_write_b128 v130, v[124:127] offset:50688
	s_waitcnt lgkmcnt(13)
	v_mfma_f32_32x32x16_bf16 v[48:63], v[214:217], v[200:203], v[48:63]
	s_waitcnt lgkmcnt(0)
	s_barrier
	v_mfma_f32_32x32x16_bf16 v[32:47], v[218:221], v[200:203], v[32:47]
	v_mfma_f32_32x32x16_bf16 v[16:31], v[214:217], v[210:213], v[16:31]
	v_mfma_f32_32x32x16_bf16 v[0:15], v[218:221], v[210:213], v[0:15]
	v_mfma_f32_32x32x16_bf16 v[48:63], v[84:87], v[76:79], v[48:63]
	v_mfma_f32_32x32x16_bf16 v[32:47], v[88:91], v[76:79], v[32:47]
	v_mfma_f32_32x32x16_bf16 v[16:31], v[84:87], v[80:83], v[16:31]
	v_mfma_f32_32x32x16_bf16 v[0:15], v[88:91], v[80:83], v[0:15]
	ds_read_b128 v[76:79], v132 offset:4608
	ds_read_b128 v[84:87], v132
	ds_read_b128 v[80:83], v131 offset:41472
	ds_read_b128 v[96:99], v131 offset:36864
	ds_read_b128 v[88:91], v132 offset:32
	ds_read_b128 v[92:95], v132 offset:4640
	ds_read_b128 v[104:107], v131 offset:36896
	ds_read_b128 v[108:111], v131 offset:41504
	s_waitcnt lgkmcnt(4)
	v_mfma_f32_32x32x16_bf16 v[48:63], v[96:99], v[84:87], v[48:63]
	v_mfma_f32_32x32x16_bf16 v[32:47], v[80:83], v[84:87], v[32:47]
	v_mfma_f32_32x32x16_bf16 v[16:31], v[96:99], v[76:79], v[16:31]
	v_mfma_f32_32x32x16_bf16 v[0:15], v[80:83], v[76:79], v[0:15]
	global_load_dwordx4 v[76:79], v168, s[6:7] offset:1024
	global_load_dwordx4 v[80:83], v169, s[6:7] offset:1024
	global_load_dwordx4 v[84:87], v170, s[6:7] offset:1024
	global_load_dwordx4 v[96:99], v171, s[6:7] offset:1024
	global_load_dwordx4 v[112:115], v168, s[8:9] offset:1024
	global_load_dwordx4 v[116:119], v169, s[8:9] offset:1024
	global_load_dwordx4 v[120:123], v170, s[8:9] offset:1024
	global_load_dwordx4 v[124:127], v171, s[8:9] offset:1024
	ds_read_b128 v[200:203], v132 offset:64
	ds_read_b128 v[210:213], v132 offset:4672
	ds_read_b128 v[214:217], v131 offset:36928
	ds_read_b128 v[218:221], v131 offset:41536
	s_waitcnt vmcnt(15)
	ds_write_b128 v130, v[64:67] offset:18432
	s_waitcnt vmcnt(14)
	ds_write_b128 v130, v[68:71] offset:23040
	s_waitcnt vmcnt(13)
	ds_write_b128 v130, v[72:75] offset:27648
	s_waitcnt vmcnt(12)
	ds_write_b128 v130, v[100:103] offset:32256
	s_waitcnt lgkmcnt(9)
	v_mfma_f32_32x32x16_bf16 v[48:63], v[104:107], v[88:91], v[48:63]
	s_waitcnt lgkmcnt(8)
	v_mfma_f32_32x32x16_bf16 v[32:47], v[108:111], v[88:91], v[32:47]
	v_mfma_f32_32x32x16_bf16 v[16:31], v[104:107], v[92:95], v[16:31]
	v_mfma_f32_32x32x16_bf16 v[0:15], v[108:111], v[92:95], v[0:15]
	ds_read_b128 v[64:67], v132 offset:96
	ds_read_b128 v[68:71], v132 offset:4704
	ds_read_b128 v[72:75], v131 offset:36960
	ds_read_b128 v[88:91], v131 offset:41568
	s_waitcnt vmcnt(11)
	ds_write_b128 v130, v[172:175] offset:55296
	s_waitcnt vmcnt(10)
	ds_write_b128 v130, v[176:179] offset:59904
	s_waitcnt vmcnt(9)
	ds_write_b128 v130, v[180:183] offset:64512
	s_waitcnt vmcnt(8)
	ds_write_b128 v133, v[196:199] offset:13824
	s_waitcnt lgkmcnt(13)
	v_mfma_f32_32x32x16_bf16 v[48:63], v[214:217], v[200:203], v[48:63]
	s_waitcnt lgkmcnt(0)
	s_barrier
	v_mfma_f32_32x32x16_bf16 v[32:47], v[218:221], v[200:203], v[32:47]
	v_mfma_f32_32x32x16_bf16 v[16:31], v[214:217], v[210:213], v[16:31]
	v_mfma_f32_32x32x16_bf16 v[0:15], v[218:221], v[210:213], v[0:15]
	v_mfma_f32_32x32x16_bf16 v[48:63], v[72:75], v[64:67], v[48:63]
	v_mfma_f32_32x32x16_bf16 v[32:47], v[88:91], v[64:67], v[32:47]
	v_mfma_f32_32x32x16_bf16 v[16:31], v[72:75], v[68:71], v[16:31]
	v_mfma_f32_32x32x16_bf16 v[0:15], v[88:91], v[68:71], v[0:15]
	ds_read_b128 v[64:67], v132 offset:23040
	ds_read_b128 v[72:75], v132 offset:18432
	ds_read_b128 v[68:71], v131 offset:59904
	ds_read_b128 v[100:103], v131 offset:55296
	ds_read_b128 v[88:91], v132 offset:18464
	ds_read_b128 v[92:95], v132 offset:23072
	ds_read_b128 v[104:107], v131 offset:55328
	ds_read_b128 v[108:111], v131 offset:59936
	s_waitcnt lgkmcnt(4)
	v_mfma_f32_32x32x16_bf16 v[48:63], v[100:103], v[72:75], v[48:63]
	v_mfma_f32_32x32x16_bf16 v[32:47], v[68:71], v[72:75], v[32:47]
	v_mfma_f32_32x32x16_bf16 v[16:31], v[100:103], v[64:67], v[16:31]
	v_mfma_f32_32x32x16_bf16 v[0:15], v[68:71], v[64:67], v[0:15]
	global_load_dwordx4 v[64:67], v168, s[6:7] offset:1152
	global_load_dwordx4 v[68:71], v169, s[6:7] offset:1152
	global_load_dwordx4 v[72:75], v170, s[6:7] offset:1152
	global_load_dwordx4 v[100:103], v171, s[6:7] offset:1152
	global_load_dwordx4 v[172:175], v168, s[8:9] offset:1152
	global_load_dwordx4 v[176:179], v169, s[8:9] offset:1152
	global_load_dwordx4 v[180:183], v170, s[8:9] offset:1152
	global_load_dwordx4 v[196:199], v171, s[8:9] offset:1152
	ds_read_b128 v[200:203], v132 offset:18496
	ds_read_b128 v[210:213], v132 offset:23104
	ds_read_b128 v[214:217], v131 offset:55360
	ds_read_b128 v[218:221], v131 offset:59968
	s_waitcnt vmcnt(15)
	ds_write_b128 v130, v[76:79]
	s_waitcnt vmcnt(14)
	ds_write_b128 v130, v[80:83] offset:4608
	s_waitcnt vmcnt(13)
	ds_write_b128 v130, v[84:87] offset:9216
	s_waitcnt vmcnt(12)
	ds_write_b128 v130, v[96:99] offset:13824
	s_waitcnt lgkmcnt(9)
	v_mfma_f32_32x32x16_bf16 v[48:63], v[104:107], v[88:91], v[48:63]
	s_waitcnt lgkmcnt(8)
	v_mfma_f32_32x32x16_bf16 v[32:47], v[108:111], v[88:91], v[32:47]
	v_mfma_f32_32x32x16_bf16 v[16:31], v[104:107], v[92:95], v[16:31]
	v_mfma_f32_32x32x16_bf16 v[0:15], v[108:111], v[92:95], v[0:15]
	ds_read_b128 v[76:79], v132 offset:18528
	ds_read_b128 v[80:83], v132 offset:23136
	ds_read_b128 v[84:87], v131 offset:55392
	ds_read_b128 v[88:91], v131 offset:60000
	s_waitcnt vmcnt(11)
	ds_write_b128 v130, v[112:115] offset:36864
	s_waitcnt vmcnt(10)
	ds_write_b128 v130, v[116:119] offset:41472
	s_waitcnt vmcnt(9)
	ds_write_b128 v130, v[120:123] offset:46080
	s_waitcnt vmcnt(8)
	ds_write_b128 v130, v[124:127] offset:50688
	s_waitcnt lgkmcnt(13)
	v_mfma_f32_32x32x16_bf16 v[48:63], v[214:217], v[200:203], v[48:63]
	s_waitcnt lgkmcnt(0)
	s_barrier
	v_mfma_f32_32x32x16_bf16 v[32:47], v[218:221], v[200:203], v[32:47]
	v_mfma_f32_32x32x16_bf16 v[16:31], v[214:217], v[210:213], v[16:31]
	v_mfma_f32_32x32x16_bf16 v[0:15], v[218:221], v[210:213], v[0:15]
	v_mfma_f32_32x32x16_bf16 v[48:63], v[84:87], v[76:79], v[48:63]
	v_mfma_f32_32x32x16_bf16 v[32:47], v[88:91], v[76:79], v[32:47]
	v_mfma_f32_32x32x16_bf16 v[16:31], v[84:87], v[80:83], v[16:31]
	v_mfma_f32_32x32x16_bf16 v[0:15], v[88:91], v[80:83], v[0:15]
	ds_read_b128 v[76:79], v132 offset:4608
	ds_read_b128 v[84:87], v132
	ds_read_b128 v[80:83], v131 offset:41472
	ds_read_b128 v[96:99], v131 offset:36864
	ds_read_b128 v[88:91], v132 offset:32
	ds_read_b128 v[92:95], v132 offset:4640
	ds_read_b128 v[104:107], v131 offset:36896
	ds_read_b128 v[108:111], v131 offset:41504
	s_waitcnt lgkmcnt(4)
	v_mfma_f32_32x32x16_bf16 v[48:63], v[96:99], v[84:87], v[48:63]
	v_mfma_f32_32x32x16_bf16 v[32:47], v[80:83], v[84:87], v[32:47]
	v_mfma_f32_32x32x16_bf16 v[16:31], v[96:99], v[76:79], v[16:31]
	v_mfma_f32_32x32x16_bf16 v[0:15], v[80:83], v[76:79], v[0:15]
	global_load_dwordx4 v[76:79], v168, s[6:7] offset:1280
	global_load_dwordx4 v[80:83], v169, s[6:7] offset:1280
	global_load_dwordx4 v[84:87], v170, s[6:7] offset:1280
	global_load_dwordx4 v[96:99], v171, s[6:7] offset:1280
	global_load_dwordx4 v[112:115], v168, s[8:9] offset:1280
	global_load_dwordx4 v[116:119], v169, s[8:9] offset:1280
	global_load_dwordx4 v[120:123], v170, s[8:9] offset:1280
	global_load_dwordx4 v[124:127], v171, s[8:9] offset:1280
	ds_read_b128 v[200:203], v132 offset:64
	ds_read_b128 v[210:213], v132 offset:4672
	ds_read_b128 v[214:217], v131 offset:36928
	ds_read_b128 v[218:221], v131 offset:41536
	s_waitcnt vmcnt(15)
	ds_write_b128 v130, v[64:67] offset:18432
	s_waitcnt vmcnt(14)
	ds_write_b128 v130, v[68:71] offset:23040
	s_waitcnt vmcnt(13)
	ds_write_b128 v130, v[72:75] offset:27648
	s_waitcnt vmcnt(12)
	ds_write_b128 v130, v[100:103] offset:32256
	s_waitcnt lgkmcnt(9)
	v_mfma_f32_32x32x16_bf16 v[48:63], v[104:107], v[88:91], v[48:63]
	s_waitcnt lgkmcnt(8)
	v_mfma_f32_32x32x16_bf16 v[32:47], v[108:111], v[88:91], v[32:47]
	v_mfma_f32_32x32x16_bf16 v[16:31], v[104:107], v[92:95], v[16:31]
	v_mfma_f32_32x32x16_bf16 v[0:15], v[108:111], v[92:95], v[0:15]
	ds_read_b128 v[64:67], v132 offset:96
	ds_read_b128 v[68:71], v132 offset:4704
	ds_read_b128 v[72:75], v131 offset:36960
	ds_read_b128 v[88:91], v131 offset:41568
	s_waitcnt vmcnt(11)
	ds_write_b128 v130, v[172:175] offset:55296
	s_waitcnt vmcnt(10)
	ds_write_b128 v130, v[176:179] offset:59904
	s_waitcnt vmcnt(9)
	ds_write_b128 v130, v[180:183] offset:64512
	s_waitcnt vmcnt(8)
	ds_write_b128 v133, v[196:199] offset:13824
	s_waitcnt lgkmcnt(13)
	v_mfma_f32_32x32x16_bf16 v[48:63], v[214:217], v[200:203], v[48:63]
	s_waitcnt lgkmcnt(0)
	s_barrier
	v_mfma_f32_32x32x16_bf16 v[32:47], v[218:221], v[200:203], v[32:47]
	v_mfma_f32_32x32x16_bf16 v[16:31], v[214:217], v[210:213], v[16:31]
	v_mfma_f32_32x32x16_bf16 v[0:15], v[218:221], v[210:213], v[0:15]
	v_mfma_f32_32x32x16_bf16 v[48:63], v[72:75], v[64:67], v[48:63]
	v_mfma_f32_32x32x16_bf16 v[32:47], v[88:91], v[64:67], v[32:47]
	v_mfma_f32_32x32x16_bf16 v[16:31], v[72:75], v[68:71], v[16:31]
	v_mfma_f32_32x32x16_bf16 v[0:15], v[88:91], v[68:71], v[0:15]
	ds_read_b128 v[64:67], v132 offset:23040
	ds_read_b128 v[72:75], v132 offset:18432
	ds_read_b128 v[68:71], v131 offset:59904
	ds_read_b128 v[100:103], v131 offset:55296
	ds_read_b128 v[88:91], v132 offset:18464
	ds_read_b128 v[92:95], v132 offset:23072
	ds_read_b128 v[104:107], v131 offset:55328
	ds_read_b128 v[108:111], v131 offset:59936
	s_waitcnt lgkmcnt(4)
	v_mfma_f32_32x32x16_bf16 v[48:63], v[100:103], v[72:75], v[48:63]
	v_mfma_f32_32x32x16_bf16 v[32:47], v[68:71], v[72:75], v[32:47]
	v_mfma_f32_32x32x16_bf16 v[16:31], v[100:103], v[64:67], v[16:31]
	v_mfma_f32_32x32x16_bf16 v[0:15], v[68:71], v[64:67], v[0:15]
	global_load_dwordx4 v[64:67], v168, s[6:7] offset:1408
	global_load_dwordx4 v[68:71], v169, s[6:7] offset:1408
	global_load_dwordx4 v[72:75], v170, s[6:7] offset:1408
	global_load_dwordx4 v[100:103], v171, s[6:7] offset:1408
	global_load_dwordx4 v[172:175], v168, s[8:9] offset:1408
	global_load_dwordx4 v[176:179], v169, s[8:9] offset:1408
	global_load_dwordx4 v[180:183], v170, s[8:9] offset:1408
	global_load_dwordx4 v[196:199], v171, s[8:9] offset:1408
	ds_read_b128 v[200:203], v132 offset:18496
	ds_read_b128 v[210:213], v132 offset:23104
	ds_read_b128 v[214:217], v131 offset:55360
	ds_read_b128 v[218:221], v131 offset:59968
	s_waitcnt vmcnt(15)
	ds_write_b128 v130, v[76:79]
	s_waitcnt vmcnt(14)
	ds_write_b128 v130, v[80:83] offset:4608
	s_waitcnt vmcnt(13)
	ds_write_b128 v130, v[84:87] offset:9216
	s_waitcnt vmcnt(12)
	ds_write_b128 v130, v[96:99] offset:13824
	s_waitcnt lgkmcnt(9)
	v_mfma_f32_32x32x16_bf16 v[48:63], v[104:107], v[88:91], v[48:63]
	s_waitcnt lgkmcnt(8)
	v_mfma_f32_32x32x16_bf16 v[32:47], v[108:111], v[88:91], v[32:47]
	v_mfma_f32_32x32x16_bf16 v[16:31], v[104:107], v[92:95], v[16:31]
	v_mfma_f32_32x32x16_bf16 v[0:15], v[108:111], v[92:95], v[0:15]
	ds_read_b128 v[76:79], v132 offset:18528
	ds_read_b128 v[80:83], v132 offset:23136
	ds_read_b128 v[84:87], v131 offset:55392
	ds_read_b128 v[88:91], v131 offset:60000
	s_waitcnt vmcnt(11)
	ds_write_b128 v130, v[112:115] offset:36864
	s_waitcnt vmcnt(10)
	ds_write_b128 v130, v[116:119] offset:41472
	s_waitcnt vmcnt(9)
	ds_write_b128 v130, v[120:123] offset:46080
	s_waitcnt vmcnt(8)
	ds_write_b128 v130, v[124:127] offset:50688
	s_waitcnt lgkmcnt(13)
	v_mfma_f32_32x32x16_bf16 v[48:63], v[214:217], v[200:203], v[48:63]
	s_waitcnt lgkmcnt(0)
	s_barrier
	v_mfma_f32_32x32x16_bf16 v[32:47], v[218:221], v[200:203], v[32:47]
	v_mfma_f32_32x32x16_bf16 v[16:31], v[214:217], v[210:213], v[16:31]
	v_mfma_f32_32x32x16_bf16 v[0:15], v[218:221], v[210:213], v[0:15]
	v_mfma_f32_32x32x16_bf16 v[48:63], v[84:87], v[76:79], v[48:63]
	v_mfma_f32_32x32x16_bf16 v[32:47], v[88:91], v[76:79], v[32:47]
	v_mfma_f32_32x32x16_bf16 v[16:31], v[84:87], v[80:83], v[16:31]
	v_mfma_f32_32x32x16_bf16 v[0:15], v[88:91], v[80:83], v[0:15]
	ds_read_b128 v[76:79], v132 offset:4608
	ds_read_b128 v[84:87], v132
	ds_read_b128 v[80:83], v131 offset:41472
	ds_read_b128 v[96:99], v131 offset:36864
	ds_read_b128 v[88:91], v132 offset:32
	ds_read_b128 v[92:95], v132 offset:4640
	ds_read_b128 v[104:107], v131 offset:36896
	ds_read_b128 v[108:111], v131 offset:41504
	s_waitcnt lgkmcnt(4)
	v_mfma_f32_32x32x16_bf16 v[48:63], v[96:99], v[84:87], v[48:63]
	v_mfma_f32_32x32x16_bf16 v[32:47], v[80:83], v[84:87], v[32:47]
	v_mfma_f32_32x32x16_bf16 v[16:31], v[96:99], v[76:79], v[16:31]
	v_mfma_f32_32x32x16_bf16 v[0:15], v[80:83], v[76:79], v[0:15]
	global_load_dwordx4 v[76:79], v168, s[6:7] offset:1536
	global_load_dwordx4 v[80:83], v169, s[6:7] offset:1536
	global_load_dwordx4 v[84:87], v170, s[6:7] offset:1536
	global_load_dwordx4 v[96:99], v171, s[6:7] offset:1536
	global_load_dwordx4 v[112:115], v168, s[8:9] offset:1536
	global_load_dwordx4 v[116:119], v169, s[8:9] offset:1536
	global_load_dwordx4 v[120:123], v170, s[8:9] offset:1536
	global_load_dwordx4 v[124:127], v171, s[8:9] offset:1536
	ds_read_b128 v[200:203], v132 offset:64
	ds_read_b128 v[210:213], v132 offset:4672
	ds_read_b128 v[214:217], v131 offset:36928
	ds_read_b128 v[218:221], v131 offset:41536
	s_waitcnt vmcnt(15)
	ds_write_b128 v130, v[64:67] offset:18432
	s_waitcnt vmcnt(14)
	ds_write_b128 v130, v[68:71] offset:23040
	s_waitcnt vmcnt(13)
	ds_write_b128 v130, v[72:75] offset:27648
	s_waitcnt vmcnt(12)
	ds_write_b128 v130, v[100:103] offset:32256
	s_waitcnt lgkmcnt(9)
	v_mfma_f32_32x32x16_bf16 v[48:63], v[104:107], v[88:91], v[48:63]
	s_waitcnt lgkmcnt(8)
	v_mfma_f32_32x32x16_bf16 v[32:47], v[108:111], v[88:91], v[32:47]
	v_mfma_f32_32x32x16_bf16 v[16:31], v[104:107], v[92:95], v[16:31]
	v_mfma_f32_32x32x16_bf16 v[0:15], v[108:111], v[92:95], v[0:15]
	ds_read_b128 v[64:67], v132 offset:96
	ds_read_b128 v[68:71], v132 offset:4704
	ds_read_b128 v[72:75], v131 offset:36960
	ds_read_b128 v[88:91], v131 offset:41568
	s_waitcnt vmcnt(11)
	ds_write_b128 v130, v[172:175] offset:55296
	s_waitcnt vmcnt(10)
	ds_write_b128 v130, v[176:179] offset:59904
	s_waitcnt vmcnt(9)
	ds_write_b128 v130, v[180:183] offset:64512
	s_waitcnt vmcnt(8)
	ds_write_b128 v133, v[196:199] offset:13824
	s_waitcnt lgkmcnt(13)
	v_mfma_f32_32x32x16_bf16 v[48:63], v[214:217], v[200:203], v[48:63]
	s_waitcnt lgkmcnt(0)
	s_barrier
	v_mfma_f32_32x32x16_bf16 v[32:47], v[218:221], v[200:203], v[32:47]
	v_mfma_f32_32x32x16_bf16 v[16:31], v[214:217], v[210:213], v[16:31]
	v_mfma_f32_32x32x16_bf16 v[0:15], v[218:221], v[210:213], v[0:15]
	v_mfma_f32_32x32x16_bf16 v[48:63], v[72:75], v[64:67], v[48:63]
	v_mfma_f32_32x32x16_bf16 v[32:47], v[88:91], v[64:67], v[32:47]
	v_mfma_f32_32x32x16_bf16 v[16:31], v[72:75], v[68:71], v[16:31]
	v_mfma_f32_32x32x16_bf16 v[0:15], v[88:91], v[68:71], v[0:15]
	ds_read_b128 v[64:67], v132 offset:23040
	ds_read_b128 v[72:75], v132 offset:18432
	ds_read_b128 v[68:71], v131 offset:59904
	ds_read_b128 v[100:103], v131 offset:55296
	ds_read_b128 v[88:91], v132 offset:18464
	ds_read_b128 v[92:95], v132 offset:23072
	ds_read_b128 v[104:107], v131 offset:55328
	ds_read_b128 v[108:111], v131 offset:59936
	s_waitcnt lgkmcnt(4)
	v_mfma_f32_32x32x16_bf16 v[48:63], v[100:103], v[72:75], v[48:63]
	v_mfma_f32_32x32x16_bf16 v[32:47], v[68:71], v[72:75], v[32:47]
	v_mfma_f32_32x32x16_bf16 v[16:31], v[100:103], v[64:67], v[16:31]
	v_mfma_f32_32x32x16_bf16 v[0:15], v[68:71], v[64:67], v[0:15]
	global_load_dwordx4 v[64:67], v168, s[6:7] offset:1664
	global_load_dwordx4 v[68:71], v169, s[6:7] offset:1664
	global_load_dwordx4 v[72:75], v170, s[6:7] offset:1664
	global_load_dwordx4 v[100:103], v171, s[6:7] offset:1664
	global_load_dwordx4 v[172:175], v168, s[8:9] offset:1664
	global_load_dwordx4 v[176:179], v169, s[8:9] offset:1664
	global_load_dwordx4 v[180:183], v170, s[8:9] offset:1664
	global_load_dwordx4 v[196:199], v171, s[8:9] offset:1664
	ds_read_b128 v[200:203], v132 offset:18496
	ds_read_b128 v[210:213], v132 offset:23104
	ds_read_b128 v[214:217], v131 offset:55360
	ds_read_b128 v[218:221], v131 offset:59968
	s_waitcnt vmcnt(15)
	ds_write_b128 v130, v[76:79]
	s_waitcnt vmcnt(14)
	ds_write_b128 v130, v[80:83] offset:4608
	s_waitcnt vmcnt(13)
	ds_write_b128 v130, v[84:87] offset:9216
	s_waitcnt vmcnt(12)
	ds_write_b128 v130, v[96:99] offset:13824
	s_waitcnt lgkmcnt(9)
	v_mfma_f32_32x32x16_bf16 v[48:63], v[104:107], v[88:91], v[48:63]
	s_waitcnt lgkmcnt(8)
	v_mfma_f32_32x32x16_bf16 v[32:47], v[108:111], v[88:91], v[32:47]
	v_mfma_f32_32x32x16_bf16 v[16:31], v[104:107], v[92:95], v[16:31]
	v_mfma_f32_32x32x16_bf16 v[0:15], v[108:111], v[92:95], v[0:15]
	ds_read_b128 v[76:79], v132 offset:18528
	ds_read_b128 v[80:83], v132 offset:23136
	ds_read_b128 v[84:87], v131 offset:55392
	ds_read_b128 v[88:91], v131 offset:60000
	s_waitcnt vmcnt(11)
	ds_write_b128 v130, v[112:115] offset:36864
	s_waitcnt vmcnt(10)
	ds_write_b128 v130, v[116:119] offset:41472
	s_waitcnt vmcnt(9)
	ds_write_b128 v130, v[120:123] offset:46080
	s_waitcnt vmcnt(8)
	ds_write_b128 v130, v[124:127] offset:50688
	s_waitcnt lgkmcnt(13)
	v_mfma_f32_32x32x16_bf16 v[48:63], v[214:217], v[200:203], v[48:63]
	s_waitcnt lgkmcnt(0)
	s_barrier
	v_mfma_f32_32x32x16_bf16 v[32:47], v[218:221], v[200:203], v[32:47]
	v_mfma_f32_32x32x16_bf16 v[16:31], v[214:217], v[210:213], v[16:31]
	v_mfma_f32_32x32x16_bf16 v[0:15], v[218:221], v[210:213], v[0:15]
	v_mfma_f32_32x32x16_bf16 v[48:63], v[84:87], v[76:79], v[48:63]
	v_mfma_f32_32x32x16_bf16 v[32:47], v[88:91], v[76:79], v[32:47]
	v_mfma_f32_32x32x16_bf16 v[16:31], v[84:87], v[80:83], v[16:31]
	v_mfma_f32_32x32x16_bf16 v[0:15], v[88:91], v[80:83], v[0:15]
	ds_read_b128 v[76:79], v132 offset:4608
	ds_read_b128 v[84:87], v132
	ds_read_b128 v[80:83], v131 offset:41472
	ds_read_b128 v[96:99], v131 offset:36864
	ds_read_b128 v[88:91], v132 offset:32
	ds_read_b128 v[92:95], v132 offset:4640
	ds_read_b128 v[104:107], v131 offset:36896
	ds_read_b128 v[108:111], v131 offset:41504
	s_waitcnt lgkmcnt(4)
	v_mfma_f32_32x32x16_bf16 v[48:63], v[96:99], v[84:87], v[48:63]
	v_mfma_f32_32x32x16_bf16 v[32:47], v[80:83], v[84:87], v[32:47]
	v_mfma_f32_32x32x16_bf16 v[16:31], v[96:99], v[76:79], v[16:31]
	v_mfma_f32_32x32x16_bf16 v[0:15], v[80:83], v[76:79], v[0:15]
	global_load_dwordx4 v[76:79], v168, s[6:7] offset:1792
	global_load_dwordx4 v[80:83], v169, s[6:7] offset:1792
	global_load_dwordx4 v[84:87], v170, s[6:7] offset:1792
	global_load_dwordx4 v[96:99], v171, s[6:7] offset:1792
	global_load_dwordx4 v[112:115], v168, s[8:9] offset:1792
	global_load_dwordx4 v[116:119], v169, s[8:9] offset:1792
	global_load_dwordx4 v[120:123], v170, s[8:9] offset:1792
	global_load_dwordx4 v[124:127], v171, s[8:9] offset:1792
	ds_read_b128 v[200:203], v132 offset:64
	ds_read_b128 v[210:213], v132 offset:4672
	ds_read_b128 v[214:217], v131 offset:36928
	ds_read_b128 v[218:221], v131 offset:41536
	s_waitcnt vmcnt(15)
	ds_write_b128 v130, v[64:67] offset:18432
	s_waitcnt vmcnt(14)
	ds_write_b128 v130, v[68:71] offset:23040
	s_waitcnt vmcnt(13)
	ds_write_b128 v130, v[72:75] offset:27648
	s_waitcnt vmcnt(12)
	ds_write_b128 v130, v[100:103] offset:32256
	s_waitcnt lgkmcnt(9)
	v_mfma_f32_32x32x16_bf16 v[48:63], v[104:107], v[88:91], v[48:63]
	s_waitcnt lgkmcnt(8)
	v_mfma_f32_32x32x16_bf16 v[32:47], v[108:111], v[88:91], v[32:47]
	v_mfma_f32_32x32x16_bf16 v[16:31], v[104:107], v[92:95], v[16:31]
	v_mfma_f32_32x32x16_bf16 v[0:15], v[108:111], v[92:95], v[0:15]
	ds_read_b128 v[64:67], v132 offset:96
	ds_read_b128 v[68:71], v132 offset:4704
	ds_read_b128 v[72:75], v131 offset:36960
	ds_read_b128 v[88:91], v131 offset:41568
	s_waitcnt vmcnt(11)
	ds_write_b128 v130, v[172:175] offset:55296
	s_waitcnt vmcnt(10)
	ds_write_b128 v130, v[176:179] offset:59904
	s_waitcnt vmcnt(9)
	ds_write_b128 v130, v[180:183] offset:64512
	s_waitcnt vmcnt(8)
	ds_write_b128 v133, v[196:199] offset:13824
	s_waitcnt lgkmcnt(13)
	v_mfma_f32_32x32x16_bf16 v[48:63], v[214:217], v[200:203], v[48:63]
	s_waitcnt lgkmcnt(0)
	s_barrier
	v_mfma_f32_32x32x16_bf16 v[32:47], v[218:221], v[200:203], v[32:47]
	v_mfma_f32_32x32x16_bf16 v[16:31], v[214:217], v[210:213], v[16:31]
	v_mfma_f32_32x32x16_bf16 v[0:15], v[218:221], v[210:213], v[0:15]
	v_mfma_f32_32x32x16_bf16 v[48:63], v[72:75], v[64:67], v[48:63]
	v_mfma_f32_32x32x16_bf16 v[32:47], v[88:91], v[64:67], v[32:47]
	v_mfma_f32_32x32x16_bf16 v[16:31], v[72:75], v[68:71], v[16:31]
	v_mfma_f32_32x32x16_bf16 v[0:15], v[88:91], v[68:71], v[0:15]
	ds_read_b128 v[64:67], v132 offset:23040
	ds_read_b128 v[72:75], v132 offset:18432
	ds_read_b128 v[68:71], v131 offset:59904
	ds_read_b128 v[100:103], v131 offset:55296
	ds_read_b128 v[88:91], v132 offset:18464
	ds_read_b128 v[92:95], v132 offset:23072
	ds_read_b128 v[104:107], v131 offset:55328
	ds_read_b128 v[108:111], v131 offset:59936
	s_waitcnt lgkmcnt(4)
	v_mfma_f32_32x32x16_bf16 v[48:63], v[100:103], v[72:75], v[48:63]
	v_mfma_f32_32x32x16_bf16 v[32:47], v[68:71], v[72:75], v[32:47]
	v_mfma_f32_32x32x16_bf16 v[16:31], v[100:103], v[64:67], v[16:31]
	v_mfma_f32_32x32x16_bf16 v[0:15], v[68:71], v[64:67], v[0:15]
	global_load_dwordx4 v[64:67], v168, s[6:7] offset:1920
	global_load_dwordx4 v[68:71], v169, s[6:7] offset:1920
	global_load_dwordx4 v[72:75], v170, s[6:7] offset:1920
	global_load_dwordx4 v[100:103], v171, s[6:7] offset:1920
	global_load_dwordx4 v[172:175], v168, s[8:9] offset:1920
	global_load_dwordx4 v[176:179], v169, s[8:9] offset:1920
	global_load_dwordx4 v[180:183], v170, s[8:9] offset:1920
	s_nop 0
	global_load_dwordx4 v[168:171], v171, s[8:9] offset:1920
	ds_read_b128 v[196:199], v132 offset:18496
	ds_read_b128 v[200:203], v132 offset:23104
	ds_read_b128 v[210:213], v131 offset:55360
	ds_read_b128 v[214:217], v131 offset:59968
	s_waitcnt vmcnt(15)
	ds_write_b128 v130, v[76:79]
	s_waitcnt vmcnt(14)
	ds_write_b128 v130, v[80:83] offset:4608
	s_waitcnt vmcnt(13)
	ds_write_b128 v130, v[84:87] offset:9216
	s_waitcnt vmcnt(12)
	ds_write_b128 v130, v[96:99] offset:13824
	s_waitcnt lgkmcnt(9)
	v_mfma_f32_32x32x16_bf16 v[48:63], v[104:107], v[88:91], v[48:63]
	s_waitcnt lgkmcnt(8)
	v_mfma_f32_32x32x16_bf16 v[32:47], v[108:111], v[88:91], v[32:47]
	v_mfma_f32_32x32x16_bf16 v[0:15], v[108:111], v[92:95], v[0:15]
	v_mfma_f32_32x32x16_bf16 v[16:31], v[104:107], v[92:95], v[16:31]
	ds_read_b128 v[76:79], v132 offset:18528
	ds_read_b128 v[80:83], v132 offset:23136
	ds_read_b128 v[84:87], v131 offset:55392
	ds_read_b128 v[88:91], v131 offset:60000
	s_waitcnt vmcnt(11)
	ds_write_b128 v130, v[112:115] offset:36864
	s_waitcnt vmcnt(10)
	ds_write_b128 v130, v[116:119] offset:41472
	s_waitcnt vmcnt(9)
	ds_write_b128 v130, v[120:123] offset:46080
	s_waitcnt vmcnt(8)
	ds_write_b128 v130, v[124:127] offset:50688
	s_waitcnt lgkmcnt(13)
	v_mfma_f32_32x32x16_bf16 v[48:63], v[210:213], v[196:199], v[48:63]
	s_waitcnt lgkmcnt(0)
	s_barrier
	ds_read_b128 v[92:95], v132
	ds_read_b128 v[96:99], v132 offset:32
	ds_read_b128 v[104:107], v131 offset:36928
	ds_read_b128 v[108:111], v131 offset:41536
	v_mfma_f32_32x32x16_bf16 v[32:47], v[214:217], v[196:199], v[32:47]
	v_mfma_f32_32x32x16_bf16 v[0:15], v[214:217], v[200:203], v[0:15]
	v_mfma_f32_32x32x16_bf16 v[16:31], v[210:213], v[200:203], v[16:31]
	v_mfma_f32_32x32x16_bf16 v[48:63], v[84:87], v[76:79], v[48:63]
	v_mfma_f32_32x32x16_bf16 v[32:47], v[88:91], v[76:79], v[32:47]
	ds_read_b128 v[76:79], v132 offset:4608
	v_mfma_f32_32x32x16_bf16 v[0:15], v[88:91], v[80:83], v[0:15]
	ds_read_b128 v[88:91], v131 offset:36896
	v_mfma_f32_32x32x16_bf16 v[16:31], v[84:87], v[80:83], v[16:31]
	ds_read_b128 v[80:83], v131 offset:41472
	ds_read_b128 v[84:87], v131 offset:36864
	s_waitcnt lgkmcnt(1)
	v_mfma_f32_32x32x16_bf16 v[32:47], v[80:83], v[92:95], v[32:47]
	v_mfma_f32_32x32x16_bf16 v[0:15], v[80:83], v[76:79], v[0:15]
	ds_read_b128 v[80:83], v132 offset:4640
	s_waitcnt lgkmcnt(1)
	v_mfma_f32_32x32x16_bf16 v[48:63], v[84:87], v[92:95], v[48:63]
	ds_read_b128 v[92:95], v132 offset:4672
	v_mfma_f32_32x32x16_bf16 v[16:31], v[84:87], v[76:79], v[16:31]
	ds_read_b128 v[76:79], v131 offset:41504
	ds_read_b128 v[84:87], v132 offset:64
	s_waitcnt vmcnt(7)
	ds_write_b128 v130, v[64:67] offset:18432
	s_waitcnt vmcnt(6)
	ds_write_b128 v130, v[68:71] offset:23040
	s_waitcnt vmcnt(5)
	ds_write_b128 v130, v[72:75] offset:27648
	s_waitcnt vmcnt(4)
	ds_write_b128 v130, v[100:103] offset:32256
	ds_read_b128 v[64:67], v132 offset:96
	v_mfma_f32_32x32x16_bf16 v[48:63], v[88:91], v[96:99], v[48:63]
	ds_read_b128 v[68:71], v132 offset:4704
	ds_read_b128 v[72:75], v131 offset:36960
	s_waitcnt lgkmcnt(8)
	v_mfma_f32_32x32x16_bf16 v[32:47], v[76:79], v[96:99], v[32:47]
	v_mfma_f32_32x32x16_bf16 v[16:31], v[88:91], v[80:83], v[16:31]
	v_mfma_f32_32x32x16_bf16 v[0:15], v[76:79], v[80:83], v[0:15]
	ds_read_b128 v[76:79], v131 offset:41568
	s_waitcnt vmcnt(3)
	ds_write_b128 v130, v[172:175] offset:55296
	s_waitcnt vmcnt(2)
	ds_write_b128 v130, v[176:179] offset:59904
	s_waitcnt vmcnt(1)
	ds_write_b128 v130, v[180:183] offset:64512
	s_waitcnt vmcnt(0)
	ds_write_b128 v133, v[168:171] offset:13824
	s_waitcnt lgkmcnt(0)
	s_barrier
	v_mfma_f32_32x32x16_bf16 v[48:63], v[104:107], v[84:87], v[48:63]
	ds_read_b128 v[80:83], v132 offset:23072
	ds_read_b128 v[88:91], v131 offset:55328
	ds_read_b128 v[96:99], v132 offset:18528
	ds_read_b128 v[100:103], v132 offset:23136
	v_mfma_f32_32x32x16_bf16 v[32:47], v[108:111], v[84:87], v[32:47]
	ds_read_b128 v[84:87], v131 offset:55296
	v_mfma_f32_32x32x16_bf16 v[16:31], v[104:107], v[92:95], v[16:31]
	ds_read_b128 v[104:107], v131 offset:55392
	v_mfma_f32_32x32x16_bf16 v[0:15], v[108:111], v[92:95], v[0:15]
	ds_read_b128 v[92:95], v131 offset:59936
	ds_read_b128 v[108:111], v131 offset:60000
	v_mfma_f32_32x32x16_bf16 v[48:63], v[72:75], v[64:67], v[48:63]
	v_mfma_f32_32x32x16_bf16 v[32:47], v[76:79], v[64:67], v[32:47]
	ds_read_b128 v[64:67], v132 offset:23040
	v_mfma_f32_32x32x16_bf16 v[16:31], v[72:75], v[68:71], v[16:31]
	ds_read_b128 v[72:75], v132 offset:18432
	v_mfma_f32_32x32x16_bf16 v[0:15], v[76:79], v[68:71], v[0:15]
	ds_read_b128 v[68:71], v131 offset:59904
	ds_read_b128 v[76:79], v132 offset:18464
	s_waitcnt lgkmcnt(2)
	v_mfma_f32_32x32x16_bf16 v[48:63], v[84:87], v[72:75], v[48:63]
	v_mfma_f32_32x32x16_bf16 v[16:31], v[84:87], v[64:67], v[16:31]
	ds_read_b128 v[84:87], v131 offset:59968
	s_waitcnt lgkmcnt(2)
	v_mfma_f32_32x32x16_bf16 v[32:47], v[68:71], v[72:75], v[32:47]
	ds_read_b128 v[72:75], v131 offset:55360
	v_mfma_f32_32x32x16_bf16 v[0:15], v[68:71], v[64:67], v[0:15]
	ds_read_b128 v[64:67], v132 offset:18496
	ds_read_b128 v[68:71], v132 offset:23104
	s_waitcnt lgkmcnt(0)
	s_barrier
	v_mfma_f32_32x32x16_bf16 v[48:63], v[88:91], v[76:79], v[48:63]
	v_mfma_f32_32x32x16_bf16 v[16:31], v[88:91], v[80:83], v[16:31]
	v_mfma_f32_32x32x16_bf16 v[32:47], v[92:95], v[76:79], v[32:47]
	v_mfma_f32_32x32x16_bf16 v[0:15], v[92:95], v[80:83], v[0:15]
	v_mfma_f32_32x32x16_bf16 v[48:63], v[72:75], v[64:67], v[48:63]
	v_mfma_f32_32x32x16_bf16 v[16:31], v[72:75], v[68:71], v[16:31]
	v_mfma_f32_32x32x16_bf16 v[32:47], v[84:87], v[64:67], v[32:47]
	v_mfma_f32_32x32x16_bf16 v[0:15], v[84:87], v[68:71], v[0:15]
	v_mfma_f32_32x32x16_bf16 v[48:63], v[104:107], v[96:99], v[48:63]
	v_mfma_f32_32x32x16_bf16 v[32:47], v[108:111], v[96:99], v[32:47]
	v_mfma_f32_32x32x16_bf16 v[16:31], v[104:107], v[100:103], v[16:31]
	v_mfma_f32_32x32x16_bf16 v[0:15], v[108:111], v[100:103], v[0:15]
	s_barrier
	v_readfirstlane_b32 s16, v186
	v_and_b32_e32 v64, 31, v186
	v_bfe_u32 v67, v186, 5, 1
	s_lshr_b32 s16, s16, 6
	s_and_b32 s17, s16, 1
	s_lshr_b32 s28, s16, 1
	s_lshl_b32 s28, s28, 6
	v_add_u32_e32 v66, s28, v64
	v_mul_u32_u24_e32 v188, 0x210, v66
	v_lshl_add_u32 v188, v67, 4, v188
	s_lshl_b32 s28, s17, 8
	v_add_u32_e32 v188, s28, v188
	s_lshl_b32 s28, s16, 5
	v_add_u32_e32 v65, s28, v67
	v_mul_u32_u24_e32 v189, 0x210, v65
	v_lshl_add_u32 v189, v64, 4, v189
	v_lshlrev_b32_e32 v192, 12, v65
	v_lshl_add_u32 v192, v64, 4, v192
	v_lshlrev_b32_e32 v195, 11, v65
	v_lshl_add_u32 v195, v64, 3, v195
	v_lshlrev_b32_e32 v197, 4, v64
	v_and_b32_e32 v66, 15, v186
	v_lshl_add_u32 v66, v66, 1, v67
	v_add_u32_e32 v66, s28, v66
	v_lshlrev_b32_e32 v66, 5, v66
	s_lshl_b32 s16, s4, 12
	s_lshl_b32 s30, s0, 2
	s_add_u32 s16, s16, s30
	s_add_u32 s18, s46, s16
	s_addc_u32 s19, s47, 0
	s_add_u32 s20, s86, s16
	s_addc_u32 s21, s87, 0
	v_readlane_b32 s52, v254, 34
	v_readlane_b32 s53, v254, 35
	v_readlane_b32 s68, v251, 36
	v_readlane_b32 s69, v251, 37
	s_lshl_b64 s[52:53], s[52:53], 2
	s_add_u32 s68, s68, s52
	s_addc_u32 s69, s69, s53
	s_add_u32 s68, s68, s30
	s_addc_u32 s69, s69, 0
	s_lshl_b32 s26, s4, 11
	s_lshl_b32 s27, s0, 1
	s_add_u32 s26, s26, s27
	s_add_u32 s26, s26, 0x2800000
	s_add_u32 s70, s88, s26
	s_addc_u32 s71, s89, 0
	s_lshl_b32 s26, s4, 5
	s_lshr_b32 s27, s0, 5
	s_add_u32 s26, s26, s27
	s_add_u32 s26, s26, 0xec00000
	s_add_u32 s72, s88, s26
	s_addc_u32 s73, s89, 0
	global_load_dwordx4 v[210:213], v197, s[68:69]
	global_load_dwordx4 v[68:71], v192, s[18:19]
	s_add_u32 s18, s18, 0x2000
	s_addc_u32 s19, s19, 0
	global_load_dwordx4 v[72:75], v192, s[18:19]
	s_add_u32 s18, s18, 0x2000
	s_addc_u32 s19, s19, 0
	global_load_dwordx4 v[76:79], v192, s[18:19]
	s_add_u32 s18, s18, 0x2000
	s_addc_u32 s19, s19, 0
	global_load_dwordx4 v[80:83], v192, s[18:19]
	s_add_u32 s18, s18, 0x2000
	s_addc_u32 s19, s19, 0
	global_load_dwordx4 v[84:87], v192, s[18:19]
	s_add_u32 s18, s18, 0x2000
	s_addc_u32 s19, s19, 0
	global_load_dwordx4 v[88:91], v192, s[18:19]
	s_add_u32 s18, s18, 0x2000
	s_addc_u32 s19, s19, 0
	global_load_dwordx4 v[92:95], v192, s[18:19]
	s_add_u32 s18, s18, 0x2000
	s_addc_u32 s19, s19, 0
	global_load_dwordx4 v[96:99], v192, s[18:19]
	s_add_u32 s18, s18, 0x2000
	s_addc_u32 s19, s19, 0
	global_load_dwordx4 v[100:103], v192, s[18:19]
	s_add_u32 s18, s18, 0x2000
	s_addc_u32 s19, s19, 0
	global_load_dwordx4 v[104:107], v192, s[18:19]
	s_add_u32 s18, s18, 0x2000
	s_addc_u32 s19, s19, 0
	global_load_dwordx4 v[108:111], v192, s[18:19]
	s_add_u32 s18, s18, 0x2000
	s_addc_u32 s19, s19, 0
	global_load_dwordx4 v[112:115], v192, s[18:19]
	s_add_u32 s18, s18, 0x2000
	s_addc_u32 s19, s19, 0
	global_load_dwordx4 v[116:119], v192, s[18:19]
	s_add_u32 s18, s18, 0x2000
	s_addc_u32 s19, s19, 0
	global_load_dwordx4 v[120:123], v192, s[18:19]
	s_add_u32 s18, s18, 0x2000
	s_addc_u32 s19, s19, 0
	global_load_dwordx4 v[124:127], v192, s[18:19]
	s_add_u32 s18, s18, 0x2000
	s_addc_u32 s19, s19, 0
	global_load_dwordx4 v[128:131], v192, s[18:19]
	ds_write_b128 v188, v[48:51]
	ds_write_b128 v188, v[52:55] offset:32
	ds_write_b128 v188, v[56:59] offset:64
	ds_write_b128 v188, v[60:63] offset:96
	ds_write_b128 v188, v[32:35] offset:128
	ds_write_b128 v188, v[36:39] offset:160
	ds_write_b128 v188, v[40:43] offset:192
	ds_write_b128 v188, v[44:47] offset:224
	ds_write_b128 v188, v[16:19] offset:16896
	ds_write_b128 v188, v[20:23] offset:16928
	ds_write_b128 v188, v[24:27] offset:16960
	ds_write_b128 v188, v[28:31] offset:16992
	ds_write_b128 v188, v[0:3] offset:17024
	ds_write_b128 v188, v[4:7] offset:17056
	ds_write_b128 v188, v[8:11] offset:17088
	ds_write_b128 v188, v[12:15] offset:17120
	s_waitcnt lgkmcnt(0)
	s_barrier
	ds_read_b128 v[0:3], v189
	ds_read_b128 v[4:7], v189 offset:1056
	ds_read_b128 v[8:11], v189 offset:2112
	ds_read_b128 v[12:15], v189 offset:3168
	ds_read_b128 v[16:19], v189 offset:4224
	ds_read_b128 v[20:23], v189 offset:5280
	ds_read_b128 v[24:27], v189 offset:6336
	ds_read_b128 v[28:31], v189 offset:7392
	ds_read_b128 v[32:35], v189 offset:8448
	ds_read_b128 v[36:39], v189 offset:9504
	ds_read_b128 v[40:43], v189 offset:10560
	ds_read_b128 v[44:47], v189 offset:11616
	ds_read_b128 v[48:51], v189 offset:12672
	ds_read_b128 v[52:55], v189 offset:13728
	ds_read_b128 v[56:59], v189 offset:14784
	ds_read_b128 v[60:63], v189 offset:15840
	s_waitcnt lgkmcnt(15)
	s_waitcnt vmcnt(15)
	v_add_f32_e32 v68, v68, v0
	v_add_f32_e32 v69, v69, v1
	v_add_f32_e32 v70, v70, v2
	v_add_f32_e32 v71, v71, v3
	global_store_dwordx4 v192, v[68:71], s[20:21]
	s_add_u32 s20, s20, 0x2000
	s_addc_u32 s21, s21, 0
	v_mul_f32_e32 v132, v68, v68
	v_fmac_f32_e32 v132, v69, v69
	v_fmac_f32_e32 v132, v70, v70
	v_fmac_f32_e32 v132, v71, v71
	v_mul_f32_e32 v198, v68, v210
	v_mul_f32_e32 v199, v69, v211
	v_mul_f32_e32 v200, v70, v212
	v_mul_f32_e32 v201, v71, v213
	v_cvt_pk_bf16_f32 v202, v198, v199
	v_cvt_pk_bf16_f32 v203, v200, v201
	global_store_dwordx2 v195, v[202:203], s[70:71]
	s_add_u32 s70, s70, 0x1000
	s_addc_u32 s71, s71, 0
	s_waitcnt lgkmcnt(14)
	s_waitcnt vmcnt(16)
	v_add_f32_e32 v72, v72, v4
	v_add_f32_e32 v73, v73, v5
	v_add_f32_e32 v74, v74, v6
	v_add_f32_e32 v75, v75, v7
	global_store_dwordx4 v192, v[72:75], s[20:21]
	s_add_u32 s20, s20, 0x2000
	s_addc_u32 s21, s21, 0
	v_mul_f32_e32 v133, v72, v72
	v_fmac_f32_e32 v133, v73, v73
	v_fmac_f32_e32 v133, v74, v74
	v_fmac_f32_e32 v133, v75, v75
	v_mul_f32_e32 v148, v72, v210
	v_mul_f32_e32 v149, v73, v211
	v_mul_f32_e32 v150, v74, v212
	v_mul_f32_e32 v151, v75, v213
	v_cvt_pk_bf16_f32 v152, v148, v149
	v_cvt_pk_bf16_f32 v153, v150, v151
	global_store_dwordx2 v195, v[152:153], s[70:71]
	s_add_u32 s70, s70, 0x1000
	s_addc_u32 s71, s71, 0
	s_waitcnt lgkmcnt(13)
	s_waitcnt vmcnt(17)
	v_add_f32_e32 v76, v76, v8
	v_add_f32_e32 v77, v77, v9
	v_add_f32_e32 v78, v78, v10
	v_add_f32_e32 v79, v79, v11
	global_store_dwordx4 v192, v[76:79], s[20:21]
	s_add_u32 s20, s20, 0x2000
	s_addc_u32 s21, s21, 0
	v_mul_f32_e32 v134, v76, v76
	v_fmac_f32_e32 v134, v77, v77
	v_fmac_f32_e32 v134, v78, v78
	v_fmac_f32_e32 v134, v79, v79
	v_mul_f32_e32 v198, v76, v210
	v_mul_f32_e32 v199, v77, v211
	v_mul_f32_e32 v200, v78, v212
	v_mul_f32_e32 v201, v79, v213
	v_cvt_pk_bf16_f32 v202, v198, v199
	v_cvt_pk_bf16_f32 v203, v200, v201
	global_store_dwordx2 v195, v[202:203], s[70:71]
	s_add_u32 s70, s70, 0x1000
	s_addc_u32 s71, s71, 0
	s_waitcnt lgkmcnt(12)
	s_waitcnt vmcnt(18)
	v_add_f32_e32 v80, v80, v12
	v_add_f32_e32 v81, v81, v13
	v_add_f32_e32 v82, v82, v14
	v_add_f32_e32 v83, v83, v15
	global_store_dwordx4 v192, v[80:83], s[20:21]
	s_add_u32 s20, s20, 0x2000
	s_addc_u32 s21, s21, 0
	v_mul_f32_e32 v135, v80, v80
	v_fmac_f32_e32 v135, v81, v81
	v_fmac_f32_e32 v135, v82, v82
	v_fmac_f32_e32 v135, v83, v83
	v_mul_f32_e32 v148, v80, v210
	v_mul_f32_e32 v149, v81, v211
	v_mul_f32_e32 v150, v82, v212
	v_mul_f32_e32 v151, v83, v213
	v_cvt_pk_bf16_f32 v152, v148, v149
	v_cvt_pk_bf16_f32 v153, v150, v151
	global_store_dwordx2 v195, v[152:153], s[70:71]
	s_add_u32 s70, s70, 0x1000
	s_addc_u32 s71, s71, 0
	s_waitcnt lgkmcnt(11)
	s_waitcnt vmcnt(19)
	v_add_f32_e32 v84, v84, v16
	v_add_f32_e32 v85, v85, v17
	v_add_f32_e32 v86, v86, v18
	v_add_f32_e32 v87, v87, v19
	global_store_dwordx4 v192, v[84:87], s[20:21]
	s_add_u32 s20, s20, 0x2000
	s_addc_u32 s21, s21, 0
	v_mul_f32_e32 v136, v84, v84
	v_fmac_f32_e32 v136, v85, v85
	v_fmac_f32_e32 v136, v86, v86
	v_fmac_f32_e32 v136, v87, v87
	v_mul_f32_e32 v198, v84, v210
	v_mul_f32_e32 v199, v85, v211
	v_mul_f32_e32 v200, v86, v212
	v_mul_f32_e32 v201, v87, v213
	v_cvt_pk_bf16_f32 v202, v198, v199
	v_cvt_pk_bf16_f32 v203, v200, v201
	global_store_dwordx2 v195, v[202:203], s[70:71]
	s_add_u32 s70, s70, 0x1000
	s_addc_u32 s71, s71, 0
	s_waitcnt lgkmcnt(10)
	s_waitcnt vmcnt(20)
	v_add_f32_e32 v88, v88, v20
	v_add_f32_e32 v89, v89, v21
	v_add_f32_e32 v90, v90, v22
	v_add_f32_e32 v91, v91, v23
	global_store_dwordx4 v192, v[88:91], s[20:21]
	s_add_u32 s20, s20, 0x2000
	s_addc_u32 s21, s21, 0
	v_mul_f32_e32 v137, v88, v88
	v_fmac_f32_e32 v137, v89, v89
	v_fmac_f32_e32 v137, v90, v90
	v_fmac_f32_e32 v137, v91, v91
	v_mul_f32_e32 v148, v88, v210
	v_mul_f32_e32 v149, v89, v211
	v_mul_f32_e32 v150, v90, v212
	v_mul_f32_e32 v151, v91, v213
	v_cvt_pk_bf16_f32 v152, v148, v149
	v_cvt_pk_bf16_f32 v153, v150, v151
	global_store_dwordx2 v195, v[152:153], s[70:71]
	s_add_u32 s70, s70, 0x1000
	s_addc_u32 s71, s71, 0
	s_waitcnt lgkmcnt(9)
	s_waitcnt vmcnt(21)
	v_add_f32_e32 v92, v92, v24
	v_add_f32_e32 v93, v93, v25
	v_add_f32_e32 v94, v94, v26
	v_add_f32_e32 v95, v95, v27
	global_store_dwordx4 v192, v[92:95], s[20:21]
	s_add_u32 s20, s20, 0x2000
	s_addc_u32 s21, s21, 0
	v_mul_f32_e32 v138, v92, v92
	v_fmac_f32_e32 v138, v93, v93
	v_fmac_f32_e32 v138, v94, v94
	v_fmac_f32_e32 v138, v95, v95
	v_mul_f32_e32 v198, v92, v210
	v_mul_f32_e32 v199, v93, v211
	v_mul_f32_e32 v200, v94, v212
	v_mul_f32_e32 v201, v95, v213
	v_cvt_pk_bf16_f32 v202, v198, v199
	v_cvt_pk_bf16_f32 v203, v200, v201
	global_store_dwordx2 v195, v[202:203], s[70:71]
	s_add_u32 s70, s70, 0x1000
	s_addc_u32 s71, s71, 0
	s_waitcnt lgkmcnt(8)
	s_waitcnt vmcnt(22)
	v_add_f32_e32 v96, v96, v28
	v_add_f32_e32 v97, v97, v29
	v_add_f32_e32 v98, v98, v30
	v_add_f32_e32 v99, v99, v31
	global_store_dwordx4 v192, v[96:99], s[20:21]
	s_add_u32 s20, s20, 0x2000
	s_addc_u32 s21, s21, 0
	v_mul_f32_e32 v139, v96, v96
	v_fmac_f32_e32 v139, v97, v97
	v_fmac_f32_e32 v139, v98, v98
	v_fmac_f32_e32 v139, v99, v99
	v_mul_f32_e32 v148, v96, v210
	v_mul_f32_e32 v149, v97, v211
	v_mul_f32_e32 v150, v98, v212
	v_mul_f32_e32 v151, v99, v213
	v_cvt_pk_bf16_f32 v152, v148, v149
	v_cvt_pk_bf16_f32 v153, v150, v151
	global_store_dwordx2 v195, v[152:153], s[70:71]
	s_add_u32 s70, s70, 0x1000
	s_addc_u32 s71, s71, 0
	s_waitcnt lgkmcnt(7)
	s_waitcnt vmcnt(23)
	v_add_f32_e32 v100, v100, v32
	v_add_f32_e32 v101, v101, v33
	v_add_f32_e32 v102, v102, v34
	v_add_f32_e32 v103, v103, v35
	global_store_dwordx4 v192, v[100:103], s[20:21]
	s_add_u32 s20, s20, 0x2000
	s_addc_u32 s21, s21, 0
	v_mul_f32_e32 v140, v100, v100
	v_fmac_f32_e32 v140, v101, v101
	v_fmac_f32_e32 v140, v102, v102
	v_fmac_f32_e32 v140, v103, v103
	v_mul_f32_e32 v198, v100, v210
	v_mul_f32_e32 v199, v101, v211
	v_mul_f32_e32 v200, v102, v212
	v_mul_f32_e32 v201, v103, v213
	v_cvt_pk_bf16_f32 v202, v198, v199
	v_cvt_pk_bf16_f32 v203, v200, v201
	global_store_dwordx2 v195, v[202:203], s[70:71]
	s_add_u32 s70, s70, 0x1000
	s_addc_u32 s71, s71, 0
	s_waitcnt lgkmcnt(6)
	s_waitcnt vmcnt(24)
	v_add_f32_e32 v104, v104, v36
	v_add_f32_e32 v105, v105, v37
	v_add_f32_e32 v106, v106, v38
	v_add_f32_e32 v107, v107, v39
	global_store_dwordx4 v192, v[104:107], s[20:21]
	s_add_u32 s20, s20, 0x2000
	s_addc_u32 s21, s21, 0
	v_mul_f32_e32 v141, v104, v104
	v_fmac_f32_e32 v141, v105, v105
	v_fmac_f32_e32 v141, v106, v106
	v_fmac_f32_e32 v141, v107, v107
	v_mul_f32_e32 v148, v104, v210
	v_mul_f32_e32 v149, v105, v211
	v_mul_f32_e32 v150, v106, v212
	v_mul_f32_e32 v151, v107, v213
	v_cvt_pk_bf16_f32 v152, v148, v149
	v_cvt_pk_bf16_f32 v153, v150, v151
	global_store_dwordx2 v195, v[152:153], s[70:71]
	s_add_u32 s70, s70, 0x1000
	s_addc_u32 s71, s71, 0
	s_waitcnt lgkmcnt(5)
	s_waitcnt vmcnt(25)
	v_add_f32_e32 v108, v108, v40
	v_add_f32_e32 v109, v109, v41
	v_add_f32_e32 v110, v110, v42
	v_add_f32_e32 v111, v111, v43
	global_store_dwordx4 v192, v[108:111], s[20:21]
	s_add_u32 s20, s20, 0x2000
	s_addc_u32 s21, s21, 0
	v_mul_f32_e32 v142, v108, v108
	v_fmac_f32_e32 v142, v109, v109
	v_fmac_f32_e32 v142, v110, v110
	v_fmac_f32_e32 v142, v111, v111
	v_mul_f32_e32 v198, v108, v210
	v_mul_f32_e32 v199, v109, v211
	v_mul_f32_e32 v200, v110, v212
	v_mul_f32_e32 v201, v111, v213
	v_cvt_pk_bf16_f32 v202, v198, v199
	v_cvt_pk_bf16_f32 v203, v200, v201
	global_store_dwordx2 v195, v[202:203], s[70:71]
	s_add_u32 s70, s70, 0x1000
	s_addc_u32 s71, s71, 0
	s_waitcnt lgkmcnt(4)
	s_waitcnt vmcnt(26)
	v_add_f32_e32 v112, v112, v44
	v_add_f32_e32 v113, v113, v45
	v_add_f32_e32 v114, v114, v46
	v_add_f32_e32 v115, v115, v47
	global_store_dwordx4 v192, v[112:115], s[20:21]
	s_add_u32 s20, s20, 0x2000
	s_addc_u32 s21, s21, 0
	v_mul_f32_e32 v143, v112, v112
	v_fmac_f32_e32 v143, v113, v113
	v_fmac_f32_e32 v143, v114, v114
	v_fmac_f32_e32 v143, v115, v115
	v_mul_f32_e32 v148, v112, v210
	v_mul_f32_e32 v149, v113, v211
	v_mul_f32_e32 v150, v114, v212
	v_mul_f32_e32 v151, v115, v213
	v_cvt_pk_bf16_f32 v152, v148, v149
	v_cvt_pk_bf16_f32 v153, v150, v151
	global_store_dwordx2 v195, v[152:153], s[70:71]
	s_add_u32 s70, s70, 0x1000
	s_addc_u32 s71, s71, 0
	s_waitcnt lgkmcnt(3)
	s_waitcnt vmcnt(27)
	v_add_f32_e32 v116, v116, v48
	v_add_f32_e32 v117, v117, v49
	v_add_f32_e32 v118, v118, v50
	v_add_f32_e32 v119, v119, v51
	global_store_dwordx4 v192, v[116:119], s[20:21]
	s_add_u32 s20, s20, 0x2000
	s_addc_u32 s21, s21, 0
	v_mul_f32_e32 v144, v116, v116
	v_fmac_f32_e32 v144, v117, v117
	v_fmac_f32_e32 v144, v118, v118
	v_fmac_f32_e32 v144, v119, v119
	v_mul_f32_e32 v198, v116, v210
	v_mul_f32_e32 v199, v117, v211
	v_mul_f32_e32 v200, v118, v212
	v_mul_f32_e32 v201, v119, v213
	v_cvt_pk_bf16_f32 v202, v198, v199
	v_cvt_pk_bf16_f32 v203, v200, v201
	global_store_dwordx2 v195, v[202:203], s[70:71]
	s_add_u32 s70, s70, 0x1000
	s_addc_u32 s71, s71, 0
	s_waitcnt lgkmcnt(2)
	s_waitcnt vmcnt(28)
	v_add_f32_e32 v120, v120, v52
	v_add_f32_e32 v121, v121, v53
	v_add_f32_e32 v122, v122, v54
	v_add_f32_e32 v123, v123, v55
	global_store_dwordx4 v192, v[120:123], s[20:21]
	s_add_u32 s20, s20, 0x2000
	s_addc_u32 s21, s21, 0
	v_mul_f32_e32 v145, v120, v120
	v_fmac_f32_e32 v145, v121, v121
	v_fmac_f32_e32 v145, v122, v122
	v_fmac_f32_e32 v145, v123, v123
	v_mul_f32_e32 v148, v120, v210
	v_mul_f32_e32 v149, v121, v211
	v_mul_f32_e32 v150, v122, v212
	v_mul_f32_e32 v151, v123, v213
	v_cvt_pk_bf16_f32 v152, v148, v149
	v_cvt_pk_bf16_f32 v153, v150, v151
	global_store_dwordx2 v195, v[152:153], s[70:71]
	s_add_u32 s70, s70, 0x1000
	s_addc_u32 s71, s71, 0
	s_waitcnt lgkmcnt(1)
	s_waitcnt vmcnt(29)
	v_add_f32_e32 v124, v124, v56
	v_add_f32_e32 v125, v125, v57
	v_add_f32_e32 v126, v126, v58
	v_add_f32_e32 v127, v127, v59
	global_store_dwordx4 v192, v[124:127], s[20:21]
	s_add_u32 s20, s20, 0x2000
	s_addc_u32 s21, s21, 0
	v_mul_f32_e32 v146, v124, v124
	v_fmac_f32_e32 v146, v125, v125
	v_fmac_f32_e32 v146, v126, v126
	v_fmac_f32_e32 v146, v127, v127
	v_mul_f32_e32 v198, v124, v210
	v_mul_f32_e32 v199, v125, v211
	v_mul_f32_e32 v200, v126, v212
	v_mul_f32_e32 v201, v127, v213
	v_cvt_pk_bf16_f32 v202, v198, v199
	v_cvt_pk_bf16_f32 v203, v200, v201
	global_store_dwordx2 v195, v[202:203], s[70:71]
	s_add_u32 s70, s70, 0x1000
	s_addc_u32 s71, s71, 0
	s_waitcnt lgkmcnt(0)
	s_waitcnt vmcnt(30)
	v_add_f32_e32 v128, v128, v60
	v_add_f32_e32 v129, v129, v61
	v_add_f32_e32 v130, v130, v62
	v_add_f32_e32 v131, v131, v63
	global_store_dwordx4 v192, v[128:131], s[20:21]
	v_mul_f32_e32 v147, v128, v128
	v_fmac_f32_e32 v147, v129, v129
	v_fmac_f32_e32 v147, v130, v130
	v_fmac_f32_e32 v147, v131, v131
	v_mul_f32_e32 v148, v128, v210
	v_mul_f32_e32 v149, v129, v211
	v_mul_f32_e32 v150, v130, v212
	v_mul_f32_e32 v151, v131, v213
	v_cvt_pk_bf16_f32 v152, v148, v149
	v_cvt_pk_bf16_f32 v153, v150, v151
	global_store_dwordx2 v195, v[152:153], s[70:71]
	v_add_f32_dpp v132, v132, v132 quad_perm:[1,0,3,2] row_mask:0xf bank_mask:0xf
	v_add_f32_dpp v133, v133, v133 quad_perm:[1,0,3,2] row_mask:0xf bank_mask:0xf
	v_add_f32_dpp v134, v134, v134 quad_perm:[1,0,3,2] row_mask:0xf bank_mask:0xf
	v_add_f32_dpp v135, v135, v135 quad_perm:[1,0,3,2] row_mask:0xf bank_mask:0xf
	v_add_f32_dpp v136, v136, v136 quad_perm:[1,0,3,2] row_mask:0xf bank_mask:0xf
	v_add_f32_dpp v137, v137, v137 quad_perm:[1,0,3,2] row_mask:0xf bank_mask:0xf
	v_add_f32_dpp v138, v138, v138 quad_perm:[1,0,3,2] row_mask:0xf bank_mask:0xf
	v_add_f32_dpp v139, v139, v139 quad_perm:[1,0,3,2] row_mask:0xf bank_mask:0xf
	v_add_f32_dpp v140, v140, v140 quad_perm:[1,0,3,2] row_mask:0xf bank_mask:0xf
	v_add_f32_dpp v141, v141, v141 quad_perm:[1,0,3,2] row_mask:0xf bank_mask:0xf
	v_add_f32_dpp v142, v142, v142 quad_perm:[1,0,3,2] row_mask:0xf bank_mask:0xf
	v_add_f32_dpp v143, v143, v143 quad_perm:[1,0,3,2] row_mask:0xf bank_mask:0xf
	v_add_f32_dpp v144, v144, v144 quad_perm:[1,0,3,2] row_mask:0xf bank_mask:0xf
	v_add_f32_dpp v145, v145, v145 quad_perm:[1,0,3,2] row_mask:0xf bank_mask:0xf
	v_add_f32_dpp v146, v146, v146 quad_perm:[1,0,3,2] row_mask:0xf bank_mask:0xf
	v_add_f32_dpp v147, v147, v147 quad_perm:[1,0,3,2] row_mask:0xf bank_mask:0xf
	v_add_f32_dpp v132, v132, v132 quad_perm:[2,3,0,1] row_mask:0xf bank_mask:0xf
	v_add_f32_dpp v133, v133, v133 quad_perm:[2,3,0,1] row_mask:0xf bank_mask:0xf
	v_add_f32_dpp v134, v134, v134 quad_perm:[2,3,0,1] row_mask:0xf bank_mask:0xf
	v_add_f32_dpp v135, v135, v135 quad_perm:[2,3,0,1] row_mask:0xf bank_mask:0xf
	v_add_f32_dpp v136, v136, v136 quad_perm:[2,3,0,1] row_mask:0xf bank_mask:0xf
	v_add_f32_dpp v137, v137, v137 quad_perm:[2,3,0,1] row_mask:0xf bank_mask:0xf
	v_add_f32_dpp v138, v138, v138 quad_perm:[2,3,0,1] row_mask:0xf bank_mask:0xf
	v_add_f32_dpp v139, v139, v139 quad_perm:[2,3,0,1] row_mask:0xf bank_mask:0xf
	v_add_f32_dpp v140, v140, v140 quad_perm:[2,3,0,1] row_mask:0xf bank_mask:0xf
	v_add_f32_dpp v141, v141, v141 quad_perm:[2,3,0,1] row_mask:0xf bank_mask:0xf
	v_add_f32_dpp v142, v142, v142 quad_perm:[2,3,0,1] row_mask:0xf bank_mask:0xf
	v_add_f32_dpp v143, v143, v143 quad_perm:[2,3,0,1] row_mask:0xf bank_mask:0xf
	v_add_f32_dpp v144, v144, v144 quad_perm:[2,3,0,1] row_mask:0xf bank_mask:0xf
	v_add_f32_dpp v145, v145, v145 quad_perm:[2,3,0,1] row_mask:0xf bank_mask:0xf
	v_add_f32_dpp v146, v146, v146 quad_perm:[2,3,0,1] row_mask:0xf bank_mask:0xf
	v_add_f32_dpp v147, v147, v147 quad_perm:[2,3,0,1] row_mask:0xf bank_mask:0xf
	v_add_f32_dpp v132, v132, v132 row_half_mirror row_mask:0xf bank_mask:0xf
	v_add_f32_dpp v133, v133, v133 row_half_mirror row_mask:0xf bank_mask:0xf
	v_add_f32_dpp v134, v134, v134 row_half_mirror row_mask:0xf bank_mask:0xf
	v_add_f32_dpp v135, v135, v135 row_half_mirror row_mask:0xf bank_mask:0xf
	v_add_f32_dpp v136, v136, v136 row_half_mirror row_mask:0xf bank_mask:0xf
	v_add_f32_dpp v137, v137, v137 row_half_mirror row_mask:0xf bank_mask:0xf
	v_add_f32_dpp v138, v138, v138 row_half_mirror row_mask:0xf bank_mask:0xf
	v_add_f32_dpp v139, v139, v139 row_half_mirror row_mask:0xf bank_mask:0xf
	v_add_f32_dpp v140, v140, v140 row_half_mirror row_mask:0xf bank_mask:0xf
	v_add_f32_dpp v141, v141, v141 row_half_mirror row_mask:0xf bank_mask:0xf
	v_add_f32_dpp v142, v142, v142 row_half_mirror row_mask:0xf bank_mask:0xf
	v_add_f32_dpp v143, v143, v143 row_half_mirror row_mask:0xf bank_mask:0xf
	v_add_f32_dpp v144, v144, v144 row_half_mirror row_mask:0xf bank_mask:0xf
	v_add_f32_dpp v145, v145, v145 row_half_mirror row_mask:0xf bank_mask:0xf
	v_add_f32_dpp v146, v146, v146 row_half_mirror row_mask:0xf bank_mask:0xf
	v_add_f32_dpp v147, v147, v147 row_half_mirror row_mask:0xf bank_mask:0xf
	v_add_f32_dpp v132, v132, v132 row_mirror row_mask:0xf bank_mask:0xf
	v_add_f32_dpp v133, v133, v133 row_mirror row_mask:0xf bank_mask:0xf
	v_add_f32_dpp v134, v134, v134 row_mirror row_mask:0xf bank_mask:0xf
	v_add_f32_dpp v135, v135, v135 row_mirror row_mask:0xf bank_mask:0xf
	v_add_f32_dpp v136, v136, v136 row_mirror row_mask:0xf bank_mask:0xf
	v_add_f32_dpp v137, v137, v137 row_mirror row_mask:0xf bank_mask:0xf
	v_add_f32_dpp v138, v138, v138 row_mirror row_mask:0xf bank_mask:0xf
	v_add_f32_dpp v139, v139, v139 row_mirror row_mask:0xf bank_mask:0xf
	v_add_f32_dpp v140, v140, v140 row_mirror row_mask:0xf bank_mask:0xf
	v_add_f32_dpp v141, v141, v141 row_mirror row_mask:0xf bank_mask:0xf
	v_add_f32_dpp v142, v142, v142 row_mirror row_mask:0xf bank_mask:0xf
	v_add_f32_dpp v143, v143, v143 row_mirror row_mask:0xf bank_mask:0xf
	v_add_f32_dpp v144, v144, v144 row_mirror row_mask:0xf bank_mask:0xf
	v_add_f32_dpp v145, v145, v145 row_mirror row_mask:0xf bank_mask:0xf
	v_add_f32_dpp v146, v146, v146 row_mirror row_mask:0xf bank_mask:0xf
	v_add_f32_dpp v147, v147, v147 row_mirror row_mask:0xf bank_mask:0xf
	v_mov_b32_e32 v164, v132
	v_mov_b32_e32 v165, v133
	v_mov_b32_e32 v166, v134
	v_mov_b32_e32 v167, v135
	v_mov_b32_e32 v168, v136
	v_mov_b32_e32 v169, v137
	v_mov_b32_e32 v170, v138
	v_mov_b32_e32 v171, v139
	v_mov_b32_e32 v172, v140
	v_mov_b32_e32 v173, v141
	v_mov_b32_e32 v174, v142
	v_mov_b32_e32 v175, v143
	v_mov_b32_e32 v176, v144
	v_mov_b32_e32 v177, v145
	v_mov_b32_e32 v178, v146
	v_mov_b32_e32 v179, v147
	v_permlane16_swap_b32_e32 v132, v164
	v_permlane16_swap_b32_e32 v133, v165
	v_permlane16_swap_b32_e32 v134, v166
	v_permlane16_swap_b32_e32 v135, v167
	v_permlane16_swap_b32_e32 v136, v168
	v_permlane16_swap_b32_e32 v137, v169
	v_permlane16_swap_b32_e32 v138, v170
	v_permlane16_swap_b32_e32 v139, v171
	v_permlane16_swap_b32_e32 v140, v172
	v_permlane16_swap_b32_e32 v141, v173
	v_permlane16_swap_b32_e32 v142, v174
	v_permlane16_swap_b32_e32 v143, v175
	v_permlane16_swap_b32_e32 v144, v176
	v_permlane16_swap_b32_e32 v145, v177
	v_permlane16_swap_b32_e32 v146, v178
	v_permlane16_swap_b32_e32 v147, v179
	v_add_f32_e32 v132, v132, v164
	v_add_f32_e32 v133, v133, v165
	v_add_f32_e32 v134, v134, v166
	v_add_f32_e32 v135, v135, v167
	v_add_f32_e32 v136, v136, v168
	v_add_f32_e32 v137, v137, v169
	v_add_f32_e32 v138, v138, v170
	v_add_f32_e32 v139, v139, v171
	v_add_f32_e32 v140, v140, v172
	v_add_f32_e32 v141, v141, v173
	v_add_f32_e32 v142, v142, v174
	v_add_f32_e32 v143, v143, v175
	v_add_f32_e32 v144, v144, v176
	v_add_f32_e32 v145, v145, v177
	v_add_f32_e32 v146, v146, v178
	v_add_f32_e32 v147, v147, v179
	v_mov_b32_e32 v196, v132
	s_mov_b32 s26, 0x2
	s_mov_b32 s27, 0x2
	s_nop 0
	v_cndmask_b32_e64 v196, v196, v133, s[26:27]
	s_mov_b32 s26, 0x4
	s_mov_b32 s27, 0x4
	s_nop 0
	v_cndmask_b32_e64 v196, v196, v134, s[26:27]
	s_mov_b32 s26, 0x8
	s_mov_b32 s27, 0x8
	s_nop 0
	v_cndmask_b32_e64 v196, v196, v135, s[26:27]
	s_mov_b32 s26, 0x10
	s_mov_b32 s27, 0x10
	s_nop 0
	v_cndmask_b32_e64 v196, v196, v136, s[26:27]
	s_mov_b32 s26, 0x20
	s_mov_b32 s27, 0x20
	s_nop 0
	v_cndmask_b32_e64 v196, v196, v137, s[26:27]
	s_mov_b32 s26, 0x40
	s_mov_b32 s27, 0x40
	s_nop 0
	v_cndmask_b32_e64 v196, v196, v138, s[26:27]
	s_mov_b32 s26, 0x80
	s_mov_b32 s27, 0x80
	s_nop 0
	v_cndmask_b32_e64 v196, v196, v139, s[26:27]
	s_mov_b32 s26, 0x100
	s_mov_b32 s27, 0x100
	s_nop 0
	v_cndmask_b32_e64 v196, v196, v140, s[26:27]
	s_mov_b32 s26, 0x200
	s_mov_b32 s27, 0x200
	s_nop 0
	v_cndmask_b32_e64 v196, v196, v141, s[26:27]
	s_mov_b32 s26, 0x400
	s_mov_b32 s27, 0x400
	s_nop 0
	v_cndmask_b32_e64 v196, v196, v142, s[26:27]
	s_mov_b32 s26, 0x800
	s_mov_b32 s27, 0x800
	s_nop 0
	v_cndmask_b32_e64 v196, v196, v143, s[26:27]
	s_mov_b32 s26, 0x1000
	s_mov_b32 s27, 0x1000
	s_nop 0
	v_cndmask_b32_e64 v196, v196, v144, s[26:27]
	s_mov_b32 s26, 0x2000
	s_mov_b32 s27, 0x2000
	s_nop 0
	v_cndmask_b32_e64 v196, v196, v145, s[26:27]
	s_mov_b32 s26, 0x4000
	s_mov_b32 s27, 0x4000
	s_nop 0
	v_cndmask_b32_e64 v196, v196, v146, s[26:27]
	s_mov_b32 s26, 0x8000
	s_mov_b32 s27, 0x8000
	s_nop 0
	v_cndmask_b32_e64 v196, v196, v147, s[26:27]
	s_mov_b32 exec_lo, 0xffff
	s_mov_b32 exec_hi, 0xffff
	global_store_dword v66, v196, s[72:73]
	s_mov_b64 exec, -1
	v_readlane_b32 s0, v252, 22
	s_nop 3
	s_add_i32 s14, s14, s0
	s_cmp_ge_i32 s14, s24
	s_cbranch_scc1 .LBB0_2152

.LBB0_2204:
	s_or_b64 exec, exec, s[0:1]
	v_readlane_b32 s23, v254, 28
	s_mov_b64 s[4:5], s[88:89]
	s_waitcnt lgkmcnt(0)
	v_mov_b32_e32 v0, v186
	s_mov_b32 s0, s90
	s_barrier
	s_nop 0
	v_readlane_b32 s0, v252, 39
	v_readlane_b32 s1, v252, 40
	s_andn2_b64 vcc, exec, s[0:1]
	s_cbranch_vccnz .LBB0_2270
	v_and_b32_e32 v248, 31, v186
	v_lshrrev_b32_e32 v247, 7, v186
	v_lshl_add_u32 v248, v247, 6, v248
	v_lshlrev_b32_e32 v248, 5, v248
	s_add_u32 s12, s4, 0x2800000
	s_addc_u32 s13, s5, 0
	s_add_u32 s0, s4, 0x4800000
	v_and_b32_e32 v1, 31, v0
	v_lshrrev_b32_e32 v2, 1, v0
	s_addc_u32 s1, s5, 0
	v_and_or_b32 v132, v2, 32, v1
	v_ashrrev_i32_e32 v1, 1, v0
	v_lshrrev_b32_e32 v0, 3, v0
	s_add_u32 s14, s4, 0x1340000
	v_and_b32_e32 v134, 4, v0
	s_addc_u32 s15, s5, 0
	v_and_b32_e32 v133, 0xffffffc0, v1
	v_or_b32_e32 v135, 1, v134
	v_or_b32_e32 v136, 2, v134
	v_or_b32_e32 v137, 3, v134
	v_or_b32_e32 v138, 8, v134
	v_or_b32_e32 v139, 9, v134
	v_or_b32_e32 v140, 10, v134
	v_or_b32_e32 v141, 11, v134
	v_or_b32_e32 v142, 16, v134
	v_or_b32_e32 v143, 17, v134
	v_or_b32_e32 v144, 18, v134
	v_or_b32_e32 v145, 19, v134
	v_or_b32_e32 v146, 24, v134
	v_or_b32_e32 v147, 25, v134
	v_or_b32_e32 v148, 26, v134
	v_or_b32_e32 v149, 27, v134
	v_or_b32_e32 v150, 32, v134
	v_or_b32_e32 v151, 33, v134
	v_or_b32_e32 v152, 34, v134
	v_or_b32_e32 v153, 35, v134
	v_or_b32_e32 v154, 40, v134
	v_or_b32_e32 v155, 41, v134
	v_or_b32_e32 v156, 42, v134
	v_or_b32_e32 v157, 43, v134
	v_or_b32_e32 v158, 48, v134
	v_or_b32_e32 v159, 49, v134
	v_or_b32_e32 v160, 50, v134
	v_or_b32_e32 v163, 51, v134
	v_or_b32_e32 v164, 56, v134
	v_or_b32_e32 v165, 57, v134
	v_or_b32_e32 v166, 58, v134
	v_or_b32_e32 v167, 59, v134
	v_readlane_b32 s16, v252, 41
	s_branch .LBB0_2263

.LBB0_2262:
	s_lshl_b32 s6, s5, 7
	s_ashr_i32 s7, s6, 31
	s_lshl_b64 s[8:9], s[6:7], 11
	v_mov_b32_e32 v0, v161
	s_add_u32 s8, s12, s8
	s_waitcnt vmcnt(8)
	v_mov_b32_e32 v49, v186
	s_addc_u32 s9, s13, s9
	s_ashr_i32 s5, s4, 31
	s_lshl_b64 s[10:11], s[4:5], 18
	v_lshlrev_b32_e32 v16, 4, v49
	v_ashrrev_i32_e32 v50, 3, v49
	v_and_b32_e32 v48, 0x70, v16
	s_add_u32 s10, s14, s10
	v_lshl_or_b32 v168, v50, 11, v48
	s_addc_u32 s11, s15, s11
	v_add_u32_e32 v169, 0x10000, v168
	v_add_u32_e32 v170, 0x20000, v168
	v_add_u32_e32 v171, 0x30000, v168
	s_barrier
	s_lshl_b32 s72, s6, 5
	s_add_u32 s72, s72, 0xec00000
	s_add_u32 s72, s88, s72
	s_addc_u32 s73, s89, 0
	global_load_dwordx4 v[222:225], v248, s[72:73]
	global_load_dwordx4 v[226:229], v248, s[72:73] offset:16
	global_load_dwordx4 v[136:139], v248, s[72:73] offset:1024
	global_load_dwordx4 v[140:143], v248, s[72:73] offset:1040
	global_load_dwordx4 v[16:19], v168, s[8:9]
	global_load_dwordx4 v[20:23], v169, s[8:9]
	global_load_dwordx4 v[24:27], v170, s[8:9]
	global_load_dwordx4 v[28:31], v171, s[8:9]
	global_load_dwordx4 v[32:35], v168, s[10:11]
	global_load_dwordx4 v[36:39], v169, s[10:11]
	global_load_dwordx4 v[40:43], v170, s[10:11]
	global_load_dwordx4 v[44:47], v171, s[10:11]
	v_mad_u64_u32 v[130:131], s[18:19], v50, s43, v[48:49]
	v_mov_b32_e32 v1, v0
	v_mov_b32_e32 v2, v0
	v_mov_b32_e32 v3, v0
	v_mov_b32_e32 v4, v0
	v_mov_b32_e32 v5, v0
	v_mov_b32_e32 v6, v0
	v_mov_b32_e32 v7, v0
	s_waitcnt vmcnt(8)
	v_mov_b32_e32 v8, v0
	v_mov_b32_e32 v9, v0
	v_mov_b32_e32 v10, v0
	v_mov_b32_e32 v11, v0
	v_mov_b32_e32 v12, v0
	v_mov_b32_e32 v13, v0
	v_mov_b32_e32 v14, v0
	v_mov_b32_e32 v15, v0
	s_waitcnt vmcnt(7)
	ds_write_b128 v130, v[16:19]
	s_waitcnt vmcnt(6)
	ds_write_b128 v130, v[20:23] offset:4608
	s_waitcnt vmcnt(5)
	ds_write_b128 v130, v[24:27] offset:9216
	s_waitcnt vmcnt(4)
	ds_write_b128 v130, v[28:31] offset:13824
	s_waitcnt vmcnt(3)
	ds_write_b128 v130, v[32:35] offset:36864
	s_waitcnt vmcnt(2)
	ds_write_b128 v130, v[36:39] offset:41472
	s_waitcnt vmcnt(1)
	ds_write_b128 v130, v[40:43] offset:46080
	s_waitcnt vmcnt(0)
	ds_write_b128 v130, v[44:47] offset:50688
	global_load_dwordx4 v[96:99], v168, s[8:9] offset:128
	global_load_dwordx4 v[100:103], v169, s[8:9] offset:128
	global_load_dwordx4 v[104:107], v170, s[8:9] offset:128
	global_load_dwordx4 v[108:111], v171, s[8:9] offset:128
	global_load_dwordx4 v[64:67], v168, s[10:11] offset:128
	global_load_dwordx4 v[68:71], v169, s[10:11] offset:128
	global_load_dwordx4 v[72:75], v170, s[10:11] offset:128
	global_load_dwordx4 v[76:79], v171, s[10:11] offset:128
	v_lshrrev_b32_e32 v18, 1, v49
	v_and_b32_e32 v17, 0x5f, v49
	v_and_b32_e32 v16, 16, v18
	v_mad_u32_u24 v131, v17, s43, v16
	v_and_b32_e32 v17, 31, v49
	v_and_or_b32 v17, v18, s44, v17
	v_mad_u64_u32 v[128:129], s[18:19], v17, s43, v[16:17]
	s_waitcnt lgkmcnt(0)
	s_barrier
	ds_read_b128 v[16:19], v128
	ds_read_b128 v[84:87], v131 offset:41472
	ds_read_b128 v[80:83], v128 offset:4608
	ds_read_b128 v[172:175], v128 offset:32
	s_waitcnt lgkmcnt(2)
	v_mfma_f32_32x32x16_bf16 v[48:63], v[84:87], v[16:19], v[0:15]
	ds_read_b128 v[88:91], v131 offset:36864
	ds_read_b128 v[176:179], v128 offset:4640
	ds_read_b128 v[180:183], v131 offset:36896
	ds_read_b128 v[196:199], v131 offset:41504
	v_add_u32_e32 v129, 0xd800, v130
	s_waitcnt lgkmcnt(3)
	v_mfma_f32_32x32x16_bf16 v[32:47], v[88:91], v[16:19], v[0:15]
	v_mfma_f32_32x32x16_bf16 v[16:31], v[88:91], v[80:83], v[0:15]
	v_mfma_f32_32x32x16_bf16 v[0:15], v[84:87], v[80:83], v[0:15]
	s_waitcnt lgkmcnt(1)
	v_mfma_f32_32x32x16_bf16 v[32:47], v[180:183], v[172:175], v[32:47]
	s_waitcnt lgkmcnt(0)
	v_mfma_f32_32x32x16_bf16 v[48:63], v[196:199], v[172:175], v[48:63]
	v_mfma_f32_32x32x16_bf16 v[16:31], v[180:183], v[176:179], v[16:31]
	v_mfma_f32_32x32x16_bf16 v[0:15], v[196:199], v[176:179], v[0:15]
	ds_read_b128 v[200:203], v128 offset:64
	ds_read_b128 v[210:213], v128 offset:4672
	ds_read_b128 v[214:217], v131 offset:36928
	ds_read_b128 v[218:221], v131 offset:41536
	s_waitcnt lgkmcnt(1)
	v_mfma_f32_32x32x16_bf16 v[32:47], v[214:217], v[200:203], v[32:47]
	s_waitcnt lgkmcnt(0)
	v_mfma_f32_32x32x16_bf16 v[48:63], v[218:221], v[200:203], v[48:63]
	v_mfma_f32_32x32x16_bf16 v[16:31], v[214:217], v[210:213], v[16:31]
	v_mfma_f32_32x32x16_bf16 v[0:15], v[218:221], v[210:213], v[0:15]
	global_load_dwordx4 v[112:115], v168, s[8:9] offset:256
	global_load_dwordx4 v[116:119], v169, s[8:9] offset:256
	global_load_dwordx4 v[120:123], v170, s[8:9] offset:256
	global_load_dwordx4 v[124:127], v171, s[8:9] offset:256
	global_load_dwordx4 v[80:83], v168, s[10:11] offset:256
	global_load_dwordx4 v[84:87], v169, s[10:11] offset:256
	global_load_dwordx4 v[88:91], v170, s[10:11] offset:256
	global_load_dwordx4 v[92:95], v171, s[10:11] offset:256
	s_waitcnt vmcnt(15)
	ds_write_b128 v130, v[96:99] offset:18432
	s_waitcnt vmcnt(14)
	ds_write_b128 v130, v[100:103] offset:23040
	s_waitcnt vmcnt(13)
	ds_write_b128 v130, v[104:107] offset:27648
	s_waitcnt vmcnt(12)
	ds_write_b128 v130, v[108:111] offset:32256
	ds_read_b128 v[96:99], v128 offset:96
	ds_read_b128 v[100:103], v128 offset:4704
	ds_read_b128 v[104:107], v131 offset:36960
	ds_read_b128 v[108:111], v131 offset:41568
	s_waitcnt vmcnt(11)
	ds_write_b128 v130, v[64:67] offset:55296
	s_waitcnt vmcnt(10)
	ds_write_b128 v130, v[68:71] offset:59904
	s_waitcnt vmcnt(9)
	ds_write_b128 v130, v[72:75] offset:64512
	s_waitcnt vmcnt(8)
	ds_write_b128 v129, v[76:79] offset:13824
	s_waitcnt lgkmcnt(5)
	v_mfma_f32_32x32x16_bf16 v[32:47], v[104:107], v[96:99], v[32:47]
	s_waitcnt lgkmcnt(0)
	s_barrier
	v_mfma_f32_32x32x16_bf16 v[48:63], v[108:111], v[96:99], v[48:63]
	v_mfma_f32_32x32x16_bf16 v[16:31], v[104:107], v[100:103], v[16:31]
	v_mfma_f32_32x32x16_bf16 v[0:15], v[108:111], v[100:103], v[0:15]
	ds_read_b128 v[64:67], v128 offset:23040
	ds_read_b128 v[72:75], v128 offset:18432
	ds_read_b128 v[68:71], v131 offset:59904
	ds_read_b128 v[100:103], v131 offset:55296
	ds_read_b128 v[76:79], v128 offset:18464
	ds_read_b128 v[96:99], v128 offset:23072
	ds_read_b128 v[104:107], v131 offset:55328
	ds_read_b128 v[108:111], v131 offset:59936
	s_waitcnt lgkmcnt(4)
	v_mfma_f32_32x32x16_bf16 v[32:47], v[100:103], v[72:75], v[32:47]
	v_mfma_f32_32x32x16_bf16 v[48:63], v[68:71], v[72:75], v[48:63]
	v_mfma_f32_32x32x16_bf16 v[16:31], v[100:103], v[64:67], v[16:31]
	v_mfma_f32_32x32x16_bf16 v[0:15], v[68:71], v[64:67], v[0:15]
	global_load_dwordx4 v[64:67], v168, s[8:9] offset:384
	global_load_dwordx4 v[68:71], v169, s[8:9] offset:384
	global_load_dwordx4 v[72:75], v170, s[8:9] offset:384
	global_load_dwordx4 v[100:103], v171, s[8:9] offset:384
	global_load_dwordx4 v[172:175], v168, s[10:11] offset:384
	global_load_dwordx4 v[176:179], v169, s[10:11] offset:384
	global_load_dwordx4 v[180:183], v170, s[10:11] offset:384
	global_load_dwordx4 v[196:199], v171, s[10:11] offset:384
	ds_read_b128 v[200:203], v128 offset:18496
	ds_read_b128 v[210:213], v128 offset:23104
	ds_read_b128 v[214:217], v131 offset:55360
	ds_read_b128 v[218:221], v131 offset:59968
	s_waitcnt vmcnt(15)
	ds_write_b128 v130, v[112:115]
	s_waitcnt vmcnt(14)
	ds_write_b128 v130, v[116:119] offset:4608
	s_waitcnt vmcnt(13)
	ds_write_b128 v130, v[120:123] offset:9216
	s_waitcnt vmcnt(12)
	ds_write_b128 v130, v[124:127] offset:13824
	s_waitcnt lgkmcnt(9)
	v_mfma_f32_32x32x16_bf16 v[32:47], v[104:107], v[76:79], v[32:47]
	s_waitcnt lgkmcnt(8)
	v_mfma_f32_32x32x16_bf16 v[48:63], v[108:111], v[76:79], v[48:63]
	v_mfma_f32_32x32x16_bf16 v[16:31], v[104:107], v[96:99], v[16:31]
	v_mfma_f32_32x32x16_bf16 v[0:15], v[108:111], v[96:99], v[0:15]
	ds_read_b128 v[76:79], v128 offset:18528
	ds_read_b128 v[96:99], v128 offset:23136
	ds_read_b128 v[104:107], v131 offset:55392
	ds_read_b128 v[108:111], v131 offset:60000
	s_waitcnt vmcnt(11)
	ds_write_b128 v130, v[80:83] offset:36864
	s_waitcnt vmcnt(10)
	ds_write_b128 v130, v[84:87] offset:41472
	s_waitcnt vmcnt(9)
	ds_write_b128 v130, v[88:91] offset:46080
	s_waitcnt vmcnt(8)
	ds_write_b128 v130, v[92:95] offset:50688
	s_waitcnt lgkmcnt(13)
	v_mfma_f32_32x32x16_bf16 v[32:47], v[214:217], v[200:203], v[32:47]
	s_waitcnt lgkmcnt(0)
	s_barrier
	v_mfma_f32_32x32x16_bf16 v[48:63], v[218:221], v[200:203], v[48:63]
	v_mfma_f32_32x32x16_bf16 v[16:31], v[214:217], v[210:213], v[16:31]
	v_mfma_f32_32x32x16_bf16 v[0:15], v[218:221], v[210:213], v[0:15]
	v_mfma_f32_32x32x16_bf16 v[32:47], v[104:107], v[76:79], v[32:47]
	v_mfma_f32_32x32x16_bf16 v[48:63], v[108:111], v[76:79], v[48:63]
	v_mfma_f32_32x32x16_bf16 v[16:31], v[104:107], v[96:99], v[16:31]
	v_mfma_f32_32x32x16_bf16 v[0:15], v[108:111], v[96:99], v[0:15]
	ds_read_b128 v[76:79], v128 offset:4608
	ds_read_b128 v[84:87], v128
	ds_read_b128 v[80:83], v131 offset:41472
	ds_read_b128 v[96:99], v131 offset:36864
	ds_read_b128 v[88:91], v128 offset:32
	ds_read_b128 v[92:95], v128 offset:4640
	ds_read_b128 v[104:107], v131 offset:36896
	ds_read_b128 v[108:111], v131 offset:41504
	s_waitcnt lgkmcnt(4)
	v_mfma_f32_32x32x16_bf16 v[32:47], v[96:99], v[84:87], v[32:47]
	v_mfma_f32_32x32x16_bf16 v[48:63], v[80:83], v[84:87], v[48:63]
	v_mfma_f32_32x32x16_bf16 v[16:31], v[96:99], v[76:79], v[16:31]
	v_mfma_f32_32x32x16_bf16 v[0:15], v[80:83], v[76:79], v[0:15]
	global_load_dwordx4 v[76:79], v168, s[8:9] offset:512
	global_load_dwordx4 v[80:83], v169, s[8:9] offset:512
	global_load_dwordx4 v[84:87], v170, s[8:9] offset:512
	global_load_dwordx4 v[96:99], v171, s[8:9] offset:512
	global_load_dwordx4 v[112:115], v168, s[10:11] offset:512
	global_load_dwordx4 v[116:119], v169, s[10:11] offset:512
	global_load_dwordx4 v[120:123], v170, s[10:11] offset:512
	global_load_dwordx4 v[124:127], v171, s[10:11] offset:512
	ds_read_b128 v[200:203], v128 offset:64
	ds_read_b128 v[210:213], v128 offset:4672
	ds_read_b128 v[214:217], v131 offset:36928
	ds_read_b128 v[218:221], v131 offset:41536
	s_waitcnt vmcnt(15)
	ds_write_b128 v130, v[64:67] offset:18432
	s_waitcnt vmcnt(14)
	ds_write_b128 v130, v[68:71] offset:23040
	s_waitcnt vmcnt(13)
	ds_write_b128 v130, v[72:75] offset:27648
	s_waitcnt vmcnt(12)
	ds_write_b128 v130, v[100:103] offset:32256
	s_waitcnt lgkmcnt(9)
	v_mfma_f32_32x32x16_bf16 v[32:47], v[104:107], v[88:91], v[32:47]
	s_waitcnt lgkmcnt(8)
	v_mfma_f32_32x32x16_bf16 v[48:63], v[108:111], v[88:91], v[48:63]
	v_mfma_f32_32x32x16_bf16 v[16:31], v[104:107], v[92:95], v[16:31]
	v_mfma_f32_32x32x16_bf16 v[0:15], v[108:111], v[92:95], v[0:15]
	ds_read_b128 v[64:67], v128 offset:96
	ds_read_b128 v[68:71], v128 offset:4704
	ds_read_b128 v[72:75], v131 offset:36960
	ds_read_b128 v[88:91], v131 offset:41568
	s_waitcnt vmcnt(11)
	ds_write_b128 v130, v[172:175] offset:55296
	s_waitcnt vmcnt(10)
	ds_write_b128 v130, v[176:179] offset:59904
	s_waitcnt vmcnt(9)
	ds_write_b128 v130, v[180:183] offset:64512
	s_waitcnt vmcnt(8)
	ds_write_b128 v129, v[196:199] offset:13824
	s_waitcnt lgkmcnt(13)
	v_mfma_f32_32x32x16_bf16 v[32:47], v[214:217], v[200:203], v[32:47]
	s_waitcnt lgkmcnt(0)
	s_barrier
	v_mfma_f32_32x32x16_bf16 v[48:63], v[218:221], v[200:203], v[48:63]
	v_mfma_f32_32x32x16_bf16 v[16:31], v[214:217], v[210:213], v[16:31]
	v_mfma_f32_32x32x16_bf16 v[0:15], v[218:221], v[210:213], v[0:15]
	v_mfma_f32_32x32x16_bf16 v[32:47], v[72:75], v[64:67], v[32:47]
	v_mfma_f32_32x32x16_bf16 v[48:63], v[88:91], v[64:67], v[48:63]
	v_mfma_f32_32x32x16_bf16 v[16:31], v[72:75], v[68:71], v[16:31]
	v_mfma_f32_32x32x16_bf16 v[0:15], v[88:91], v[68:71], v[0:15]
	ds_read_b128 v[64:67], v128 offset:23040
	ds_read_b128 v[72:75], v128 offset:18432
	ds_read_b128 v[68:71], v131 offset:59904
	ds_read_b128 v[100:103], v131 offset:55296
	ds_read_b128 v[88:91], v128 offset:18464
	ds_read_b128 v[92:95], v128 offset:23072
	ds_read_b128 v[104:107], v131 offset:55328
	ds_read_b128 v[108:111], v131 offset:59936
	s_waitcnt lgkmcnt(4)
	v_mfma_f32_32x32x16_bf16 v[32:47], v[100:103], v[72:75], v[32:47]
	v_mfma_f32_32x32x16_bf16 v[48:63], v[68:71], v[72:75], v[48:63]
	v_mfma_f32_32x32x16_bf16 v[16:31], v[100:103], v[64:67], v[16:31]
	v_mfma_f32_32x32x16_bf16 v[0:15], v[68:71], v[64:67], v[0:15]
	global_load_dwordx4 v[64:67], v168, s[8:9] offset:640
	global_load_dwordx4 v[68:71], v169, s[8:9] offset:640
	global_load_dwordx4 v[72:75], v170, s[8:9] offset:640
	global_load_dwordx4 v[100:103], v171, s[8:9] offset:640
	global_load_dwordx4 v[172:175], v168, s[10:11] offset:640
	global_load_dwordx4 v[176:179], v169, s[10:11] offset:640
	global_load_dwordx4 v[180:183], v170, s[10:11] offset:640
	global_load_dwordx4 v[196:199], v171, s[10:11] offset:640
	ds_read_b128 v[200:203], v128 offset:18496
	ds_read_b128 v[210:213], v128 offset:23104
	ds_read_b128 v[214:217], v131 offset:55360
	ds_read_b128 v[218:221], v131 offset:59968
	s_waitcnt vmcnt(15)
	ds_write_b128 v130, v[76:79]
	s_waitcnt vmcnt(14)
	ds_write_b128 v130, v[80:83] offset:4608
	s_waitcnt vmcnt(13)
	ds_write_b128 v130, v[84:87] offset:9216
	s_waitcnt vmcnt(12)
	ds_write_b128 v130, v[96:99] offset:13824
	s_waitcnt lgkmcnt(9)
	v_mfma_f32_32x32x16_bf16 v[32:47], v[104:107], v[88:91], v[32:47]
	s_waitcnt lgkmcnt(8)
	v_mfma_f32_32x32x16_bf16 v[48:63], v[108:111], v[88:91], v[48:63]
	v_mfma_f32_32x32x16_bf16 v[16:31], v[104:107], v[92:95], v[16:31]
	v_mfma_f32_32x32x16_bf16 v[0:15], v[108:111], v[92:95], v[0:15]
	ds_read_b128 v[76:79], v128 offset:18528
	ds_read_b128 v[80:83], v128 offset:23136
	ds_read_b128 v[84:87], v131 offset:55392
	ds_read_b128 v[88:91], v131 offset:60000
	s_waitcnt vmcnt(11)
	ds_write_b128 v130, v[112:115] offset:36864
	s_waitcnt vmcnt(10)
	ds_write_b128 v130, v[116:119] offset:41472
	s_waitcnt vmcnt(9)
	ds_write_b128 v130, v[120:123] offset:46080
	s_waitcnt vmcnt(8)
	ds_write_b128 v130, v[124:127] offset:50688
	s_waitcnt lgkmcnt(13)
	v_mfma_f32_32x32x16_bf16 v[32:47], v[214:217], v[200:203], v[32:47]
	s_waitcnt lgkmcnt(0)
	s_barrier
	v_mfma_f32_32x32x16_bf16 v[48:63], v[218:221], v[200:203], v[48:63]
	v_mfma_f32_32x32x16_bf16 v[16:31], v[214:217], v[210:213], v[16:31]
	v_mfma_f32_32x32x16_bf16 v[0:15], v[218:221], v[210:213], v[0:15]
	v_mfma_f32_32x32x16_bf16 v[32:47], v[84:87], v[76:79], v[32:47]
	v_mfma_f32_32x32x16_bf16 v[48:63], v[88:91], v[76:79], v[48:63]
	v_mfma_f32_32x32x16_bf16 v[16:31], v[84:87], v[80:83], v[16:31]
	v_mfma_f32_32x32x16_bf16 v[0:15], v[88:91], v[80:83], v[0:15]
	ds_read_b128 v[76:79], v128 offset:4608
	ds_read_b128 v[84:87], v128
	ds_read_b128 v[80:83], v131 offset:41472
	ds_read_b128 v[96:99], v131 offset:36864
	ds_read_b128 v[88:91], v128 offset:32
	ds_read_b128 v[92:95], v128 offset:4640
	ds_read_b128 v[104:107], v131 offset:36896
	ds_read_b128 v[108:111], v131 offset:41504
	s_waitcnt lgkmcnt(4)
	v_mfma_f32_32x32x16_bf16 v[32:47], v[96:99], v[84:87], v[32:47]
	v_mfma_f32_32x32x16_bf16 v[48:63], v[80:83], v[84:87], v[48:63]
	v_mfma_f32_32x32x16_bf16 v[16:31], v[96:99], v[76:79], v[16:31]
	v_mfma_f32_32x32x16_bf16 v[0:15], v[80:83], v[76:79], v[0:15]
	global_load_dwordx4 v[76:79], v168, s[8:9] offset:768
	global_load_dwordx4 v[80:83], v169, s[8:9] offset:768
	global_load_dwordx4 v[84:87], v170, s[8:9] offset:768
	global_load_dwordx4 v[96:99], v171, s[8:9] offset:768
	global_load_dwordx4 v[112:115], v168, s[10:11] offset:768
	global_load_dwordx4 v[116:119], v169, s[10:11] offset:768
	global_load_dwordx4 v[120:123], v170, s[10:11] offset:768
	global_load_dwordx4 v[124:127], v171, s[10:11] offset:768
	ds_read_b128 v[200:203], v128 offset:64
	ds_read_b128 v[210:213], v128 offset:4672
	ds_read_b128 v[214:217], v131 offset:36928
	ds_read_b128 v[218:221], v131 offset:41536
	s_waitcnt vmcnt(15)
	ds_write_b128 v130, v[64:67] offset:18432
	s_waitcnt vmcnt(14)
	ds_write_b128 v130, v[68:71] offset:23040
	s_waitcnt vmcnt(13)
	ds_write_b128 v130, v[72:75] offset:27648
	s_waitcnt vmcnt(12)
	ds_write_b128 v130, v[100:103] offset:32256
	s_waitcnt lgkmcnt(9)
	v_mfma_f32_32x32x16_bf16 v[32:47], v[104:107], v[88:91], v[32:47]
	s_waitcnt lgkmcnt(8)
	v_mfma_f32_32x32x16_bf16 v[48:63], v[108:111], v[88:91], v[48:63]
	v_mfma_f32_32x32x16_bf16 v[16:31], v[104:107], v[92:95], v[16:31]
	v_mfma_f32_32x32x16_bf16 v[0:15], v[108:111], v[92:95], v[0:15]
	ds_read_b128 v[64:67], v128 offset:96
	ds_read_b128 v[68:71], v128 offset:4704
	ds_read_b128 v[72:75], v131 offset:36960
	ds_read_b128 v[88:91], v131 offset:41568
	s_waitcnt vmcnt(11)
	ds_write_b128 v130, v[172:175] offset:55296
	s_waitcnt vmcnt(10)
	ds_write_b128 v130, v[176:179] offset:59904
	s_waitcnt vmcnt(9)
	ds_write_b128 v130, v[180:183] offset:64512
	s_waitcnt vmcnt(8)
	ds_write_b128 v129, v[196:199] offset:13824
	s_waitcnt lgkmcnt(13)
	v_mfma_f32_32x32x16_bf16 v[32:47], v[214:217], v[200:203], v[32:47]
	s_waitcnt lgkmcnt(0)
	s_barrier
	v_mfma_f32_32x32x16_bf16 v[48:63], v[218:221], v[200:203], v[48:63]
	v_mfma_f32_32x32x16_bf16 v[16:31], v[214:217], v[210:213], v[16:31]
	v_mfma_f32_32x32x16_bf16 v[0:15], v[218:221], v[210:213], v[0:15]
	v_mfma_f32_32x32x16_bf16 v[32:47], v[72:75], v[64:67], v[32:47]
	v_mfma_f32_32x32x16_bf16 v[48:63], v[88:91], v[64:67], v[48:63]
	v_mfma_f32_32x32x16_bf16 v[16:31], v[72:75], v[68:71], v[16:31]
	v_mfma_f32_32x32x16_bf16 v[0:15], v[88:91], v[68:71], v[0:15]
	ds_read_b128 v[64:67], v128 offset:23040
	ds_read_b128 v[72:75], v128 offset:18432
	ds_read_b128 v[68:71], v131 offset:59904
	ds_read_b128 v[100:103], v131 offset:55296
	ds_read_b128 v[88:91], v128 offset:18464
	ds_read_b128 v[92:95], v128 offset:23072
	ds_read_b128 v[104:107], v131 offset:55328
	ds_read_b128 v[108:111], v131 offset:59936
	s_waitcnt lgkmcnt(4)
	v_mfma_f32_32x32x16_bf16 v[32:47], v[100:103], v[72:75], v[32:47]
	v_mfma_f32_32x32x16_bf16 v[48:63], v[68:71], v[72:75], v[48:63]
	v_mfma_f32_32x32x16_bf16 v[16:31], v[100:103], v[64:67], v[16:31]
	v_mfma_f32_32x32x16_bf16 v[0:15], v[68:71], v[64:67], v[0:15]
	global_load_dwordx4 v[64:67], v168, s[8:9] offset:896
	global_load_dwordx4 v[68:71], v169, s[8:9] offset:896
	global_load_dwordx4 v[72:75], v170, s[8:9] offset:896
	global_load_dwordx4 v[100:103], v171, s[8:9] offset:896
	global_load_dwordx4 v[172:175], v168, s[10:11] offset:896
	global_load_dwordx4 v[176:179], v169, s[10:11] offset:896
	global_load_dwordx4 v[180:183], v170, s[10:11] offset:896
	global_load_dwordx4 v[196:199], v171, s[10:11] offset:896
	ds_read_b128 v[200:203], v128 offset:18496
	ds_read_b128 v[210:213], v128 offset:23104
	ds_read_b128 v[214:217], v131 offset:55360
	ds_read_b128 v[218:221], v131 offset:59968
	s_waitcnt vmcnt(15)
	ds_write_b128 v130, v[76:79]
	s_waitcnt vmcnt(14)
	ds_write_b128 v130, v[80:83] offset:4608
	s_waitcnt vmcnt(13)
	ds_write_b128 v130, v[84:87] offset:9216
	s_waitcnt vmcnt(12)
	ds_write_b128 v130, v[96:99] offset:13824
	s_waitcnt lgkmcnt(9)
	v_mfma_f32_32x32x16_bf16 v[32:47], v[104:107], v[88:91], v[32:47]
	s_waitcnt lgkmcnt(8)
	v_mfma_f32_32x32x16_bf16 v[48:63], v[108:111], v[88:91], v[48:63]
	v_mfma_f32_32x32x16_bf16 v[16:31], v[104:107], v[92:95], v[16:31]
	v_mfma_f32_32x32x16_bf16 v[0:15], v[108:111], v[92:95], v[0:15]
	ds_read_b128 v[76:79], v128 offset:18528
	ds_read_b128 v[80:83], v128 offset:23136
	ds_read_b128 v[84:87], v131 offset:55392
	ds_read_b128 v[88:91], v131 offset:60000
	s_waitcnt vmcnt(11)
	ds_write_b128 v130, v[112:115] offset:36864
	s_waitcnt vmcnt(10)
	ds_write_b128 v130, v[116:119] offset:41472
	s_waitcnt vmcnt(9)
	ds_write_b128 v130, v[120:123] offset:46080
	s_waitcnt vmcnt(8)
	ds_write_b128 v130, v[124:127] offset:50688
	s_waitcnt lgkmcnt(13)
	v_mfma_f32_32x32x16_bf16 v[32:47], v[214:217], v[200:203], v[32:47]
	s_waitcnt lgkmcnt(0)
	s_barrier
	v_mfma_f32_32x32x16_bf16 v[48:63], v[218:221], v[200:203], v[48:63]
	v_mfma_f32_32x32x16_bf16 v[16:31], v[214:217], v[210:213], v[16:31]
	v_mfma_f32_32x32x16_bf16 v[0:15], v[218:221], v[210:213], v[0:15]
	v_mfma_f32_32x32x16_bf16 v[32:47], v[84:87], v[76:79], v[32:47]
	v_mfma_f32_32x32x16_bf16 v[48:63], v[88:91], v[76:79], v[48:63]
	v_mfma_f32_32x32x16_bf16 v[16:31], v[84:87], v[80:83], v[16:31]
	v_mfma_f32_32x32x16_bf16 v[0:15], v[88:91], v[80:83], v[0:15]
	ds_read_b128 v[76:79], v128 offset:4608
	ds_read_b128 v[84:87], v128
	ds_read_b128 v[80:83], v131 offset:41472
	ds_read_b128 v[96:99], v131 offset:36864
	ds_read_b128 v[88:91], v128 offset:32
	ds_read_b128 v[92:95], v128 offset:4640
	ds_read_b128 v[104:107], v131 offset:36896
	ds_read_b128 v[108:111], v131 offset:41504
	s_waitcnt lgkmcnt(4)
	v_mfma_f32_32x32x16_bf16 v[32:47], v[96:99], v[84:87], v[32:47]
	v_mfma_f32_32x32x16_bf16 v[48:63], v[80:83], v[84:87], v[48:63]
	v_mfma_f32_32x32x16_bf16 v[16:31], v[96:99], v[76:79], v[16:31]
	v_mfma_f32_32x32x16_bf16 v[0:15], v[80:83], v[76:79], v[0:15]
	global_load_dwordx4 v[76:79], v168, s[8:9] offset:1024
	global_load_dwordx4 v[80:83], v169, s[8:9] offset:1024
	global_load_dwordx4 v[84:87], v170, s[8:9] offset:1024
	global_load_dwordx4 v[96:99], v171, s[8:9] offset:1024
	global_load_dwordx4 v[112:115], v168, s[10:11] offset:1024
	global_load_dwordx4 v[116:119], v169, s[10:11] offset:1024
	global_load_dwordx4 v[120:123], v170, s[10:11] offset:1024
	global_load_dwordx4 v[124:127], v171, s[10:11] offset:1024
	ds_read_b128 v[200:203], v128 offset:64
	ds_read_b128 v[210:213], v128 offset:4672
	ds_read_b128 v[214:217], v131 offset:36928
	ds_read_b128 v[218:221], v131 offset:41536
	s_waitcnt vmcnt(15)
	ds_write_b128 v130, v[64:67] offset:18432
	s_waitcnt vmcnt(14)
	ds_write_b128 v130, v[68:71] offset:23040
	s_waitcnt vmcnt(13)
	ds_write_b128 v130, v[72:75] offset:27648
	s_waitcnt vmcnt(12)
	ds_write_b128 v130, v[100:103] offset:32256
	s_waitcnt lgkmcnt(9)
	v_mfma_f32_32x32x16_bf16 v[32:47], v[104:107], v[88:91], v[32:47]
	s_waitcnt lgkmcnt(8)
	v_mfma_f32_32x32x16_bf16 v[48:63], v[108:111], v[88:91], v[48:63]
	v_mfma_f32_32x32x16_bf16 v[16:31], v[104:107], v[92:95], v[16:31]
	v_mfma_f32_32x32x16_bf16 v[0:15], v[108:111], v[92:95], v[0:15]
	ds_read_b128 v[64:67], v128 offset:96
	ds_read_b128 v[68:71], v128 offset:4704
	ds_read_b128 v[72:75], v131 offset:36960
	ds_read_b128 v[88:91], v131 offset:41568
	s_waitcnt vmcnt(11)
	ds_write_b128 v130, v[172:175] offset:55296
	s_waitcnt vmcnt(10)
	ds_write_b128 v130, v[176:179] offset:59904
	s_waitcnt vmcnt(9)
	ds_write_b128 v130, v[180:183] offset:64512
	s_waitcnt vmcnt(8)
	ds_write_b128 v129, v[196:199] offset:13824
	s_waitcnt lgkmcnt(13)
	v_mfma_f32_32x32x16_bf16 v[32:47], v[214:217], v[200:203], v[32:47]
	s_waitcnt lgkmcnt(0)
	s_barrier
	v_mfma_f32_32x32x16_bf16 v[48:63], v[218:221], v[200:203], v[48:63]
	v_mfma_f32_32x32x16_bf16 v[16:31], v[214:217], v[210:213], v[16:31]
	v_mfma_f32_32x32x16_bf16 v[0:15], v[218:221], v[210:213], v[0:15]
	v_mfma_f32_32x32x16_bf16 v[32:47], v[72:75], v[64:67], v[32:47]
	v_mfma_f32_32x32x16_bf16 v[48:63], v[88:91], v[64:67], v[48:63]
	v_mfma_f32_32x32x16_bf16 v[16:31], v[72:75], v[68:71], v[16:31]
	v_mfma_f32_32x32x16_bf16 v[0:15], v[88:91], v[68:71], v[0:15]
	ds_read_b128 v[64:67], v128 offset:23040
	ds_read_b128 v[72:75], v128 offset:18432
	ds_read_b128 v[68:71], v131 offset:59904
	ds_read_b128 v[100:103], v131 offset:55296
	ds_read_b128 v[88:91], v128 offset:18464
	ds_read_b128 v[92:95], v128 offset:23072
	ds_read_b128 v[104:107], v131 offset:55328
	ds_read_b128 v[108:111], v131 offset:59936
	s_waitcnt lgkmcnt(4)
	v_mfma_f32_32x32x16_bf16 v[32:47], v[100:103], v[72:75], v[32:47]
	v_mfma_f32_32x32x16_bf16 v[48:63], v[68:71], v[72:75], v[48:63]
	v_mfma_f32_32x32x16_bf16 v[16:31], v[100:103], v[64:67], v[16:31]
	v_mfma_f32_32x32x16_bf16 v[0:15], v[68:71], v[64:67], v[0:15]
	global_load_dwordx4 v[64:67], v168, s[8:9] offset:1152
	global_load_dwordx4 v[68:71], v169, s[8:9] offset:1152
	global_load_dwordx4 v[72:75], v170, s[8:9] offset:1152
	global_load_dwordx4 v[100:103], v171, s[8:9] offset:1152
	global_load_dwordx4 v[172:175], v168, s[10:11] offset:1152
	global_load_dwordx4 v[176:179], v169, s[10:11] offset:1152
	global_load_dwordx4 v[180:183], v170, s[10:11] offset:1152
	global_load_dwordx4 v[196:199], v171, s[10:11] offset:1152
	ds_read_b128 v[200:203], v128 offset:18496
	ds_read_b128 v[210:213], v128 offset:23104
	ds_read_b128 v[214:217], v131 offset:55360
	ds_read_b128 v[218:221], v131 offset:59968
	s_waitcnt vmcnt(15)
	ds_write_b128 v130, v[76:79]
	s_waitcnt vmcnt(14)
	ds_write_b128 v130, v[80:83] offset:4608
	s_waitcnt vmcnt(13)
	ds_write_b128 v130, v[84:87] offset:9216
	s_waitcnt vmcnt(12)
	ds_write_b128 v130, v[96:99] offset:13824
	s_waitcnt lgkmcnt(9)
	v_mfma_f32_32x32x16_bf16 v[32:47], v[104:107], v[88:91], v[32:47]
	s_waitcnt lgkmcnt(8)
	v_mfma_f32_32x32x16_bf16 v[48:63], v[108:111], v[88:91], v[48:63]
	v_mfma_f32_32x32x16_bf16 v[16:31], v[104:107], v[92:95], v[16:31]
	v_mfma_f32_32x32x16_bf16 v[0:15], v[108:111], v[92:95], v[0:15]
	ds_read_b128 v[76:79], v128 offset:18528
	ds_read_b128 v[80:83], v128 offset:23136
	ds_read_b128 v[84:87], v131 offset:55392
	ds_read_b128 v[88:91], v131 offset:60000
	s_waitcnt vmcnt(11)
	ds_write_b128 v130, v[112:115] offset:36864
	s_waitcnt vmcnt(10)
	ds_write_b128 v130, v[116:119] offset:41472
	s_waitcnt vmcnt(9)
	ds_write_b128 v130, v[120:123] offset:46080
	s_waitcnt vmcnt(8)
	ds_write_b128 v130, v[124:127] offset:50688
	s_waitcnt lgkmcnt(13)
	v_mfma_f32_32x32x16_bf16 v[32:47], v[214:217], v[200:203], v[32:47]
	s_waitcnt lgkmcnt(0)
	s_barrier
	v_mfma_f32_32x32x16_bf16 v[48:63], v[218:221], v[200:203], v[48:63]
	v_mfma_f32_32x32x16_bf16 v[16:31], v[214:217], v[210:213], v[16:31]
	v_mfma_f32_32x32x16_bf16 v[0:15], v[218:221], v[210:213], v[0:15]
	v_mfma_f32_32x32x16_bf16 v[32:47], v[84:87], v[76:79], v[32:47]
	v_mfma_f32_32x32x16_bf16 v[48:63], v[88:91], v[76:79], v[48:63]
	v_mfma_f32_32x32x16_bf16 v[16:31], v[84:87], v[80:83], v[16:31]
	v_mfma_f32_32x32x16_bf16 v[0:15], v[88:91], v[80:83], v[0:15]
	ds_read_b128 v[76:79], v128 offset:4608
	ds_read_b128 v[84:87], v128
	ds_read_b128 v[80:83], v131 offset:41472
	ds_read_b128 v[96:99], v131 offset:36864
	ds_read_b128 v[88:91], v128 offset:32
	ds_read_b128 v[92:95], v128 offset:4640
	ds_read_b128 v[104:107], v131 offset:36896
	ds_read_b128 v[108:111], v131 offset:41504
	s_waitcnt lgkmcnt(4)
	v_mfma_f32_32x32x16_bf16 v[32:47], v[96:99], v[84:87], v[32:47]
	v_mfma_f32_32x32x16_bf16 v[48:63], v[80:83], v[84:87], v[48:63]
	v_mfma_f32_32x32x16_bf16 v[16:31], v[96:99], v[76:79], v[16:31]
	v_mfma_f32_32x32x16_bf16 v[0:15], v[80:83], v[76:79], v[0:15]
	global_load_dwordx4 v[76:79], v168, s[8:9] offset:1280
	global_load_dwordx4 v[80:83], v169, s[8:9] offset:1280
	global_load_dwordx4 v[84:87], v170, s[8:9] offset:1280
	global_load_dwordx4 v[96:99], v171, s[8:9] offset:1280
	global_load_dwordx4 v[112:115], v168, s[10:11] offset:1280
	global_load_dwordx4 v[116:119], v169, s[10:11] offset:1280
	global_load_dwordx4 v[120:123], v170, s[10:11] offset:1280
	global_load_dwordx4 v[124:127], v171, s[10:11] offset:1280
	ds_read_b128 v[200:203], v128 offset:64
	ds_read_b128 v[210:213], v128 offset:4672
	ds_read_b128 v[214:217], v131 offset:36928
	ds_read_b128 v[218:221], v131 offset:41536
	s_waitcnt vmcnt(15)
	ds_write_b128 v130, v[64:67] offset:18432
	s_waitcnt vmcnt(14)
	ds_write_b128 v130, v[68:71] offset:23040
	s_waitcnt vmcnt(13)
	ds_write_b128 v130, v[72:75] offset:27648
	s_waitcnt vmcnt(12)
	ds_write_b128 v130, v[100:103] offset:32256
	s_waitcnt lgkmcnt(9)
	v_mfma_f32_32x32x16_bf16 v[32:47], v[104:107], v[88:91], v[32:47]
	s_waitcnt lgkmcnt(8)
	v_mfma_f32_32x32x16_bf16 v[48:63], v[108:111], v[88:91], v[48:63]
	v_mfma_f32_32x32x16_bf16 v[16:31], v[104:107], v[92:95], v[16:31]
	v_mfma_f32_32x32x16_bf16 v[0:15], v[108:111], v[92:95], v[0:15]
	ds_read_b128 v[64:67], v128 offset:96
	ds_read_b128 v[68:71], v128 offset:4704
	ds_read_b128 v[72:75], v131 offset:36960
	ds_read_b128 v[88:91], v131 offset:41568
	s_waitcnt vmcnt(11)
	ds_write_b128 v130, v[172:175] offset:55296
	s_waitcnt vmcnt(10)
	ds_write_b128 v130, v[176:179] offset:59904
	s_waitcnt vmcnt(9)
	ds_write_b128 v130, v[180:183] offset:64512
	s_waitcnt vmcnt(8)
	ds_write_b128 v129, v[196:199] offset:13824
	s_waitcnt lgkmcnt(13)
	v_mfma_f32_32x32x16_bf16 v[32:47], v[214:217], v[200:203], v[32:47]
	s_waitcnt lgkmcnt(0)
	s_barrier
	v_mfma_f32_32x32x16_bf16 v[48:63], v[218:221], v[200:203], v[48:63]
	v_mfma_f32_32x32x16_bf16 v[16:31], v[214:217], v[210:213], v[16:31]
	v_mfma_f32_32x32x16_bf16 v[0:15], v[218:221], v[210:213], v[0:15]
	v_mfma_f32_32x32x16_bf16 v[32:47], v[72:75], v[64:67], v[32:47]
	v_mfma_f32_32x32x16_bf16 v[48:63], v[88:91], v[64:67], v[48:63]
	v_mfma_f32_32x32x16_bf16 v[16:31], v[72:75], v[68:71], v[16:31]
	v_mfma_f32_32x32x16_bf16 v[0:15], v[88:91], v[68:71], v[0:15]
	ds_read_b128 v[64:67], v128 offset:23040
	ds_read_b128 v[72:75], v128 offset:18432
	ds_read_b128 v[68:71], v131 offset:59904
	ds_read_b128 v[100:103], v131 offset:55296
	ds_read_b128 v[88:91], v128 offset:18464
	ds_read_b128 v[92:95], v128 offset:23072
	ds_read_b128 v[104:107], v131 offset:55328
	ds_read_b128 v[108:111], v131 offset:59936
	s_waitcnt lgkmcnt(4)
	v_mfma_f32_32x32x16_bf16 v[32:47], v[100:103], v[72:75], v[32:47]
	v_mfma_f32_32x32x16_bf16 v[48:63], v[68:71], v[72:75], v[48:63]
	v_mfma_f32_32x32x16_bf16 v[16:31], v[100:103], v[64:67], v[16:31]
	v_mfma_f32_32x32x16_bf16 v[0:15], v[68:71], v[64:67], v[0:15]
	global_load_dwordx4 v[64:67], v168, s[8:9] offset:1408
	global_load_dwordx4 v[68:71], v169, s[8:9] offset:1408
	global_load_dwordx4 v[72:75], v170, s[8:9] offset:1408
	global_load_dwordx4 v[100:103], v171, s[8:9] offset:1408
	global_load_dwordx4 v[172:175], v168, s[10:11] offset:1408
	global_load_dwordx4 v[176:179], v169, s[10:11] offset:1408
	global_load_dwordx4 v[180:183], v170, s[10:11] offset:1408
	global_load_dwordx4 v[196:199], v171, s[10:11] offset:1408
	ds_read_b128 v[200:203], v128 offset:18496
	ds_read_b128 v[210:213], v128 offset:23104
	ds_read_b128 v[214:217], v131 offset:55360
	ds_read_b128 v[218:221], v131 offset:59968
	s_waitcnt vmcnt(15)
	ds_write_b128 v130, v[76:79]
	s_waitcnt vmcnt(14)
	ds_write_b128 v130, v[80:83] offset:4608
	s_waitcnt vmcnt(13)
	ds_write_b128 v130, v[84:87] offset:9216
	s_waitcnt vmcnt(12)
	ds_write_b128 v130, v[96:99] offset:13824
	s_waitcnt lgkmcnt(9)
	v_mfma_f32_32x32x16_bf16 v[32:47], v[104:107], v[88:91], v[32:47]
	s_waitcnt lgkmcnt(8)
	v_mfma_f32_32x32x16_bf16 v[48:63], v[108:111], v[88:91], v[48:63]
	v_mfma_f32_32x32x16_bf16 v[16:31], v[104:107], v[92:95], v[16:31]
	v_mfma_f32_32x32x16_bf16 v[0:15], v[108:111], v[92:95], v[0:15]
	ds_read_b128 v[76:79], v128 offset:18528
	ds_read_b128 v[80:83], v128 offset:23136
	ds_read_b128 v[84:87], v131 offset:55392
	ds_read_b128 v[88:91], v131 offset:60000
	s_waitcnt vmcnt(11)
	ds_write_b128 v130, v[112:115] offset:36864
	s_waitcnt vmcnt(10)
	ds_write_b128 v130, v[116:119] offset:41472
	s_waitcnt vmcnt(9)
	ds_write_b128 v130, v[120:123] offset:46080
	s_waitcnt vmcnt(8)
	ds_write_b128 v130, v[124:127] offset:50688
	s_waitcnt lgkmcnt(13)
	v_mfma_f32_32x32x16_bf16 v[32:47], v[214:217], v[200:203], v[32:47]
	s_waitcnt lgkmcnt(0)
	s_barrier
	v_mfma_f32_32x32x16_bf16 v[48:63], v[218:221], v[200:203], v[48:63]
	v_mfma_f32_32x32x16_bf16 v[16:31], v[214:217], v[210:213], v[16:31]
	v_mfma_f32_32x32x16_bf16 v[0:15], v[218:221], v[210:213], v[0:15]
	v_mfma_f32_32x32x16_bf16 v[32:47], v[84:87], v[76:79], v[32:47]
	v_mfma_f32_32x32x16_bf16 v[48:63], v[88:91], v[76:79], v[48:63]
	v_mfma_f32_32x32x16_bf16 v[16:31], v[84:87], v[80:83], v[16:31]
	v_mfma_f32_32x32x16_bf16 v[0:15], v[88:91], v[80:83], v[0:15]
	ds_read_b128 v[76:79], v128 offset:4608
	ds_read_b128 v[84:87], v128
	ds_read_b128 v[80:83], v131 offset:41472
	ds_read_b128 v[96:99], v131 offset:36864
	ds_read_b128 v[88:91], v128 offset:32
	ds_read_b128 v[92:95], v128 offset:4640
	ds_read_b128 v[104:107], v131 offset:36896
	ds_read_b128 v[108:111], v131 offset:41504
	s_waitcnt lgkmcnt(4)
	v_mfma_f32_32x32x16_bf16 v[32:47], v[96:99], v[84:87], v[32:47]
	v_mfma_f32_32x32x16_bf16 v[48:63], v[80:83], v[84:87], v[48:63]
	v_mfma_f32_32x32x16_bf16 v[16:31], v[96:99], v[76:79], v[16:31]
	v_mfma_f32_32x32x16_bf16 v[0:15], v[80:83], v[76:79], v[0:15]
	global_load_dwordx4 v[76:79], v168, s[8:9] offset:1536
	global_load_dwordx4 v[80:83], v169, s[8:9] offset:1536
	global_load_dwordx4 v[84:87], v170, s[8:9] offset:1536
	global_load_dwordx4 v[96:99], v171, s[8:9] offset:1536
	global_load_dwordx4 v[112:115], v168, s[10:11] offset:1536
	global_load_dwordx4 v[116:119], v169, s[10:11] offset:1536
	global_load_dwordx4 v[120:123], v170, s[10:11] offset:1536
	global_load_dwordx4 v[124:127], v171, s[10:11] offset:1536
	ds_read_b128 v[200:203], v128 offset:64
	ds_read_b128 v[210:213], v128 offset:4672
	ds_read_b128 v[214:217], v131 offset:36928
	ds_read_b128 v[218:221], v131 offset:41536
	s_waitcnt vmcnt(15)
	ds_write_b128 v130, v[64:67] offset:18432
	s_waitcnt vmcnt(14)
	ds_write_b128 v130, v[68:71] offset:23040
	s_waitcnt vmcnt(13)
	ds_write_b128 v130, v[72:75] offset:27648
	s_waitcnt vmcnt(12)
	ds_write_b128 v130, v[100:103] offset:32256
	s_waitcnt lgkmcnt(9)
	v_mfma_f32_32x32x16_bf16 v[32:47], v[104:107], v[88:91], v[32:47]
	s_waitcnt lgkmcnt(8)
	v_mfma_f32_32x32x16_bf16 v[48:63], v[108:111], v[88:91], v[48:63]
	v_mfma_f32_32x32x16_bf16 v[16:31], v[104:107], v[92:95], v[16:31]
	v_mfma_f32_32x32x16_bf16 v[0:15], v[108:111], v[92:95], v[0:15]
	ds_read_b128 v[64:67], v128 offset:96
	ds_read_b128 v[68:71], v128 offset:4704
	ds_read_b128 v[72:75], v131 offset:36960
	ds_read_b128 v[88:91], v131 offset:41568
	s_waitcnt vmcnt(11)
	ds_write_b128 v130, v[172:175] offset:55296
	s_waitcnt vmcnt(10)
	ds_write_b128 v130, v[176:179] offset:59904
	s_waitcnt vmcnt(9)
	ds_write_b128 v130, v[180:183] offset:64512
	s_waitcnt vmcnt(8)
	ds_write_b128 v129, v[196:199] offset:13824
	s_waitcnt lgkmcnt(13)
	v_mfma_f32_32x32x16_bf16 v[32:47], v[214:217], v[200:203], v[32:47]
	s_waitcnt lgkmcnt(0)
	s_barrier
	v_mfma_f32_32x32x16_bf16 v[48:63], v[218:221], v[200:203], v[48:63]
	v_mfma_f32_32x32x16_bf16 v[16:31], v[214:217], v[210:213], v[16:31]
	v_mfma_f32_32x32x16_bf16 v[0:15], v[218:221], v[210:213], v[0:15]
	v_mfma_f32_32x32x16_bf16 v[32:47], v[72:75], v[64:67], v[32:47]
	v_mfma_f32_32x32x16_bf16 v[48:63], v[88:91], v[64:67], v[48:63]
	v_mfma_f32_32x32x16_bf16 v[16:31], v[72:75], v[68:71], v[16:31]
	v_mfma_f32_32x32x16_bf16 v[0:15], v[88:91], v[68:71], v[0:15]
	ds_read_b128 v[64:67], v128 offset:23040
	ds_read_b128 v[72:75], v128 offset:18432
	ds_read_b128 v[68:71], v131 offset:59904
	ds_read_b128 v[100:103], v131 offset:55296
	ds_read_b128 v[88:91], v128 offset:18464
	ds_read_b128 v[92:95], v128 offset:23072
	ds_read_b128 v[104:107], v131 offset:55328
	ds_read_b128 v[108:111], v131 offset:59936
	s_waitcnt lgkmcnt(4)
	v_mfma_f32_32x32x16_bf16 v[32:47], v[100:103], v[72:75], v[32:47]
	v_mfma_f32_32x32x16_bf16 v[48:63], v[68:71], v[72:75], v[48:63]
	v_mfma_f32_32x32x16_bf16 v[16:31], v[100:103], v[64:67], v[16:31]
	v_mfma_f32_32x32x16_bf16 v[0:15], v[68:71], v[64:67], v[0:15]
	global_load_dwordx4 v[64:67], v168, s[8:9] offset:1664
	global_load_dwordx4 v[68:71], v169, s[8:9] offset:1664
	global_load_dwordx4 v[72:75], v170, s[8:9] offset:1664
	global_load_dwordx4 v[100:103], v171, s[8:9] offset:1664
	global_load_dwordx4 v[172:175], v168, s[10:11] offset:1664
	global_load_dwordx4 v[176:179], v169, s[10:11] offset:1664
	global_load_dwordx4 v[180:183], v170, s[10:11] offset:1664
	global_load_dwordx4 v[196:199], v171, s[10:11] offset:1664
	ds_read_b128 v[200:203], v128 offset:18496
	ds_read_b128 v[210:213], v128 offset:23104
	ds_read_b128 v[214:217], v131 offset:55360
	ds_read_b128 v[218:221], v131 offset:59968
	s_waitcnt vmcnt(15)
	ds_write_b128 v130, v[76:79]
	s_waitcnt vmcnt(14)
	ds_write_b128 v130, v[80:83] offset:4608
	s_waitcnt vmcnt(13)
	ds_write_b128 v130, v[84:87] offset:9216
	s_waitcnt vmcnt(12)
	ds_write_b128 v130, v[96:99] offset:13824
	s_waitcnt lgkmcnt(9)
	v_mfma_f32_32x32x16_bf16 v[32:47], v[104:107], v[88:91], v[32:47]
	s_waitcnt lgkmcnt(8)
	v_mfma_f32_32x32x16_bf16 v[48:63], v[108:111], v[88:91], v[48:63]
	v_mfma_f32_32x32x16_bf16 v[16:31], v[104:107], v[92:95], v[16:31]
	v_mfma_f32_32x32x16_bf16 v[0:15], v[108:111], v[92:95], v[0:15]
	ds_read_b128 v[76:79], v128 offset:18528
	ds_read_b128 v[80:83], v128 offset:23136
	ds_read_b128 v[84:87], v131 offset:55392
	ds_read_b128 v[88:91], v131 offset:60000
	s_waitcnt vmcnt(11)
	ds_write_b128 v130, v[112:115] offset:36864
	s_waitcnt vmcnt(10)
	ds_write_b128 v130, v[116:119] offset:41472
	s_waitcnt vmcnt(9)
	ds_write_b128 v130, v[120:123] offset:46080
	s_waitcnt vmcnt(8)
	ds_write_b128 v130, v[124:127] offset:50688
	s_waitcnt lgkmcnt(13)
	v_mfma_f32_32x32x16_bf16 v[32:47], v[214:217], v[200:203], v[32:47]
	s_waitcnt lgkmcnt(0)
	s_barrier
	v_mfma_f32_32x32x16_bf16 v[48:63], v[218:221], v[200:203], v[48:63]
	v_mfma_f32_32x32x16_bf16 v[16:31], v[214:217], v[210:213], v[16:31]
	v_mfma_f32_32x32x16_bf16 v[0:15], v[218:221], v[210:213], v[0:15]
	v_mfma_f32_32x32x16_bf16 v[32:47], v[84:87], v[76:79], v[32:47]
	v_mfma_f32_32x32x16_bf16 v[48:63], v[88:91], v[76:79], v[48:63]
	v_mfma_f32_32x32x16_bf16 v[16:31], v[84:87], v[80:83], v[16:31]
	v_mfma_f32_32x32x16_bf16 v[0:15], v[88:91], v[80:83], v[0:15]
	ds_read_b128 v[76:79], v128 offset:4608
	ds_read_b128 v[84:87], v128
	ds_read_b128 v[80:83], v131 offset:41472
	ds_read_b128 v[96:99], v131 offset:36864
	ds_read_b128 v[88:91], v128 offset:32
	ds_read_b128 v[92:95], v128 offset:4640
	ds_read_b128 v[104:107], v131 offset:36896
	ds_read_b128 v[108:111], v131 offset:41504
	s_waitcnt lgkmcnt(4)
	v_mfma_f32_32x32x16_bf16 v[32:47], v[96:99], v[84:87], v[32:47]
	v_mfma_f32_32x32x16_bf16 v[48:63], v[80:83], v[84:87], v[48:63]
	v_mfma_f32_32x32x16_bf16 v[16:31], v[96:99], v[76:79], v[16:31]
	v_mfma_f32_32x32x16_bf16 v[0:15], v[80:83], v[76:79], v[0:15]
	global_load_dwordx4 v[76:79], v168, s[8:9] offset:1792
	global_load_dwordx4 v[80:83], v169, s[8:9] offset:1792
	global_load_dwordx4 v[84:87], v170, s[8:9] offset:1792
	global_load_dwordx4 v[96:99], v171, s[8:9] offset:1792
	global_load_dwordx4 v[112:115], v168, s[10:11] offset:1792
	global_load_dwordx4 v[116:119], v169, s[10:11] offset:1792
	global_load_dwordx4 v[120:123], v170, s[10:11] offset:1792
	global_load_dwordx4 v[124:127], v171, s[10:11] offset:1792
	ds_read_b128 v[200:203], v128 offset:64
	ds_read_b128 v[210:213], v128 offset:4672
	ds_read_b128 v[214:217], v131 offset:36928
	ds_read_b128 v[218:221], v131 offset:41536
	s_waitcnt vmcnt(15)
	ds_write_b128 v130, v[64:67] offset:18432
	s_waitcnt vmcnt(14)
	ds_write_b128 v130, v[68:71] offset:23040
	s_waitcnt vmcnt(13)
	ds_write_b128 v130, v[72:75] offset:27648
	s_waitcnt vmcnt(12)
	ds_write_b128 v130, v[100:103] offset:32256
	s_waitcnt lgkmcnt(9)
	v_mfma_f32_32x32x16_bf16 v[32:47], v[104:107], v[88:91], v[32:47]
	s_waitcnt lgkmcnt(8)
	v_mfma_f32_32x32x16_bf16 v[48:63], v[108:111], v[88:91], v[48:63]
	v_mfma_f32_32x32x16_bf16 v[16:31], v[104:107], v[92:95], v[16:31]
	v_mfma_f32_32x32x16_bf16 v[0:15], v[108:111], v[92:95], v[0:15]
	ds_read_b128 v[64:67], v128 offset:96
	ds_read_b128 v[68:71], v128 offset:4704
	ds_read_b128 v[72:75], v131 offset:36960
	ds_read_b128 v[88:91], v131 offset:41568
	s_waitcnt vmcnt(11)
	ds_write_b128 v130, v[172:175] offset:55296
	s_waitcnt vmcnt(10)
	ds_write_b128 v130, v[176:179] offset:59904
	s_waitcnt vmcnt(9)
	ds_write_b128 v130, v[180:183] offset:64512
	s_waitcnt vmcnt(8)
	ds_write_b128 v129, v[196:199] offset:13824
	s_waitcnt lgkmcnt(13)
	v_mfma_f32_32x32x16_bf16 v[32:47], v[214:217], v[200:203], v[32:47]
	s_waitcnt lgkmcnt(0)
	s_barrier
	v_mfma_f32_32x32x16_bf16 v[48:63], v[218:221], v[200:203], v[48:63]
	v_mfma_f32_32x32x16_bf16 v[16:31], v[214:217], v[210:213], v[16:31]
	v_mfma_f32_32x32x16_bf16 v[0:15], v[218:221], v[210:213], v[0:15]
	v_mfma_f32_32x32x16_bf16 v[32:47], v[72:75], v[64:67], v[32:47]
	v_mfma_f32_32x32x16_bf16 v[48:63], v[88:91], v[64:67], v[48:63]
	v_mfma_f32_32x32x16_bf16 v[16:31], v[72:75], v[68:71], v[16:31]
	v_mfma_f32_32x32x16_bf16 v[0:15], v[88:91], v[68:71], v[0:15]
	ds_read_b128 v[64:67], v128 offset:23040
	ds_read_b128 v[72:75], v128 offset:18432
	ds_read_b128 v[68:71], v131 offset:59904
	ds_read_b128 v[100:103], v131 offset:55296
	ds_read_b128 v[88:91], v128 offset:18464
	ds_read_b128 v[92:95], v128 offset:23072
	ds_read_b128 v[104:107], v131 offset:55328
	ds_read_b128 v[108:111], v131 offset:59936
	s_waitcnt lgkmcnt(4)
	v_mfma_f32_32x32x16_bf16 v[32:47], v[100:103], v[72:75], v[32:47]
	v_mfma_f32_32x32x16_bf16 v[48:63], v[68:71], v[72:75], v[48:63]
	v_mfma_f32_32x32x16_bf16 v[16:31], v[100:103], v[64:67], v[16:31]
	v_mfma_f32_32x32x16_bf16 v[0:15], v[68:71], v[64:67], v[0:15]
	global_load_dwordx4 v[64:67], v168, s[8:9] offset:1920
	global_load_dwordx4 v[68:71], v169, s[8:9] offset:1920
	global_load_dwordx4 v[72:75], v170, s[8:9] offset:1920
	global_load_dwordx4 v[100:103], v171, s[8:9] offset:1920
	global_load_dwordx4 v[172:175], v168, s[10:11] offset:1920
	global_load_dwordx4 v[176:179], v169, s[10:11] offset:1920
	global_load_dwordx4 v[180:183], v170, s[10:11] offset:1920
	s_nop 0
	global_load_dwordx4 v[168:171], v171, s[10:11] offset:1920
	ds_read_b128 v[196:199], v128 offset:18496
	ds_read_b128 v[200:203], v128 offset:23104
	ds_read_b128 v[210:213], v131 offset:55360
	ds_read_b128 v[214:217], v131 offset:59968
	s_waitcnt vmcnt(15)
	ds_write_b128 v130, v[76:79]
	s_waitcnt vmcnt(14)
	ds_write_b128 v130, v[80:83] offset:4608
	s_waitcnt vmcnt(13)
	ds_write_b128 v130, v[84:87] offset:9216
	s_waitcnt vmcnt(12)
	ds_write_b128 v130, v[96:99] offset:13824
	s_waitcnt lgkmcnt(9)
	v_mfma_f32_32x32x16_bf16 v[32:47], v[104:107], v[88:91], v[32:47]
	s_waitcnt lgkmcnt(8)
	v_mfma_f32_32x32x16_bf16 v[48:63], v[108:111], v[88:91], v[48:63]
	v_mfma_f32_32x32x16_bf16 v[0:15], v[108:111], v[92:95], v[0:15]
	v_mfma_f32_32x32x16_bf16 v[16:31], v[104:107], v[92:95], v[16:31]
	ds_read_b128 v[76:79], v128 offset:18528
	ds_read_b128 v[80:83], v128 offset:23136
	ds_read_b128 v[84:87], v131 offset:55392
	ds_read_b128 v[88:91], v131 offset:60000
	s_waitcnt vmcnt(11)
	ds_write_b128 v130, v[112:115] offset:36864
	s_waitcnt vmcnt(10)
	ds_write_b128 v130, v[116:119] offset:41472
	s_waitcnt vmcnt(9)
	ds_write_b128 v130, v[120:123] offset:46080
	s_waitcnt vmcnt(8)
	ds_write_b128 v130, v[124:127] offset:50688
	s_waitcnt lgkmcnt(13)
	v_mfma_f32_32x32x16_bf16 v[32:47], v[210:213], v[196:199], v[32:47]
	s_waitcnt lgkmcnt(0)
	s_barrier
	ds_read_b128 v[92:95], v128
	ds_read_b128 v[96:99], v128 offset:32
	ds_read_b128 v[104:107], v131 offset:36928
	ds_read_b128 v[108:111], v131 offset:41536
	v_mfma_f32_32x32x16_bf16 v[48:63], v[214:217], v[196:199], v[48:63]
	v_mfma_f32_32x32x16_bf16 v[0:15], v[214:217], v[200:203], v[0:15]
	v_mfma_f32_32x32x16_bf16 v[16:31], v[210:213], v[200:203], v[16:31]
	v_mfma_f32_32x32x16_bf16 v[32:47], v[84:87], v[76:79], v[32:47]
	v_mfma_f32_32x32x16_bf16 v[48:63], v[88:91], v[76:79], v[48:63]
	ds_read_b128 v[76:79], v128 offset:4608
	v_mfma_f32_32x32x16_bf16 v[0:15], v[88:91], v[80:83], v[0:15]
	ds_read_b128 v[88:91], v131 offset:36896
	v_mfma_f32_32x32x16_bf16 v[16:31], v[84:87], v[80:83], v[16:31]
	ds_read_b128 v[80:83], v131 offset:41472
	ds_read_b128 v[84:87], v131 offset:36864
	s_waitcnt lgkmcnt(1)
	v_mfma_f32_32x32x16_bf16 v[48:63], v[80:83], v[92:95], v[48:63]
	v_mfma_f32_32x32x16_bf16 v[0:15], v[80:83], v[76:79], v[0:15]
	ds_read_b128 v[80:83], v128 offset:4640
	s_waitcnt lgkmcnt(1)
	v_mfma_f32_32x32x16_bf16 v[32:47], v[84:87], v[92:95], v[32:47]
	ds_read_b128 v[92:95], v128 offset:4672
	v_mfma_f32_32x32x16_bf16 v[16:31], v[84:87], v[76:79], v[16:31]
	ds_read_b128 v[76:79], v131 offset:41504
	ds_read_b128 v[84:87], v128 offset:64
	s_waitcnt vmcnt(7)
	ds_write_b128 v130, v[64:67] offset:18432
	s_waitcnt vmcnt(6)
	ds_write_b128 v130, v[68:71] offset:23040
	s_waitcnt vmcnt(5)
	ds_write_b128 v130, v[72:75] offset:27648
	s_waitcnt vmcnt(4)
	ds_write_b128 v130, v[100:103] offset:32256
	ds_read_b128 v[64:67], v128 offset:96
	v_mfma_f32_32x32x16_bf16 v[32:47], v[88:91], v[96:99], v[32:47]
	ds_read_b128 v[68:71], v128 offset:4704
	ds_read_b128 v[72:75], v131 offset:36960
	s_waitcnt lgkmcnt(10)
	v_mfma_f32_32x32x16_bf16 v[16:31], v[88:91], v[80:83], v[16:31]
	s_waitcnt lgkmcnt(8)
	v_mfma_f32_32x32x16_bf16 v[48:63], v[76:79], v[96:99], v[48:63]
	v_mfma_f32_32x32x16_bf16 v[0:15], v[76:79], v[80:83], v[0:15]
	ds_read_b128 v[76:79], v131 offset:41568
	s_waitcnt vmcnt(3)
	ds_write_b128 v130, v[172:175] offset:55296
	s_waitcnt vmcnt(2)
	ds_write_b128 v130, v[176:179] offset:59904
	s_waitcnt vmcnt(1)
	ds_write_b128 v130, v[180:183] offset:64512
	s_waitcnt vmcnt(0)
	ds_write_b128 v129, v[168:171] offset:13824
	s_waitcnt lgkmcnt(0)
	s_barrier
	v_mfma_f32_32x32x16_bf16 v[32:47], v[104:107], v[84:87], v[32:47]
	ds_read_b128 v[96:99], v128 offset:18464
	ds_read_b128 v[100:103], v128 offset:23072
	ds_read_b128 v[80:83], v131 offset:55360
	ds_read_b128 v[88:91], v131 offset:55392
	v_mfma_f32_32x32x16_bf16 v[16:31], v[104:107], v[92:95], v[16:31]
	ds_read_b128 v[104:107], v131 offset:55328
	v_mfma_f32_32x32x16_bf16 v[48:63], v[108:111], v[84:87], v[48:63]
	ds_read_b128 v[84:87], v131 offset:59968
	v_mfma_f32_32x32x16_bf16 v[0:15], v[108:111], v[92:95], v[0:15]
	ds_read_b128 v[108:111], v131 offset:59936
	ds_read_b128 v[92:95], v131 offset:60000
	v_mfma_f32_32x32x16_bf16 v[32:47], v[72:75], v[64:67], v[32:47]
	v_mfma_f32_32x32x16_bf16 v[16:31], v[72:75], v[68:71], v[16:31]
	ds_read_b128 v[72:75], v128 offset:18432
	v_mfma_f32_32x32x16_bf16 v[48:63], v[76:79], v[64:67], v[48:63]
	ds_read_b128 v[64:67], v128 offset:23040
	v_mfma_f32_32x32x16_bf16 v[0:15], v[76:79], v[68:71], v[0:15]
	ds_read_b128 v[76:79], v131 offset:55296
	ds_read_b128 v[68:71], v131 offset:59904
	s_waitcnt lgkmcnt(1)
	v_mfma_f32_32x32x16_bf16 v[32:47], v[76:79], v[72:75], v[32:47]
	s_waitcnt lgkmcnt(0)
	v_mfma_f32_32x32x16_bf16 v[48:63], v[68:71], v[72:75], v[48:63]
	ds_read_b128 v[72:75], v128 offset:18496
	v_mfma_f32_32x32x16_bf16 v[16:31], v[76:79], v[64:67], v[16:31]
	ds_read_b128 v[76:79], v128 offset:18528
	v_mfma_f32_32x32x16_bf16 v[0:15], v[68:71], v[64:67], v[0:15]
	ds_read_b128 v[64:67], v128 offset:23104
	ds_read_b128 v[68:71], v128 offset:23136
	s_waitcnt lgkmcnt(0)
	s_barrier
	v_mfma_f32_32x32x16_bf16 v[32:47], v[104:107], v[96:99], v[32:47]
	v_mfma_f32_32x32x16_bf16 v[16:31], v[104:107], v[100:103], v[16:31]
	v_mfma_f32_32x32x16_bf16 v[0:15], v[108:111], v[100:103], v[0:15]
	v_mfma_f32_32x32x16_bf16 v[32:47], v[80:83], v[72:75], v[32:47]
	v_mfma_f32_32x32x16_bf16 v[16:31], v[80:83], v[64:67], v[16:31]
	v_mfma_f32_32x32x16_bf16 v[0:15], v[84:87], v[64:67], v[0:15]
	v_mfma_f32_32x32x16_bf16 v[32:47], v[88:91], v[76:79], v[32:47]
	v_mfma_f32_32x32x16_bf16 v[48:63], v[108:111], v[96:99], v[48:63]
	v_mfma_f32_32x32x16_bf16 v[16:31], v[88:91], v[68:71], v[16:31]
	v_mfma_f32_32x32x16_bf16 v[0:15], v[92:95], v[68:71], v[0:15]
	v_mfma_f32_32x32x16_bf16 v[48:63], v[84:87], v[72:75], v[48:63]
	v_mfma_f32_32x32x16_bf16 v[48:63], v[92:95], v[76:79], v[48:63]
	v_and_b32_e32 v64, 63, v186
	v_lshrrev_b32_e32 v65, 6, v186
	v_and_b32_e32 v66, 31, v64
	v_lshrrev_b32_e32 v67, 5, v64
	v_lshrrev_b32_e32 v68, 1, v65
	v_and_b32_e32 v65, 1, v65
	v_lshl_add_u32 v66, v68, 6, v66
	v_mul_u32_u24_e32 v66, 0x1600, v66
	v_lshl_add_u32 v66, v65, 6, v66
	v_lshl_add_u32 v66, v67, 3, v66
	v_add_u32_e32 v67, 0x2c000, v66
	s_mul_i32 s8, s6, 0x1600
	s_lshl_b32 s9, s4, 7
	s_add_i32 s8, s8, s9
	s_add_u32 s10, s0, s8
	s_addc_u32 s11, s1, 0
	s_nop 7
	s_nop 3
	s_waitcnt vmcnt(0)
	v_add_f32_e32 v222, v222, v223
	v_add_f32_e32 v224, v224, v225
	v_add_f32_e32 v226, v226, v227
	v_add_f32_e32 v228, v228, v229
	v_add_f32_e32 v222, v222, v224
	v_add_f32_e32 v226, v226, v228
	v_add_f32_e32 v222, v222, v226
	v_fmamk_f32 v250, v222, 0x3a800000, v187
	v_add_f32_e32 v136, v136, v137
	v_add_f32_e32 v138, v138, v139
	v_add_f32_e32 v140, v140, v141
	v_add_f32_e32 v142, v142, v143
	v_add_f32_e32 v136, v136, v138
	v_add_f32_e32 v140, v140, v142
	v_add_f32_e32 v136, v136, v140
	v_fmamk_f32 v249, v136, 0x3a800000, v187
	v_rsq_f32_e32 v250, v250
	v_rsq_f32_e32 v249, v249
	s_nop 0
	v_mul_f32_e32 v32, v250, v32
	v_mul_f32_e32 v33, v250, v33
	v_mul_f32_e32 v34, v250, v34
	v_mul_f32_e32 v35, v250, v35
	v_mul_f32_e32 v48, v250, v48
	v_mul_f32_e32 v49, v250, v49
	v_mul_f32_e32 v50, v250, v50
	v_mul_f32_e32 v51, v250, v51
	v_mul_f32_e32 v70, 0xbfb8aa3b, v32
	v_mul_f32_e32 v71, 0xbfb8aa3b, v33
	v_mul_f32_e32 v72, 0xbfb8aa3b, v34
	v_mul_f32_e32 v73, 0xbfb8aa3b, v35
	v_exp_f32_e32 v70, v70
	v_exp_f32_e32 v71, v71
	v_exp_f32_e32 v72, v72
	v_exp_f32_e32 v73, v73
	v_add_f32_e32 v70, 1.0, v70
	v_add_f32_e32 v71, 1.0, v71
	v_add_f32_e32 v72, 1.0, v72
	v_add_f32_e32 v73, 1.0, v73
	v_rcp_f32_e32 v70, v70
	v_rcp_f32_e32 v71, v71
	v_rcp_f32_e32 v72, v72
	v_rcp_f32_e32 v73, v73
	v_mul_f32_e32 v70, v32, v70
	v_mul_f32_e32 v71, v33, v71
	v_mul_f32_e32 v72, v34, v72
	v_mul_f32_e32 v73, v35, v73
	v_mul_f32_e32 v70, v48, v70
	v_mul_f32_e32 v71, v49, v71
	v_mul_f32_e32 v72, v50, v72
	v_mul_f32_e32 v73, v51, v73
	v_cvt_pk_bf16_f32 v74, v70, v71
	v_cvt_pk_bf16_f32 v75, v72, v73
	global_store_dwordx2 v66, v[74:75], s[10:11]
	v_mul_f32_e32 v36, v250, v36
	v_mul_f32_e32 v37, v250, v37
	v_mul_f32_e32 v38, v250, v38
	v_mul_f32_e32 v39, v250, v39
	v_mul_f32_e32 v52, v250, v52
	v_mul_f32_e32 v53, v250, v53
	v_mul_f32_e32 v54, v250, v54
	v_mul_f32_e32 v55, v250, v55
	v_mul_f32_e32 v76, 0xbfb8aa3b, v36
	v_mul_f32_e32 v77, 0xbfb8aa3b, v37
	v_mul_f32_e32 v78, 0xbfb8aa3b, v38
	v_mul_f32_e32 v79, 0xbfb8aa3b, v39
	v_exp_f32_e32 v76, v76
	v_exp_f32_e32 v77, v77
	v_exp_f32_e32 v78, v78
	v_exp_f32_e32 v79, v79
	v_add_f32_e32 v76, 1.0, v76
	v_add_f32_e32 v77, 1.0, v77
	v_add_f32_e32 v78, 1.0, v78
	v_add_f32_e32 v79, 1.0, v79
	v_rcp_f32_e32 v76, v76
	v_rcp_f32_e32 v77, v77
	v_rcp_f32_e32 v78, v78
	v_rcp_f32_e32 v79, v79
	v_mul_f32_e32 v76, v36, v76
	v_mul_f32_e32 v77, v37, v77
	v_mul_f32_e32 v78, v38, v78
	v_mul_f32_e32 v79, v39, v79
	v_mul_f32_e32 v76, v52, v76
	v_mul_f32_e32 v77, v53, v77
	v_mul_f32_e32 v78, v54, v78
	v_mul_f32_e32 v79, v55, v79
	v_cvt_pk_bf16_f32 v80, v76, v77
	v_cvt_pk_bf16_f32 v81, v78, v79
	global_store_dwordx2 v66, v[80:81], s[10:11] offset:16
	v_mul_f32_e32 v40, v250, v40
	v_mul_f32_e32 v41, v250, v41
	v_mul_f32_e32 v42, v250, v42
	v_mul_f32_e32 v43, v250, v43
	v_mul_f32_e32 v56, v250, v56
	v_mul_f32_e32 v57, v250, v57
	v_mul_f32_e32 v58, v250, v58
	v_mul_f32_e32 v59, v250, v59
	v_mul_f32_e32 v82, 0xbfb8aa3b, v40
	v_mul_f32_e32 v83, 0xbfb8aa3b, v41
	v_mul_f32_e32 v84, 0xbfb8aa3b, v42
	v_mul_f32_e32 v85, 0xbfb8aa3b, v43
	v_exp_f32_e32 v82, v82
	v_exp_f32_e32 v83, v83
	v_exp_f32_e32 v84, v84
	v_exp_f32_e32 v85, v85
	v_add_f32_e32 v82, 1.0, v82
	v_add_f32_e32 v83, 1.0, v83
	v_add_f32_e32 v84, 1.0, v84
	v_add_f32_e32 v85, 1.0, v85
	v_rcp_f32_e32 v82, v82
	v_rcp_f32_e32 v83, v83
	v_rcp_f32_e32 v84, v84
	v_rcp_f32_e32 v85, v85
	v_mul_f32_e32 v82, v40, v82
	v_mul_f32_e32 v83, v41, v83
	v_mul_f32_e32 v84, v42, v84
	v_mul_f32_e32 v85, v43, v85
	v_mul_f32_e32 v82, v56, v82
	v_mul_f32_e32 v83, v57, v83
	v_mul_f32_e32 v84, v58, v84
	v_mul_f32_e32 v85, v59, v85
	v_cvt_pk_bf16_f32 v86, v82, v83
	v_cvt_pk_bf16_f32 v87, v84, v85
	global_store_dwordx2 v66, v[86:87], s[10:11] offset:32
	v_mul_f32_e32 v44, v250, v44
	v_mul_f32_e32 v45, v250, v45
	v_mul_f32_e32 v46, v250, v46
	v_mul_f32_e32 v47, v250, v47
	v_mul_f32_e32 v60, v250, v60
	v_mul_f32_e32 v61, v250, v61
	v_mul_f32_e32 v62, v250, v62
	v_mul_f32_e32 v63, v250, v63
	v_mul_f32_e32 v70, 0xbfb8aa3b, v44
	v_mul_f32_e32 v71, 0xbfb8aa3b, v45
	v_mul_f32_e32 v72, 0xbfb8aa3b, v46
	v_mul_f32_e32 v73, 0xbfb8aa3b, v47
	v_exp_f32_e32 v70, v70
	v_exp_f32_e32 v71, v71
	v_exp_f32_e32 v72, v72
	v_exp_f32_e32 v73, v73
	v_add_f32_e32 v70, 1.0, v70
	v_add_f32_e32 v71, 1.0, v71
	v_add_f32_e32 v72, 1.0, v72
	v_add_f32_e32 v73, 1.0, v73
	v_rcp_f32_e32 v70, v70
	v_rcp_f32_e32 v71, v71
	v_rcp_f32_e32 v72, v72
	v_rcp_f32_e32 v73, v73
	v_mul_f32_e32 v70, v44, v70
	v_mul_f32_e32 v71, v45, v71
	v_mul_f32_e32 v72, v46, v72
	v_mul_f32_e32 v73, v47, v73
	v_mul_f32_e32 v70, v60, v70
	v_mul_f32_e32 v71, v61, v71
	v_mul_f32_e32 v72, v62, v72
	v_mul_f32_e32 v73, v63, v73
	v_cvt_pk_bf16_f32 v74, v70, v71
	v_cvt_pk_bf16_f32 v75, v72, v73
	global_store_dwordx2 v66, v[74:75], s[10:11] offset:48
	v_mul_f32_e32 v16, v249, v16
	v_mul_f32_e32 v17, v249, v17
	v_mul_f32_e32 v18, v249, v18
	v_mul_f32_e32 v19, v249, v19
	v_mul_f32_e32 v0, v249, v0
	v_mul_f32_e32 v1, v249, v1
	v_mul_f32_e32 v2, v249, v2
	v_mul_f32_e32 v3, v249, v3
	v_mul_f32_e32 v76, 0xbfb8aa3b, v16
	v_mul_f32_e32 v77, 0xbfb8aa3b, v17
	v_mul_f32_e32 v78, 0xbfb8aa3b, v18
	v_mul_f32_e32 v79, 0xbfb8aa3b, v19
	v_exp_f32_e32 v76, v76
	v_exp_f32_e32 v77, v77
	v_exp_f32_e32 v78, v78
	v_exp_f32_e32 v79, v79
	v_add_f32_e32 v76, 1.0, v76
	v_add_f32_e32 v77, 1.0, v77
	v_add_f32_e32 v78, 1.0, v78
	v_add_f32_e32 v79, 1.0, v79
	v_rcp_f32_e32 v76, v76
	v_rcp_f32_e32 v77, v77
	v_rcp_f32_e32 v78, v78
	v_rcp_f32_e32 v79, v79
	v_mul_f32_e32 v76, v16, v76
	v_mul_f32_e32 v77, v17, v77
	v_mul_f32_e32 v78, v18, v78
	v_mul_f32_e32 v79, v19, v79
	v_mul_f32_e32 v76, v0, v76
	v_mul_f32_e32 v77, v1, v77
	v_mul_f32_e32 v78, v2, v78
	v_mul_f32_e32 v79, v3, v79
	v_cvt_pk_bf16_f32 v80, v76, v77
	v_cvt_pk_bf16_f32 v81, v78, v79
	global_store_dwordx2 v67, v[80:81], s[10:11]
	v_mul_f32_e32 v20, v249, v20
	v_mul_f32_e32 v21, v249, v21
	v_mul_f32_e32 v22, v249, v22
	v_mul_f32_e32 v23, v249, v23
	v_mul_f32_e32 v4, v249, v4
	v_mul_f32_e32 v5, v249, v5
	v_mul_f32_e32 v6, v249, v6
	v_mul_f32_e32 v7, v249, v7
	v_mul_f32_e32 v82, 0xbfb8aa3b, v20
	v_mul_f32_e32 v83, 0xbfb8aa3b, v21
	v_mul_f32_e32 v84, 0xbfb8aa3b, v22
	v_mul_f32_e32 v85, 0xbfb8aa3b, v23
	v_exp_f32_e32 v82, v82
	v_exp_f32_e32 v83, v83
	v_exp_f32_e32 v84, v84
	v_exp_f32_e32 v85, v85
	v_add_f32_e32 v82, 1.0, v82
	v_add_f32_e32 v83, 1.0, v83
	v_add_f32_e32 v84, 1.0, v84
	v_add_f32_e32 v85, 1.0, v85
	v_rcp_f32_e32 v82, v82
	v_rcp_f32_e32 v83, v83
	v_rcp_f32_e32 v84, v84
	v_rcp_f32_e32 v85, v85
	v_mul_f32_e32 v82, v20, v82
	v_mul_f32_e32 v83, v21, v83
	v_mul_f32_e32 v84, v22, v84
	v_mul_f32_e32 v85, v23, v85
	v_mul_f32_e32 v82, v4, v82
	v_mul_f32_e32 v83, v5, v83
	v_mul_f32_e32 v84, v6, v84
	v_mul_f32_e32 v85, v7, v85
	v_cvt_pk_bf16_f32 v86, v82, v83
	v_cvt_pk_bf16_f32 v87, v84, v85
	global_store_dwordx2 v67, v[86:87], s[10:11] offset:16
	v_mul_f32_e32 v24, v249, v24
	v_mul_f32_e32 v25, v249, v25
	v_mul_f32_e32 v26, v249, v26
	v_mul_f32_e32 v27, v249, v27
	v_mul_f32_e32 v8, v249, v8
	v_mul_f32_e32 v9, v249, v9
	v_mul_f32_e32 v10, v249, v10
	v_mul_f32_e32 v11, v249, v11
	v_mul_f32_e32 v70, 0xbfb8aa3b, v24
	v_mul_f32_e32 v71, 0xbfb8aa3b, v25
	v_mul_f32_e32 v72, 0xbfb8aa3b, v26
	v_mul_f32_e32 v73, 0xbfb8aa3b, v27
	v_exp_f32_e32 v70, v70
	v_exp_f32_e32 v71, v71
	v_exp_f32_e32 v72, v72
	v_exp_f32_e32 v73, v73
	v_add_f32_e32 v70, 1.0, v70
	v_add_f32_e32 v71, 1.0, v71
	v_add_f32_e32 v72, 1.0, v72
	v_add_f32_e32 v73, 1.0, v73
	v_rcp_f32_e32 v70, v70
	v_rcp_f32_e32 v71, v71
	v_rcp_f32_e32 v72, v72
	v_rcp_f32_e32 v73, v73
	v_mul_f32_e32 v70, v24, v70
	v_mul_f32_e32 v71, v25, v71
	v_mul_f32_e32 v72, v26, v72
	v_mul_f32_e32 v73, v27, v73
	v_mul_f32_e32 v70, v8, v70
	v_mul_f32_e32 v71, v9, v71
	v_mul_f32_e32 v72, v10, v72
	v_mul_f32_e32 v73, v11, v73
	v_cvt_pk_bf16_f32 v74, v70, v71
	v_cvt_pk_bf16_f32 v75, v72, v73
	global_store_dwordx2 v67, v[74:75], s[10:11] offset:32
	v_mul_f32_e32 v28, v249, v28
	v_mul_f32_e32 v29, v249, v29
	v_mul_f32_e32 v30, v249, v30
	v_mul_f32_e32 v31, v249, v31
	v_mul_f32_e32 v12, v249, v12
	v_mul_f32_e32 v13, v249, v13
	v_mul_f32_e32 v14, v249, v14
	v_mul_f32_e32 v15, v249, v15
	v_mul_f32_e32 v76, 0xbfb8aa3b, v28
	v_mul_f32_e32 v77, 0xbfb8aa3b, v29
	v_mul_f32_e32 v78, 0xbfb8aa3b, v30
	v_mul_f32_e32 v79, 0xbfb8aa3b, v31
	v_exp_f32_e32 v76, v76
	v_exp_f32_e32 v77, v77
	v_exp_f32_e32 v78, v78
	v_exp_f32_e32 v79, v79
	v_add_f32_e32 v76, 1.0, v76
	v_add_f32_e32 v77, 1.0, v77
	v_add_f32_e32 v78, 1.0, v78
	v_add_f32_e32 v79, 1.0, v79
	v_rcp_f32_e32 v76, v76
	v_rcp_f32_e32 v77, v77
	v_rcp_f32_e32 v78, v78
	v_rcp_f32_e32 v79, v79
	v_mul_f32_e32 v76, v28, v76
	v_mul_f32_e32 v77, v29, v77
	v_mul_f32_e32 v78, v30, v78
	v_mul_f32_e32 v79, v31, v79
	v_mul_f32_e32 v76, v12, v76
	v_mul_f32_e32 v77, v13, v77
	v_mul_f32_e32 v78, v14, v78
	v_mul_f32_e32 v79, v15, v79
	v_cvt_pk_bf16_f32 v80, v76, v77
	v_cvt_pk_bf16_f32 v81, v78, v79
	global_store_dwordx2 v67, v[80:81], s[10:11] offset:48
	v_readlane_b32 s4, v252, 22
	s_add_i32 s16, s16, s4
	s_cmp_ge_i32 s16, s23
	s_cbranch_scc1 .LBB0_2270

.LBB0_2324:
	s_barrier
	v_readfirstlane_b32 s20, v186
	v_and_b32_e32 v64, 31, v186
	v_bfe_u32 v67, v186, 5, 1
	s_lshr_b32 s20, s20, 6
	s_and_b32 s21, s20, 1
	s_lshr_b32 s28, s20, 1
	s_lshl_b32 s28, s28, 6
	v_add_u32_e32 v66, s28, v64
	v_mul_u32_u24_e32 v188, 0x210, v66
	v_lshl_add_u32 v188, v67, 4, v188
	s_lshl_b32 s28, s21, 8
	v_add_u32_e32 v188, s28, v188
	s_lshl_b32 s28, s20, 5
	v_add_u32_e32 v65, s28, v67
	v_mul_u32_u24_e32 v189, 0x210, v65
	v_lshl_add_u32 v189, v64, 4, v189
	v_lshlrev_b32_e32 v192, 12, v65
	v_lshl_add_u32 v192, v64, 4, v192
	v_lshlrev_b32_e32 v195, 11, v65
	v_lshl_add_u32 v195, v64, 3, v195
	v_lshlrev_b32_e32 v197, 4, v64
	v_and_b32_e32 v66, 15, v186
	v_lshl_add_u32 v66, v66, 1, v67
	v_add_u32_e32 v66, s28, v66
	v_lshlrev_b32_e32 v66, 5, v66
	s_lshl_b32 s20, s17, 12
	s_lshl_b32 s30, s2, 2
	s_add_u32 s20, s20, s30
	s_add_u32 s22, s86, s20
	s_addc_u32 s23, s87, 0
	s_add_u32 s24, s86, s20
	s_addc_u32 s25, s87, 0
	v_readlane_b32 s52, v254, 34
	v_readlane_b32 s53, v254, 35
	v_readlane_b32 s68, v251, 2
	v_readlane_b32 s69, v251, 3
	s_lshl_b64 s[52:53], s[52:53], 2
	s_add_u32 s68, s68, s52
	s_addc_u32 s69, s69, s53
	s_add_u32 s68, s68, s30
	s_addc_u32 s69, s69, 0
	s_lshl_b32 s26, s17, 11
	s_lshl_b32 s27, s2, 1
	s_add_u32 s26, s26, s27
	s_add_u32 s26, s26, 0x2800000
	s_add_u32 s70, s88, s26
	s_addc_u32 s71, s89, 0
	s_lshl_b32 s26, s17, 5
	s_lshr_b32 s27, s2, 5
	s_add_u32 s26, s26, s27
	s_add_u32 s26, s26, 0xed00000
	s_add_u32 s72, s88, s26
	s_addc_u32 s73, s89, 0
	global_load_dwordx4 v[210:213], v197, s[68:69]
	global_load_dwordx4 v[68:71], v192, s[22:23]
	s_add_u32 s22, s22, 0x2000
	s_addc_u32 s23, s23, 0
	global_load_dwordx4 v[72:75], v192, s[22:23]
	s_add_u32 s22, s22, 0x2000
	s_addc_u32 s23, s23, 0
	global_load_dwordx4 v[76:79], v192, s[22:23]
	s_add_u32 s22, s22, 0x2000
	s_addc_u32 s23, s23, 0
	global_load_dwordx4 v[80:83], v192, s[22:23]
	s_add_u32 s22, s22, 0x2000
	s_addc_u32 s23, s23, 0
	global_load_dwordx4 v[84:87], v192, s[22:23]
	s_add_u32 s22, s22, 0x2000
	s_addc_u32 s23, s23, 0
	global_load_dwordx4 v[88:91], v192, s[22:23]
	s_add_u32 s22, s22, 0x2000
	s_addc_u32 s23, s23, 0
	global_load_dwordx4 v[92:95], v192, s[22:23]
	s_add_u32 s22, s22, 0x2000
	s_addc_u32 s23, s23, 0
	global_load_dwordx4 v[96:99], v192, s[22:23]
	s_add_u32 s22, s22, 0x2000
	s_addc_u32 s23, s23, 0
	global_load_dwordx4 v[100:103], v192, s[22:23]
	s_add_u32 s22, s22, 0x2000
	s_addc_u32 s23, s23, 0
	global_load_dwordx4 v[104:107], v192, s[22:23]
	s_add_u32 s22, s22, 0x2000
	s_addc_u32 s23, s23, 0
	global_load_dwordx4 v[108:111], v192, s[22:23]
	s_add_u32 s22, s22, 0x2000
	s_addc_u32 s23, s23, 0
	global_load_dwordx4 v[112:115], v192, s[22:23]
	s_add_u32 s22, s22, 0x2000
	s_addc_u32 s23, s23, 0
	global_load_dwordx4 v[116:119], v192, s[22:23]
	s_add_u32 s22, s22, 0x2000
	s_addc_u32 s23, s23, 0
	global_load_dwordx4 v[120:123], v192, s[22:23]
	s_add_u32 s22, s22, 0x2000
	s_addc_u32 s23, s23, 0
	global_load_dwordx4 v[124:127], v192, s[22:23]
	s_add_u32 s22, s22, 0x2000
	s_addc_u32 s23, s23, 0
	global_load_dwordx4 v[128:131], v192, s[22:23]
	ds_write_b128 v188, v[48:51]
	ds_write_b128 v188, v[52:55] offset:32
	ds_write_b128 v188, v[56:59] offset:64
	ds_write_b128 v188, v[60:63] offset:96
	ds_write_b128 v188, v[32:35] offset:128
	ds_write_b128 v188, v[36:39] offset:160
	ds_write_b128 v188, v[40:43] offset:192
	ds_write_b128 v188, v[44:47] offset:224
	ds_write_b128 v188, v[16:19] offset:16896
	ds_write_b128 v188, v[20:23] offset:16928
	ds_write_b128 v188, v[24:27] offset:16960
	ds_write_b128 v188, v[28:31] offset:16992
	ds_write_b128 v188, v[0:3] offset:17024
	ds_write_b128 v188, v[4:7] offset:17056
	ds_write_b128 v188, v[8:11] offset:17088
	ds_write_b128 v188, v[12:15] offset:17120
	s_waitcnt lgkmcnt(0)
	s_barrier
	ds_read_b128 v[0:3], v189
	ds_read_b128 v[4:7], v189 offset:1056
	ds_read_b128 v[8:11], v189 offset:2112
	ds_read_b128 v[12:15], v189 offset:3168
	ds_read_b128 v[16:19], v189 offset:4224
	ds_read_b128 v[20:23], v189 offset:5280
	ds_read_b128 v[24:27], v189 offset:6336
	ds_read_b128 v[28:31], v189 offset:7392
	ds_read_b128 v[32:35], v189 offset:8448
	ds_read_b128 v[36:39], v189 offset:9504
	ds_read_b128 v[40:43], v189 offset:10560
	ds_read_b128 v[44:47], v189 offset:11616
	ds_read_b128 v[48:51], v189 offset:12672
	ds_read_b128 v[52:55], v189 offset:13728
	ds_read_b128 v[56:59], v189 offset:14784
	ds_read_b128 v[60:63], v189 offset:15840
	s_waitcnt lgkmcnt(15)
	s_waitcnt vmcnt(15)
	v_add_f32_e32 v68, v68, v0
	v_add_f32_e32 v69, v69, v1
	v_add_f32_e32 v70, v70, v2
	v_add_f32_e32 v71, v71, v3
	global_store_dwordx4 v192, v[68:71], s[24:25]
	s_add_u32 s24, s24, 0x2000
	s_addc_u32 s25, s25, 0
	v_mul_f32_e32 v132, v68, v68
	v_fmac_f32_e32 v132, v69, v69
	v_fmac_f32_e32 v132, v70, v70
	v_fmac_f32_e32 v132, v71, v71
	v_mul_f32_e32 v198, v68, v210
	v_mul_f32_e32 v199, v69, v211
	v_mul_f32_e32 v200, v70, v212
	v_mul_f32_e32 v201, v71, v213
	v_cvt_pk_bf16_f32 v202, v198, v199
	v_cvt_pk_bf16_f32 v203, v200, v201
	global_store_dwordx2 v195, v[202:203], s[70:71]
	s_add_u32 s70, s70, 0x1000
	s_addc_u32 s71, s71, 0
	s_waitcnt lgkmcnt(14)
	s_waitcnt vmcnt(16)
	v_add_f32_e32 v72, v72, v4
	v_add_f32_e32 v73, v73, v5
	v_add_f32_e32 v74, v74, v6
	v_add_f32_e32 v75, v75, v7
	global_store_dwordx4 v192, v[72:75], s[24:25]
	s_add_u32 s24, s24, 0x2000
	s_addc_u32 s25, s25, 0
	v_mul_f32_e32 v133, v72, v72
	v_fmac_f32_e32 v133, v73, v73
	v_fmac_f32_e32 v133, v74, v74
	v_fmac_f32_e32 v133, v75, v75
	v_mul_f32_e32 v148, v72, v210
	v_mul_f32_e32 v149, v73, v211
	v_mul_f32_e32 v150, v74, v212
	v_mul_f32_e32 v151, v75, v213
	v_cvt_pk_bf16_f32 v152, v148, v149
	v_cvt_pk_bf16_f32 v153, v150, v151
	global_store_dwordx2 v195, v[152:153], s[70:71]
	s_add_u32 s70, s70, 0x1000
	s_addc_u32 s71, s71, 0
	s_waitcnt lgkmcnt(13)
	s_waitcnt vmcnt(17)
	v_add_f32_e32 v76, v76, v8
	v_add_f32_e32 v77, v77, v9
	v_add_f32_e32 v78, v78, v10
	v_add_f32_e32 v79, v79, v11
	global_store_dwordx4 v192, v[76:79], s[24:25]
	s_add_u32 s24, s24, 0x2000
	s_addc_u32 s25, s25, 0
	v_mul_f32_e32 v134, v76, v76
	v_fmac_f32_e32 v134, v77, v77
	v_fmac_f32_e32 v134, v78, v78
	v_fmac_f32_e32 v134, v79, v79
	v_mul_f32_e32 v198, v76, v210
	v_mul_f32_e32 v199, v77, v211
	v_mul_f32_e32 v200, v78, v212
	v_mul_f32_e32 v201, v79, v213
	v_cvt_pk_bf16_f32 v202, v198, v199
	v_cvt_pk_bf16_f32 v203, v200, v201
	global_store_dwordx2 v195, v[202:203], s[70:71]
	s_add_u32 s70, s70, 0x1000
	s_addc_u32 s71, s71, 0
	s_waitcnt lgkmcnt(12)
	s_waitcnt vmcnt(18)
	v_add_f32_e32 v80, v80, v12
	v_add_f32_e32 v81, v81, v13
	v_add_f32_e32 v82, v82, v14
	v_add_f32_e32 v83, v83, v15
	global_store_dwordx4 v192, v[80:83], s[24:25]
	s_add_u32 s24, s24, 0x2000
	s_addc_u32 s25, s25, 0
	v_mul_f32_e32 v135, v80, v80
	v_fmac_f32_e32 v135, v81, v81
	v_fmac_f32_e32 v135, v82, v82
	v_fmac_f32_e32 v135, v83, v83
	v_mul_f32_e32 v148, v80, v210
	v_mul_f32_e32 v149, v81, v211
	v_mul_f32_e32 v150, v82, v212
	v_mul_f32_e32 v151, v83, v213
	v_cvt_pk_bf16_f32 v152, v148, v149
	v_cvt_pk_bf16_f32 v153, v150, v151
	global_store_dwordx2 v195, v[152:153], s[70:71]
	s_add_u32 s70, s70, 0x1000
	s_addc_u32 s71, s71, 0
	s_waitcnt lgkmcnt(11)
	s_waitcnt vmcnt(19)
	v_add_f32_e32 v84, v84, v16
	v_add_f32_e32 v85, v85, v17
	v_add_f32_e32 v86, v86, v18
	v_add_f32_e32 v87, v87, v19
	global_store_dwordx4 v192, v[84:87], s[24:25]
	s_add_u32 s24, s24, 0x2000
	s_addc_u32 s25, s25, 0
	v_mul_f32_e32 v136, v84, v84
	v_fmac_f32_e32 v136, v85, v85
	v_fmac_f32_e32 v136, v86, v86
	v_fmac_f32_e32 v136, v87, v87
	v_mul_f32_e32 v198, v84, v210
	v_mul_f32_e32 v199, v85, v211
	v_mul_f32_e32 v200, v86, v212
	v_mul_f32_e32 v201, v87, v213
	v_cvt_pk_bf16_f32 v202, v198, v199
	v_cvt_pk_bf16_f32 v203, v200, v201
	global_store_dwordx2 v195, v[202:203], s[70:71]
	s_add_u32 s70, s70, 0x1000
	s_addc_u32 s71, s71, 0
	s_waitcnt lgkmcnt(10)
	s_waitcnt vmcnt(20)
	v_add_f32_e32 v88, v88, v20
	v_add_f32_e32 v89, v89, v21
	v_add_f32_e32 v90, v90, v22
	v_add_f32_e32 v91, v91, v23
	global_store_dwordx4 v192, v[88:91], s[24:25]
	s_add_u32 s24, s24, 0x2000
	s_addc_u32 s25, s25, 0
	v_mul_f32_e32 v137, v88, v88
	v_fmac_f32_e32 v137, v89, v89
	v_fmac_f32_e32 v137, v90, v90
	v_fmac_f32_e32 v137, v91, v91
	v_mul_f32_e32 v148, v88, v210
	v_mul_f32_e32 v149, v89, v211
	v_mul_f32_e32 v150, v90, v212
	v_mul_f32_e32 v151, v91, v213
	v_cvt_pk_bf16_f32 v152, v148, v149
	v_cvt_pk_bf16_f32 v153, v150, v151
	global_store_dwordx2 v195, v[152:153], s[70:71]
	s_add_u32 s70, s70, 0x1000
	s_addc_u32 s71, s71, 0
	s_waitcnt lgkmcnt(9)
	s_waitcnt vmcnt(21)
	v_add_f32_e32 v92, v92, v24
	v_add_f32_e32 v93, v93, v25
	v_add_f32_e32 v94, v94, v26
	v_add_f32_e32 v95, v95, v27
	global_store_dwordx4 v192, v[92:95], s[24:25]
	s_add_u32 s24, s24, 0x2000
	s_addc_u32 s25, s25, 0
	v_mul_f32_e32 v138, v92, v92
	v_fmac_f32_e32 v138, v93, v93
	v_fmac_f32_e32 v138, v94, v94
	v_fmac_f32_e32 v138, v95, v95
	v_mul_f32_e32 v198, v92, v210
	v_mul_f32_e32 v199, v93, v211
	v_mul_f32_e32 v200, v94, v212
	v_mul_f32_e32 v201, v95, v213
	v_cvt_pk_bf16_f32 v202, v198, v199
	v_cvt_pk_bf16_f32 v203, v200, v201
	global_store_dwordx2 v195, v[202:203], s[70:71]
	s_add_u32 s70, s70, 0x1000
	s_addc_u32 s71, s71, 0
	s_waitcnt lgkmcnt(8)
	s_waitcnt vmcnt(22)
	v_add_f32_e32 v96, v96, v28
	v_add_f32_e32 v97, v97, v29
	v_add_f32_e32 v98, v98, v30
	v_add_f32_e32 v99, v99, v31
	global_store_dwordx4 v192, v[96:99], s[24:25]
	s_add_u32 s24, s24, 0x2000
	s_addc_u32 s25, s25, 0
	v_mul_f32_e32 v139, v96, v96
	v_fmac_f32_e32 v139, v97, v97
	v_fmac_f32_e32 v139, v98, v98
	v_fmac_f32_e32 v139, v99, v99
	v_mul_f32_e32 v148, v96, v210
	v_mul_f32_e32 v149, v97, v211
	v_mul_f32_e32 v150, v98, v212
	v_mul_f32_e32 v151, v99, v213
	v_cvt_pk_bf16_f32 v152, v148, v149
	v_cvt_pk_bf16_f32 v153, v150, v151
	global_store_dwordx2 v195, v[152:153], s[70:71]
	s_add_u32 s70, s70, 0x1000
	s_addc_u32 s71, s71, 0
	s_waitcnt lgkmcnt(7)
	s_waitcnt vmcnt(23)
	v_add_f32_e32 v100, v100, v32
	v_add_f32_e32 v101, v101, v33
	v_add_f32_e32 v102, v102, v34
	v_add_f32_e32 v103, v103, v35
	global_store_dwordx4 v192, v[100:103], s[24:25]
	s_add_u32 s24, s24, 0x2000
	s_addc_u32 s25, s25, 0
	v_mul_f32_e32 v140, v100, v100
	v_fmac_f32_e32 v140, v101, v101
	v_fmac_f32_e32 v140, v102, v102
	v_fmac_f32_e32 v140, v103, v103
	v_mul_f32_e32 v198, v100, v210
	v_mul_f32_e32 v199, v101, v211
	v_mul_f32_e32 v200, v102, v212
	v_mul_f32_e32 v201, v103, v213
	v_cvt_pk_bf16_f32 v202, v198, v199
	v_cvt_pk_bf16_f32 v203, v200, v201
	global_store_dwordx2 v195, v[202:203], s[70:71]
	s_add_u32 s70, s70, 0x1000
	s_addc_u32 s71, s71, 0
	s_waitcnt lgkmcnt(6)
	s_waitcnt vmcnt(24)
	v_add_f32_e32 v104, v104, v36
	v_add_f32_e32 v105, v105, v37
	v_add_f32_e32 v106, v106, v38
	v_add_f32_e32 v107, v107, v39
	global_store_dwordx4 v192, v[104:107], s[24:25]
	s_add_u32 s24, s24, 0x2000
	s_addc_u32 s25, s25, 0
	v_mul_f32_e32 v141, v104, v104
	v_fmac_f32_e32 v141, v105, v105
	v_fmac_f32_e32 v141, v106, v106
	v_fmac_f32_e32 v141, v107, v107
	v_mul_f32_e32 v148, v104, v210
	v_mul_f32_e32 v149, v105, v211
	v_mul_f32_e32 v150, v106, v212
	v_mul_f32_e32 v151, v107, v213
	v_cvt_pk_bf16_f32 v152, v148, v149
	v_cvt_pk_bf16_f32 v153, v150, v151
	global_store_dwordx2 v195, v[152:153], s[70:71]
	s_add_u32 s70, s70, 0x1000
	s_addc_u32 s71, s71, 0
	s_waitcnt lgkmcnt(5)
	s_waitcnt vmcnt(25)
	v_add_f32_e32 v108, v108, v40
	v_add_f32_e32 v109, v109, v41
	v_add_f32_e32 v110, v110, v42
	v_add_f32_e32 v111, v111, v43
	global_store_dwordx4 v192, v[108:111], s[24:25]
	s_add_u32 s24, s24, 0x2000
	s_addc_u32 s25, s25, 0
	v_mul_f32_e32 v142, v108, v108
	v_fmac_f32_e32 v142, v109, v109
	v_fmac_f32_e32 v142, v110, v110
	v_fmac_f32_e32 v142, v111, v111
	v_mul_f32_e32 v198, v108, v210
	v_mul_f32_e32 v199, v109, v211
	v_mul_f32_e32 v200, v110, v212
	v_mul_f32_e32 v201, v111, v213
	v_cvt_pk_bf16_f32 v202, v198, v199
	v_cvt_pk_bf16_f32 v203, v200, v201
	global_store_dwordx2 v195, v[202:203], s[70:71]
	s_add_u32 s70, s70, 0x1000
	s_addc_u32 s71, s71, 0
	s_waitcnt lgkmcnt(4)
	s_waitcnt vmcnt(26)
	v_add_f32_e32 v112, v112, v44
	v_add_f32_e32 v113, v113, v45
	v_add_f32_e32 v114, v114, v46
	v_add_f32_e32 v115, v115, v47
	global_store_dwordx4 v192, v[112:115], s[24:25]
	s_add_u32 s24, s24, 0x2000
	s_addc_u32 s25, s25, 0
	v_mul_f32_e32 v143, v112, v112
	v_fmac_f32_e32 v143, v113, v113
	v_fmac_f32_e32 v143, v114, v114
	v_fmac_f32_e32 v143, v115, v115
	v_mul_f32_e32 v148, v112, v210
	v_mul_f32_e32 v149, v113, v211
	v_mul_f32_e32 v150, v114, v212
	v_mul_f32_e32 v151, v115, v213
	v_cvt_pk_bf16_f32 v152, v148, v149
	v_cvt_pk_bf16_f32 v153, v150, v151
	global_store_dwordx2 v195, v[152:153], s[70:71]
	s_add_u32 s70, s70, 0x1000
	s_addc_u32 s71, s71, 0
	s_waitcnt lgkmcnt(3)
	s_waitcnt vmcnt(27)
	v_add_f32_e32 v116, v116, v48
	v_add_f32_e32 v117, v117, v49
	v_add_f32_e32 v118, v118, v50
	v_add_f32_e32 v119, v119, v51
	global_store_dwordx4 v192, v[116:119], s[24:25]
	s_add_u32 s24, s24, 0x2000
	s_addc_u32 s25, s25, 0
	v_mul_f32_e32 v144, v116, v116
	v_fmac_f32_e32 v144, v117, v117
	v_fmac_f32_e32 v144, v118, v118
	v_fmac_f32_e32 v144, v119, v119
	v_mul_f32_e32 v198, v116, v210
	v_mul_f32_e32 v199, v117, v211
	v_mul_f32_e32 v200, v118, v212
	v_mul_f32_e32 v201, v119, v213
	v_cvt_pk_bf16_f32 v202, v198, v199
	v_cvt_pk_bf16_f32 v203, v200, v201
	global_store_dwordx2 v195, v[202:203], s[70:71]
	s_add_u32 s70, s70, 0x1000
	s_addc_u32 s71, s71, 0
	s_waitcnt lgkmcnt(2)
	s_waitcnt vmcnt(28)
	v_add_f32_e32 v120, v120, v52
	v_add_f32_e32 v121, v121, v53
	v_add_f32_e32 v122, v122, v54
	v_add_f32_e32 v123, v123, v55
	global_store_dwordx4 v192, v[120:123], s[24:25]
	s_add_u32 s24, s24, 0x2000
	s_addc_u32 s25, s25, 0
	v_mul_f32_e32 v145, v120, v120
	v_fmac_f32_e32 v145, v121, v121
	v_fmac_f32_e32 v145, v122, v122
	v_fmac_f32_e32 v145, v123, v123
	v_mul_f32_e32 v148, v120, v210
	v_mul_f32_e32 v149, v121, v211
	v_mul_f32_e32 v150, v122, v212
	v_mul_f32_e32 v151, v123, v213
	v_cvt_pk_bf16_f32 v152, v148, v149
	v_cvt_pk_bf16_f32 v153, v150, v151
	global_store_dwordx2 v195, v[152:153], s[70:71]
	s_add_u32 s70, s70, 0x1000
	s_addc_u32 s71, s71, 0
	s_waitcnt lgkmcnt(1)
	s_waitcnt vmcnt(29)
	v_add_f32_e32 v124, v124, v56
	v_add_f32_e32 v125, v125, v57
	v_add_f32_e32 v126, v126, v58
	v_add_f32_e32 v127, v127, v59
	global_store_dwordx4 v192, v[124:127], s[24:25]
	s_add_u32 s24, s24, 0x2000
	s_addc_u32 s25, s25, 0
	v_mul_f32_e32 v146, v124, v124
	v_fmac_f32_e32 v146, v125, v125
	v_fmac_f32_e32 v146, v126, v126
	v_fmac_f32_e32 v146, v127, v127
	v_mul_f32_e32 v198, v124, v210
	v_mul_f32_e32 v199, v125, v211
	v_mul_f32_e32 v200, v126, v212
	v_mul_f32_e32 v201, v127, v213
	v_cvt_pk_bf16_f32 v202, v198, v199
	v_cvt_pk_bf16_f32 v203, v200, v201
	global_store_dwordx2 v195, v[202:203], s[70:71]
	s_add_u32 s70, s70, 0x1000
	s_addc_u32 s71, s71, 0
	s_waitcnt lgkmcnt(0)
	s_waitcnt vmcnt(30)
	v_add_f32_e32 v128, v128, v60
	v_add_f32_e32 v129, v129, v61
	v_add_f32_e32 v130, v130, v62
	v_add_f32_e32 v131, v131, v63
	global_store_dwordx4 v192, v[128:131], s[24:25]
	v_mul_f32_e32 v147, v128, v128
	v_fmac_f32_e32 v147, v129, v129
	v_fmac_f32_e32 v147, v130, v130
	v_fmac_f32_e32 v147, v131, v131
	v_mul_f32_e32 v148, v128, v210
	v_mul_f32_e32 v149, v129, v211
	v_mul_f32_e32 v150, v130, v212
	v_mul_f32_e32 v151, v131, v213
	v_cvt_pk_bf16_f32 v152, v148, v149
	v_cvt_pk_bf16_f32 v153, v150, v151
	global_store_dwordx2 v195, v[152:153], s[70:71]
	v_add_f32_dpp v132, v132, v132 quad_perm:[1,0,3,2] row_mask:0xf bank_mask:0xf
	v_add_f32_dpp v133, v133, v133 quad_perm:[1,0,3,2] row_mask:0xf bank_mask:0xf
	v_add_f32_dpp v134, v134, v134 quad_perm:[1,0,3,2] row_mask:0xf bank_mask:0xf
	v_add_f32_dpp v135, v135, v135 quad_perm:[1,0,3,2] row_mask:0xf bank_mask:0xf
	v_add_f32_dpp v136, v136, v136 quad_perm:[1,0,3,2] row_mask:0xf bank_mask:0xf
	v_add_f32_dpp v137, v137, v137 quad_perm:[1,0,3,2] row_mask:0xf bank_mask:0xf
	v_add_f32_dpp v138, v138, v138 quad_perm:[1,0,3,2] row_mask:0xf bank_mask:0xf
	v_add_f32_dpp v139, v139, v139 quad_perm:[1,0,3,2] row_mask:0xf bank_mask:0xf
	v_add_f32_dpp v140, v140, v140 quad_perm:[1,0,3,2] row_mask:0xf bank_mask:0xf
	v_add_f32_dpp v141, v141, v141 quad_perm:[1,0,3,2] row_mask:0xf bank_mask:0xf
	v_add_f32_dpp v142, v142, v142 quad_perm:[1,0,3,2] row_mask:0xf bank_mask:0xf
	v_add_f32_dpp v143, v143, v143 quad_perm:[1,0,3,2] row_mask:0xf bank_mask:0xf
	v_add_f32_dpp v144, v144, v144 quad_perm:[1,0,3,2] row_mask:0xf bank_mask:0xf
	v_add_f32_dpp v145, v145, v145 quad_perm:[1,0,3,2] row_mask:0xf bank_mask:0xf
	v_add_f32_dpp v146, v146, v146 quad_perm:[1,0,3,2] row_mask:0xf bank_mask:0xf
	v_add_f32_dpp v147, v147, v147 quad_perm:[1,0,3,2] row_mask:0xf bank_mask:0xf
	v_add_f32_dpp v132, v132, v132 quad_perm:[2,3,0,1] row_mask:0xf bank_mask:0xf
	v_add_f32_dpp v133, v133, v133 quad_perm:[2,3,0,1] row_mask:0xf bank_mask:0xf
	v_add_f32_dpp v134, v134, v134 quad_perm:[2,3,0,1] row_mask:0xf bank_mask:0xf
	v_add_f32_dpp v135, v135, v135 quad_perm:[2,3,0,1] row_mask:0xf bank_mask:0xf
	v_add_f32_dpp v136, v136, v136 quad_perm:[2,3,0,1] row_mask:0xf bank_mask:0xf
	v_add_f32_dpp v137, v137, v137 quad_perm:[2,3,0,1] row_mask:0xf bank_mask:0xf
	v_add_f32_dpp v138, v138, v138 quad_perm:[2,3,0,1] row_mask:0xf bank_mask:0xf
	v_add_f32_dpp v139, v139, v139 quad_perm:[2,3,0,1] row_mask:0xf bank_mask:0xf
	v_add_f32_dpp v140, v140, v140 quad_perm:[2,3,0,1] row_mask:0xf bank_mask:0xf
	v_add_f32_dpp v141, v141, v141 quad_perm:[2,3,0,1] row_mask:0xf bank_mask:0xf
	v_add_f32_dpp v142, v142, v142 quad_perm:[2,3,0,1] row_mask:0xf bank_mask:0xf
	v_add_f32_dpp v143, v143, v143 quad_perm:[2,3,0,1] row_mask:0xf bank_mask:0xf
	v_add_f32_dpp v144, v144, v144 quad_perm:[2,3,0,1] row_mask:0xf bank_mask:0xf
	v_add_f32_dpp v145, v145, v145 quad_perm:[2,3,0,1] row_mask:0xf bank_mask:0xf
	v_add_f32_dpp v146, v146, v146 quad_perm:[2,3,0,1] row_mask:0xf bank_mask:0xf
	v_add_f32_dpp v147, v147, v147 quad_perm:[2,3,0,1] row_mask:0xf bank_mask:0xf
	v_add_f32_dpp v132, v132, v132 row_half_mirror row_mask:0xf bank_mask:0xf
	v_add_f32_dpp v133, v133, v133 row_half_mirror row_mask:0xf bank_mask:0xf
	v_add_f32_dpp v134, v134, v134 row_half_mirror row_mask:0xf bank_mask:0xf
	v_add_f32_dpp v135, v135, v135 row_half_mirror row_mask:0xf bank_mask:0xf
	v_add_f32_dpp v136, v136, v136 row_half_mirror row_mask:0xf bank_mask:0xf
	v_add_f32_dpp v137, v137, v137 row_half_mirror row_mask:0xf bank_mask:0xf
	v_add_f32_dpp v138, v138, v138 row_half_mirror row_mask:0xf bank_mask:0xf
	v_add_f32_dpp v139, v139, v139 row_half_mirror row_mask:0xf bank_mask:0xf
	v_add_f32_dpp v140, v140, v140 row_half_mirror row_mask:0xf bank_mask:0xf
	v_add_f32_dpp v141, v141, v141 row_half_mirror row_mask:0xf bank_mask:0xf
	v_add_f32_dpp v142, v142, v142 row_half_mirror row_mask:0xf bank_mask:0xf
	v_add_f32_dpp v143, v143, v143 row_half_mirror row_mask:0xf bank_mask:0xf
	v_add_f32_dpp v144, v144, v144 row_half_mirror row_mask:0xf bank_mask:0xf
	v_add_f32_dpp v145, v145, v145 row_half_mirror row_mask:0xf bank_mask:0xf
	v_add_f32_dpp v146, v146, v146 row_half_mirror row_mask:0xf bank_mask:0xf
	v_add_f32_dpp v147, v147, v147 row_half_mirror row_mask:0xf bank_mask:0xf
	v_add_f32_dpp v132, v132, v132 row_mirror row_mask:0xf bank_mask:0xf
	v_add_f32_dpp v133, v133, v133 row_mirror row_mask:0xf bank_mask:0xf
	v_add_f32_dpp v134, v134, v134 row_mirror row_mask:0xf bank_mask:0xf
	v_add_f32_dpp v135, v135, v135 row_mirror row_mask:0xf bank_mask:0xf
	v_add_f32_dpp v136, v136, v136 row_mirror row_mask:0xf bank_mask:0xf
	v_add_f32_dpp v137, v137, v137 row_mirror row_mask:0xf bank_mask:0xf
	v_add_f32_dpp v138, v138, v138 row_mirror row_mask:0xf bank_mask:0xf
	v_add_f32_dpp v139, v139, v139 row_mirror row_mask:0xf bank_mask:0xf
	v_add_f32_dpp v140, v140, v140 row_mirror row_mask:0xf bank_mask:0xf
	v_add_f32_dpp v141, v141, v141 row_mirror row_mask:0xf bank_mask:0xf
	v_add_f32_dpp v142, v142, v142 row_mirror row_mask:0xf bank_mask:0xf
	v_add_f32_dpp v143, v143, v143 row_mirror row_mask:0xf bank_mask:0xf
	v_add_f32_dpp v144, v144, v144 row_mirror row_mask:0xf bank_mask:0xf
	v_add_f32_dpp v145, v145, v145 row_mirror row_mask:0xf bank_mask:0xf
	v_add_f32_dpp v146, v146, v146 row_mirror row_mask:0xf bank_mask:0xf
	v_add_f32_dpp v147, v147, v147 row_mirror row_mask:0xf bank_mask:0xf
	v_mov_b32_e32 v164, v132
	v_mov_b32_e32 v165, v133
	v_mov_b32_e32 v166, v134
	v_mov_b32_e32 v167, v135
	v_mov_b32_e32 v168, v136
	v_mov_b32_e32 v169, v137
	v_mov_b32_e32 v170, v138
	v_mov_b32_e32 v171, v139
	v_mov_b32_e32 v172, v140
	v_mov_b32_e32 v173, v141
	v_mov_b32_e32 v174, v142
	v_mov_b32_e32 v175, v143
	v_mov_b32_e32 v176, v144
	v_mov_b32_e32 v177, v145
	v_mov_b32_e32 v178, v146
	v_mov_b32_e32 v179, v147
	v_permlane16_swap_b32_e32 v132, v164
	v_permlane16_swap_b32_e32 v133, v165
	v_permlane16_swap_b32_e32 v134, v166
	v_permlane16_swap_b32_e32 v135, v167
	v_permlane16_swap_b32_e32 v136, v168
	v_permlane16_swap_b32_e32 v137, v169
	v_permlane16_swap_b32_e32 v138, v170
	v_permlane16_swap_b32_e32 v139, v171
	v_permlane16_swap_b32_e32 v140, v172
	v_permlane16_swap_b32_e32 v141, v173
	v_permlane16_swap_b32_e32 v142, v174
	v_permlane16_swap_b32_e32 v143, v175
	v_permlane16_swap_b32_e32 v144, v176
	v_permlane16_swap_b32_e32 v145, v177
	v_permlane16_swap_b32_e32 v146, v178
	v_permlane16_swap_b32_e32 v147, v179
	v_add_f32_e32 v132, v132, v164
	v_add_f32_e32 v133, v133, v165
	v_add_f32_e32 v134, v134, v166
	v_add_f32_e32 v135, v135, v167
	v_add_f32_e32 v136, v136, v168
	v_add_f32_e32 v137, v137, v169
	v_add_f32_e32 v138, v138, v170
	v_add_f32_e32 v139, v139, v171
	v_add_f32_e32 v140, v140, v172
	v_add_f32_e32 v141, v141, v173
	v_add_f32_e32 v142, v142, v174
	v_add_f32_e32 v143, v143, v175
	v_add_f32_e32 v144, v144, v176
	v_add_f32_e32 v145, v145, v177
	v_add_f32_e32 v146, v146, v178
	v_add_f32_e32 v147, v147, v179
	v_mov_b32_e32 v196, v132
	s_mov_b32 s26, 0x2
	s_mov_b32 s27, 0x2
	s_nop 0
	v_cndmask_b32_e64 v196, v196, v133, s[26:27]
	s_mov_b32 s26, 0x4
	s_mov_b32 s27, 0x4
	s_nop 0
	v_cndmask_b32_e64 v196, v196, v134, s[26:27]
	s_mov_b32 s26, 0x8
	s_mov_b32 s27, 0x8
	s_nop 0
	v_cndmask_b32_e64 v196, v196, v135, s[26:27]
	s_mov_b32 s26, 0x10
	s_mov_b32 s27, 0x10
	s_nop 0
	v_cndmask_b32_e64 v196, v196, v136, s[26:27]
	s_mov_b32 s26, 0x20
	s_mov_b32 s27, 0x20
	s_nop 0
	v_cndmask_b32_e64 v196, v196, v137, s[26:27]
	s_mov_b32 s26, 0x40
	s_mov_b32 s27, 0x40
	s_nop 0
	v_cndmask_b32_e64 v196, v196, v138, s[26:27]
	s_mov_b32 s26, 0x80
	s_mov_b32 s27, 0x80
	s_nop 0
	v_cndmask_b32_e64 v196, v196, v139, s[26:27]
	s_mov_b32 s26, 0x100
	s_mov_b32 s27, 0x100
	s_nop 0
	v_cndmask_b32_e64 v196, v196, v140, s[26:27]
	s_mov_b32 s26, 0x200
	s_mov_b32 s27, 0x200
	s_nop 0
	v_cndmask_b32_e64 v196, v196, v141, s[26:27]
	s_mov_b32 s26, 0x400
	s_mov_b32 s27, 0x400
	s_nop 0
	v_cndmask_b32_e64 v196, v196, v142, s[26:27]
	s_mov_b32 s26, 0x800
	s_mov_b32 s27, 0x800
	s_nop 0
	v_cndmask_b32_e64 v196, v196, v143, s[26:27]
	s_mov_b32 s26, 0x1000
	s_mov_b32 s27, 0x1000
	s_nop 0
	v_cndmask_b32_e64 v196, v196, v144, s[26:27]
	s_mov_b32 s26, 0x2000
	s_mov_b32 s27, 0x2000
	s_nop 0
	v_cndmask_b32_e64 v196, v196, v145, s[26:27]
	s_mov_b32 s26, 0x4000
	s_mov_b32 s27, 0x4000
	s_nop 0
	v_cndmask_b32_e64 v196, v196, v146, s[26:27]
	s_mov_b32 s26, 0x8000
	s_mov_b32 s27, 0x8000
	s_nop 0
	v_cndmask_b32_e64 v196, v196, v147, s[26:27]
	s_mov_b32 exec_lo, 0xffff
	s_mov_b32 exec_hi, 0xffff
	global_store_dword v66, v196, s[72:73]
	s_mov_b64 exec, -1
	v_readlane_b32 s0, v252, 22
	s_nop 3
	s_add_i32 s16, s16, s0
	v_readlane_b32 s0, v252, 36
	s_nop 3
	s_cmp_ge_i32 s16, s0
	s_cbranch_scc1 .LBB0_2343

.LBB0_2395:
	s_or_b64 exec, exec, s[0:1]
	s_mov_b64 s[0:1], s[88:89]
	s_waitcnt lgkmcnt(0)
	v_mov_b32_e32 v0, v186
	s_mov_b32 s2, s90
	s_barrier
	s_nop 0
	v_readlane_b32 s2, v252, 42
	v_readlane_b32 s3, v252, 43
	s_andn2_b64 vcc, exec, s[2:3]
	s_cbranch_vccnz .LBB0_2461
	v_and_b32_e32 v248, 31, v186
	v_lshrrev_b32_e32 v247, 7, v186
	v_lshl_add_u32 v248, v247, 6, v248
	v_lshlrev_b32_e32 v248, 5, v248
	s_add_u32 s8, s0, 0x2800000
	s_addc_u32 s9, s1, 0
	s_add_u32 s10, s0, 0xe400000
	s_addc_u32 s11, s1, 0
	v_ashrrev_i32_e32 v1, 1, v0
	v_and_b32_e32 v2, 31, v0
	s_add_u32 s12, s0, 0x23c0000
	v_and_b32_e32 v86, 0xffffffc0, v1
	v_lshrrev_b32_e32 v1, 3, v0
	v_lshlrev_b32_e32 v0, 1, v0
	s_addc_u32 s13, s1, 0
	v_and_b32_e32 v160, 0x80, v0
	s_add_u32 s14, s0, 0x2440000
	v_and_b32_e32 v87, 4, v1
	v_lshl_add_u64 v[0:1], s[86:87], 0, v[160:161]
	v_lshlrev_b32_e32 v160, 2, v2
	s_addc_u32 s15, s1, 0
	v_lshl_add_u64 v[80:81], v[0:1], 0, v[160:161]
	v_or_b32_e32 v88, 1, v87
	v_or_b32_e32 v89, 2, v87
	v_or_b32_e32 v90, 3, v87
	v_or_b32_e32 v91, 8, v87
	v_or_b32_e32 v92, 9, v87
	v_or_b32_e32 v93, 10, v87
	v_or_b32_e32 v94, 11, v87
	v_or_b32_e32 v95, 16, v87
	v_or_b32_e32 v96, 17, v87
	v_or_b32_e32 v97, 18, v87
	v_or_b32_e32 v98, 19, v87
	v_or_b32_e32 v99, 24, v87
	v_or_b32_e32 v100, 25, v87
	v_or_b32_e32 v101, 26, v87
	v_or_b32_e32 v102, 27, v87
	v_or_b32_e32 v103, 32, v87
	v_or_b32_e32 v104, 33, v87
	v_or_b32_e32 v105, 34, v87
	v_or_b32_e32 v106, 35, v87
	v_or_b32_e32 v107, 40, v87
	v_or_b32_e32 v108, 41, v87
	v_or_b32_e32 v109, 42, v87
	v_or_b32_e32 v110, 43, v87
	v_or_b32_e32 v111, 48, v87
	v_or_b32_e32 v112, 49, v87
	v_or_b32_e32 v113, 50, v87
	v_or_b32_e32 v114, 51, v87
	v_or_b32_e32 v115, 56, v87
	v_or_b32_e32 v116, 57, v87
	v_or_b32_e32 v117, 58, v87
	v_or_b32_e32 v118, 59, v87
	v_readlane_b32 s16, v252, 41
	s_branch .LBB0_2454

.LBB0_2453:
	s_lshl_b32 s0, s4, 7
	s_ashr_i32 s1, s0, 31
	s_lshl_b32 s2, s2, 6
	s_lshl_b64 s[4:5], s[0:1], 9
	v_mov_b32_e32 v0, v161
	s_add_u32 s4, s10, s4
	v_mov_b32_e32 v1, v186
	s_addc_u32 s5, s11, s5
	s_ashr_i32 s3, s2, 31
	s_lshl_b64 s[6:7], s[2:3], 9
	v_lshlrev_b32_e32 v2, 4, v1
	s_waitcnt vmcnt(17)
	v_ashrrev_i32_e32 v27, 3, v1
	v_and_b32_e32 v26, 0x70, v2
	s_add_u32 s6, s12, s6
	v_lshl_or_b32 v119, v27, 9, v26
	s_addc_u32 s7, s13, s7
	v_add_u32_e32 v120, 0x4000, v119
	v_add_u32_e32 v121, 0x8000, v119
	v_add_u32_e32 v122, 0xc000, v119
	s_barrier
	s_lshl_b32 s72, s0, 5
	s_add_u32 s72, s72, 0xed00000
	s_add_u32 s72, s88, s72
	s_addc_u32 s73, s89, 0
	global_load_dwordx4 v[210:213], v248, s[72:73]
	global_load_dwordx4 v[214:217], v248, s[72:73] offset:16
	global_load_dwordx4 v[226:229], v248, s[72:73] offset:1024
	global_load_dwordx4 v[230:233], v248, s[72:73] offset:1040
	global_load_dwordx4 v[2:5], v119, s[4:5]
	global_load_dwordx4 v[6:9], v120, s[4:5]
	global_load_dwordx4 v[10:13], v121, s[4:5]
	global_load_dwordx4 v[14:17], v122, s[4:5]
	global_load_dwordx4 v[18:21], v119, s[6:7]
	global_load_dwordx4 v[22:25], v120, s[6:7]
	v_mad_u64_u32 v[84:85], s[18:19], v27, s43, v[26:27]
	s_waitcnt vmcnt(5)
	ds_write_b128 v84, v[2:5]
	s_waitcnt vmcnt(4)
	ds_write_b128 v84, v[6:9] offset:4608
	s_waitcnt vmcnt(3)
	ds_write_b128 v84, v[10:13] offset:9216
	s_waitcnt vmcnt(2)
	ds_write_b128 v84, v[14:17] offset:13824
	s_waitcnt vmcnt(1)
	ds_write_b128 v84, v[18:21] offset:36864
	s_waitcnt vmcnt(0)
	ds_write_b128 v84, v[22:25] offset:41472
	global_load_dwordx4 v[40:43], v119, s[4:5] offset:128
	global_load_dwordx4 v[44:47], v120, s[4:5] offset:128
	global_load_dwordx4 v[48:51], v121, s[4:5] offset:128
	global_load_dwordx4 v[52:55], v122, s[4:5] offset:128
	global_load_dwordx4 v[32:35], v119, s[6:7] offset:128
	global_load_dwordx4 v[36:39], v120, s[6:7] offset:128
	v_lshrrev_b32_e32 v3, 1, v1
	v_and_b32_e32 v1, 31, v1
	v_and_or_b32 v4, v3, 32, v1
	v_and_b32_e32 v2, 16, v3
	v_and_or_b32 v1, v3, s44, v1
	v_mad_u64_u32 v[82:83], s[18:19], v1, s43, v[2:3]
	s_waitcnt lgkmcnt(0)
	s_barrier
	ds_read_b128 v[56:59], v82 offset:4608
	ds_read_b128 v[60:63], v82
	v_mad_u32_u24 v85, v4, s43, v2
	ds_read_b128 v[124:127], v82 offset:32
	ds_read_b128 v[64:67], v85 offset:36864
	ds_read_b128 v[128:131], v82 offset:4640
	v_mov_b32_e32 v1, v0
	v_mov_b32_e32 v2, v0
	v_mov_b32_e32 v3, v0
	v_mov_b32_e32 v4, v0
	v_mov_b32_e32 v5, v0
	v_mov_b32_e32 v6, v0
	v_mov_b32_e32 v7, v0
	v_mov_b32_e32 v8, v0
	v_mov_b32_e32 v9, v0
	v_mov_b32_e32 v10, v0
	v_mov_b32_e32 v11, v0
	v_mov_b32_e32 v12, v0
	v_mov_b32_e32 v13, v0
	v_mov_b32_e32 v14, v0
	v_mov_b32_e32 v15, v0
	ds_read_b128 v[132:135], v85 offset:36896
	s_waitcnt lgkmcnt(2)
	v_mfma_f32_32x32x16_bf16 v[16:31], v[64:67], v[60:63], v[0:15]
	v_mfma_f32_32x32x16_bf16 v[0:15], v[64:67], v[56:59], v[0:15]
	s_waitcnt lgkmcnt(0)
	v_mfma_f32_32x32x16_bf16 v[16:31], v[132:135], v[124:127], v[16:31]
	v_mfma_f32_32x32x16_bf16 v[0:15], v[132:135], v[128:131], v[0:15]
	ds_read_b128 v[136:139], v82 offset:64
	ds_read_b128 v[140:143], v82 offset:4672
	ds_read_b128 v[144:147], v85 offset:36928
	s_waitcnt lgkmcnt(0)
	v_mfma_f32_32x32x16_bf16 v[16:31], v[144:147], v[136:139], v[16:31]
	v_mfma_f32_32x32x16_bf16 v[0:15], v[144:147], v[140:143], v[0:15]
	global_load_dwordx4 v[64:67], v119, s[4:5] offset:256
	global_load_dwordx4 v[68:71], v120, s[4:5] offset:256
	global_load_dwordx4 v[72:75], v121, s[4:5] offset:256
	global_load_dwordx4 v[76:79], v122, s[4:5] offset:256
	global_load_dwordx4 v[56:59], v119, s[6:7] offset:256
	global_load_dwordx4 v[60:63], v120, s[6:7] offset:256
	s_waitcnt vmcnt(11)
	ds_write_b128 v84, v[40:43] offset:18432
	s_waitcnt vmcnt(10)
	ds_write_b128 v84, v[44:47] offset:23040
	s_waitcnt vmcnt(9)
	ds_write_b128 v84, v[48:51] offset:27648
	s_waitcnt vmcnt(8)
	ds_write_b128 v84, v[52:55] offset:32256
	ds_read_b128 v[40:43], v82 offset:96
	ds_read_b128 v[44:47], v82 offset:4704
	ds_read_b128 v[48:51], v85 offset:36960
	s_waitcnt vmcnt(7)
	ds_write_b128 v84, v[32:35] offset:46080
	s_waitcnt vmcnt(6)
	ds_write_b128 v84, v[36:39] offset:50688
	s_waitcnt lgkmcnt(2)
	v_mfma_f32_32x32x16_bf16 v[16:31], v[48:51], v[40:43], v[16:31]
	s_waitcnt lgkmcnt(0)
	s_barrier
	v_mfma_f32_32x32x16_bf16 v[0:15], v[48:51], v[44:47], v[0:15]
	ds_read_b128 v[32:35], v82 offset:23040
	ds_read_b128 v[36:39], v82 offset:18432
	ds_read_b128 v[48:51], v85 offset:46080
	ds_read_b128 v[40:43], v82 offset:18464
	ds_read_b128 v[44:47], v82 offset:23072
	ds_read_b128 v[52:55], v85 offset:46112
	s_waitcnt lgkmcnt(3)
	v_mfma_f32_32x32x16_bf16 v[16:31], v[48:51], v[36:39], v[16:31]
	v_mfma_f32_32x32x16_bf16 v[0:15], v[48:51], v[32:35], v[0:15]
	global_load_dwordx4 v[32:35], v119, s[4:5] offset:384
	global_load_dwordx4 v[36:39], v120, s[4:5] offset:384
	global_load_dwordx4 v[48:51], v121, s[4:5] offset:384
	global_load_dwordx4 v[126:129], v119, s[6:7] offset:384
	global_load_dwordx4 v[130:133], v120, s[6:7] offset:384
	s_nop 0
	global_load_dwordx4 v[122:125], v122, s[4:5] offset:384
	ds_read_b128 v[134:137], v82 offset:18496
	ds_read_b128 v[138:141], v82 offset:23104
	ds_read_b128 v[142:145], v85 offset:46144
	s_lshl_b64 s[4:5], s[0:1], 11
	s_add_u32 s4, s8, s4
	s_addc_u32 s5, s9, s5
	s_lshl_b64 s[6:7], s[2:3], 11
	s_add_u32 s6, s14, s6
	s_addc_u32 s7, s15, s7
	s_waitcnt vmcnt(11)
	ds_write_b128 v84, v[64:67]
	s_waitcnt vmcnt(10)
	ds_write_b128 v84, v[68:71] offset:4608
	s_waitcnt vmcnt(9)
	ds_write_b128 v84, v[72:75] offset:9216
	s_waitcnt vmcnt(8)
	ds_write_b128 v84, v[76:79] offset:13824
	s_waitcnt lgkmcnt(7)
	v_mfma_f32_32x32x16_bf16 v[16:31], v[52:55], v[40:43], v[16:31]
	v_mfma_f32_32x32x16_bf16 v[0:15], v[52:55], v[44:47], v[0:15]
	ds_read_b128 v[40:43], v82 offset:18528
	ds_read_b128 v[44:47], v82 offset:23136
	ds_read_b128 v[52:55], v85 offset:46176
	s_waitcnt vmcnt(7)
	ds_write_b128 v84, v[56:59] offset:36864
	s_waitcnt vmcnt(6)
	ds_write_b128 v84, v[60:63] offset:41472
	s_waitcnt lgkmcnt(0)
	s_barrier
	v_mfma_f32_32x32x16_bf16 v[16:31], v[142:145], v[134:137], v[16:31]
	v_mfma_f32_32x32x16_bf16 v[0:15], v[142:145], v[138:141], v[0:15]
	v_mfma_f32_32x32x16_bf16 v[16:31], v[52:55], v[40:43], v[16:31]
	v_mfma_f32_32x32x16_bf16 v[0:15], v[52:55], v[44:47], v[0:15]
	ds_read_b128 v[40:43], v82 offset:4608
	ds_read_b128 v[56:59], v82
	ds_read_b128 v[44:47], v85 offset:36864
	ds_read_b128 v[52:55], v85 offset:36896
	ds_read_b128 v[60:63], v82 offset:32
	ds_read_b128 v[64:67], v85 offset:36928
	s_waitcnt lgkmcnt(3)
	v_mfma_f32_32x32x16_bf16 v[16:31], v[44:47], v[56:59], v[16:31]
	v_mfma_f32_32x32x16_bf16 v[0:15], v[44:47], v[40:43], v[0:15]
	ds_read_b128 v[40:43], v82 offset:4640
	ds_read_b128 v[44:47], v82 offset:64
	ds_read_b128 v[56:59], v82 offset:4672
	s_waitcnt vmcnt(5)
	ds_write_b128 v84, v[32:35] offset:18432
	s_waitcnt vmcnt(4)
	ds_write_b128 v84, v[36:39] offset:23040
	s_waitcnt vmcnt(3)
	ds_write_b128 v84, v[48:51] offset:27648
	s_waitcnt vmcnt(0)
	ds_write_b128 v84, v[122:125] offset:32256
	s_waitcnt lgkmcnt(8)
	v_mfma_f32_32x32x16_bf16 v[16:31], v[52:55], v[60:63], v[16:31]
	s_waitcnt lgkmcnt(6)
	v_mfma_f32_32x32x16_bf16 v[0:15], v[52:55], v[40:43], v[0:15]
	ds_read_b128 v[32:35], v82 offset:96
	ds_read_b128 v[36:39], v82 offset:4704
	ds_read_b128 v[40:43], v85 offset:36960
	ds_write_b128 v84, v[126:129] offset:46080
	ds_write_b128 v84, v[130:133] offset:50688
	s_waitcnt lgkmcnt(0)
	s_barrier
	v_mfma_f32_32x32x16_bf16 v[16:31], v[64:67], v[44:47], v[16:31]
	v_mfma_f32_32x32x16_bf16 v[0:15], v[64:67], v[56:59], v[0:15]
	v_mfma_f32_32x32x16_bf16 v[16:31], v[40:43], v[32:35], v[16:31]
	v_mfma_f32_32x32x16_bf16 v[0:15], v[40:43], v[36:39], v[0:15]
	ds_read_b128 v[32:35], v82 offset:23040
	ds_read_b128 v[36:39], v82 offset:18432
	ds_read_b128 v[48:51], v85 offset:46080
	ds_read_b128 v[44:47], v82 offset:23072
	ds_read_b128 v[40:43], v82 offset:18464
	ds_read_b128 v[52:55], v85 offset:46112
	s_waitcnt lgkmcnt(3)
	v_mfma_f32_32x32x16_bf16 v[0:15], v[48:51], v[32:35], v[0:15]
	v_mfma_f32_32x32x16_bf16 v[16:31], v[48:51], v[36:39], v[16:31]
	ds_read_b128 v[36:39], v82 offset:23104
	ds_read_b128 v[32:35], v82 offset:18496
	ds_read_b128 v[48:51], v85 offset:46144
	s_waitcnt lgkmcnt(3)
	v_mfma_f32_32x32x16_bf16 v[0:15], v[52:55], v[44:47], v[0:15]
	v_mfma_f32_32x32x16_bf16 v[16:31], v[52:55], v[40:43], v[16:31]
	ds_read_b128 v[60:63], v82 offset:23136
	ds_read_b128 v[56:59], v82 offset:18528
	ds_read_b128 v[64:67], v85 offset:46176
	s_waitcnt lgkmcnt(0)
	s_barrier
	v_mfma_f32_32x32x16_bf16 v[0:15], v[48:51], v[36:39], v[0:15]
	v_mfma_f32_32x32x16_bf16 v[16:31], v[48:51], v[32:35], v[16:31]
	v_mfma_f32_32x32x16_bf16 v[0:15], v[64:67], v[60:63], v[0:15]
	v_mfma_f32_32x32x16_bf16 v[16:31], v[64:67], v[56:59], v[16:31]
	s_nop 10
	v_cvt_pk_bf16_f32 v126, v0, v1
	v_mov_b32_e32 v0, v161
	v_mov_b32_e32 v1, v186
	v_cvt_pk_bf16_f32 v125, v2, v3
	v_cvt_pk_bf16_f32 v124, v4, v5
	v_lshlrev_b32_e32 v2, 4, v1
	v_cvt_pk_bf16_f32 v129, v26, v27
	v_ashrrev_i32_e32 v27, 3, v1
	v_and_b32_e32 v26, 0x70, v2
	v_lshl_or_b32 v135, v27, 11, v26
	v_add_u32_e32 v136, 0x10000, v135
	v_add_u32_e32 v137, 0x20000, v135
	v_add_u32_e32 v138, 0x30000, v135
	v_cvt_pk_bf16_f32 v134, v16, v17
	v_cvt_pk_bf16_f32 v133, v18, v19
	v_cvt_pk_bf16_f32 v132, v20, v21
	v_cvt_pk_bf16_f32 v131, v22, v23
	v_cvt_pk_bf16_f32 v130, v24, v25
	v_cvt_pk_bf16_f32 v123, v6, v7
	v_cvt_pk_bf16_f32 v122, v8, v9
	v_cvt_pk_bf16_f32 v121, v10, v11
	v_cvt_pk_bf16_f32 v120, v12, v13
	v_cvt_pk_bf16_f32 v119, v14, v15
	s_barrier
	global_load_dwordx4 v[2:5], v135, s[4:5]
	global_load_dwordx4 v[6:9], v136, s[4:5]
	global_load_dwordx4 v[10:13], v137, s[4:5]
	global_load_dwordx4 v[14:17], v138, s[4:5]
	global_load_dwordx4 v[18:21], v135, s[6:7]
	global_load_dwordx4 v[22:25], v136, s[6:7]
	v_mad_u64_u32 v[82:83], s[18:19], v27, s43, v[26:27]
	v_cvt_pk_bf16_f32 v128, v28, v29
	v_cvt_pk_bf16_f32 v127, v30, v31
	s_waitcnt vmcnt(5)
	ds_write_b128 v82, v[2:5]
	s_waitcnt vmcnt(4)
	ds_write_b128 v82, v[6:9] offset:4608
	s_waitcnt vmcnt(3)
	ds_write_b128 v82, v[10:13] offset:9216
	s_waitcnt vmcnt(2)
	ds_write_b128 v82, v[14:17] offset:13824
	s_waitcnt vmcnt(1)
	ds_write_b128 v82, v[18:21] offset:36864
	s_waitcnt vmcnt(0)
	ds_write_b128 v82, v[22:25] offset:41472
	global_load_dwordx4 v[40:43], v135, s[4:5] offset:128
	global_load_dwordx4 v[44:47], v136, s[4:5] offset:128
	global_load_dwordx4 v[48:51], v137, s[4:5] offset:128
	global_load_dwordx4 v[52:55], v138, s[4:5] offset:128
	global_load_dwordx4 v[32:35], v135, s[6:7] offset:128
	global_load_dwordx4 v[36:39], v136, s[6:7] offset:128
	v_lshrrev_b32_e32 v3, 1, v1
	v_and_b32_e32 v1, 31, v1
	v_and_or_b32 v4, v3, 32, v1
	v_and_b32_e32 v2, 16, v3
	v_and_or_b32 v1, v3, s44, v1
	v_mad_u64_u32 v[84:85], s[18:19], v1, s43, v[2:3]
	s_waitcnt lgkmcnt(0)
	s_barrier
	ds_read_b128 v[56:59], v84 offset:4608
	ds_read_b128 v[60:63], v84
	v_mad_u32_u24 v83, v4, s43, v2
	ds_read_b128 v[140:143], v84 offset:32
	ds_read_b128 v[64:67], v83 offset:36864
	ds_read_b128 v[144:147], v84 offset:4640
	v_mov_b32_e32 v1, v0
	v_mov_b32_e32 v2, v0
	v_mov_b32_e32 v3, v0
	v_mov_b32_e32 v4, v0
	v_mov_b32_e32 v5, v0
	v_mov_b32_e32 v6, v0
	v_mov_b32_e32 v7, v0
	v_mov_b32_e32 v8, v0
	v_mov_b32_e32 v9, v0
	v_mov_b32_e32 v10, v0
	v_mov_b32_e32 v11, v0
	v_mov_b32_e32 v12, v0
	v_mov_b32_e32 v13, v0
	v_mov_b32_e32 v14, v0
	v_mov_b32_e32 v15, v0
	ds_read_b128 v[148:151], v83 offset:36896
	s_waitcnt lgkmcnt(2)
	v_mfma_f32_32x32x16_bf16 v[16:31], v[64:67], v[60:63], v[0:15]
	v_mfma_f32_32x32x16_bf16 v[0:15], v[64:67], v[56:59], v[0:15]
	s_waitcnt lgkmcnt(0)
	v_mfma_f32_32x32x16_bf16 v[16:31], v[148:151], v[140:143], v[16:31]
	v_mfma_f32_32x32x16_bf16 v[0:15], v[148:151], v[144:147], v[0:15]
	ds_read_b128 v[152:155], v84 offset:64
	ds_read_b128 v[156:159], v84 offset:4672
	ds_read_b128 v[164:167], v83 offset:36928
	s_waitcnt lgkmcnt(0)
	v_mfma_f32_32x32x16_bf16 v[16:31], v[164:167], v[152:155], v[16:31]
	v_mfma_f32_32x32x16_bf16 v[0:15], v[164:167], v[156:159], v[0:15]
	global_load_dwordx4 v[64:67], v135, s[4:5] offset:256
	global_load_dwordx4 v[68:71], v136, s[4:5] offset:256
	global_load_dwordx4 v[72:75], v137, s[4:5] offset:256
	global_load_dwordx4 v[76:79], v138, s[4:5] offset:256
	global_load_dwordx4 v[56:59], v135, s[6:7] offset:256
	global_load_dwordx4 v[60:63], v136, s[6:7] offset:256
	s_waitcnt vmcnt(11)
	ds_write_b128 v82, v[40:43] offset:18432
	s_waitcnt vmcnt(10)
	ds_write_b128 v82, v[44:47] offset:23040
	s_waitcnt vmcnt(9)
	ds_write_b128 v82, v[48:51] offset:27648
	s_waitcnt vmcnt(8)
	ds_write_b128 v82, v[52:55] offset:32256
	ds_read_b128 v[40:43], v84 offset:96
	ds_read_b128 v[44:47], v84 offset:4704
	ds_read_b128 v[48:51], v83 offset:36960
	s_waitcnt vmcnt(7)
	ds_write_b128 v82, v[32:35] offset:46080
	s_waitcnt vmcnt(6)
	ds_write_b128 v82, v[36:39] offset:50688
	s_waitcnt lgkmcnt(2)
	v_mfma_f32_32x32x16_bf16 v[16:31], v[48:51], v[40:43], v[16:31]
	s_waitcnt lgkmcnt(0)
	s_barrier
	v_mfma_f32_32x32x16_bf16 v[0:15], v[48:51], v[44:47], v[0:15]
	ds_read_b128 v[32:35], v84 offset:23040
	ds_read_b128 v[36:39], v84 offset:18432
	ds_read_b128 v[48:51], v83 offset:46080
	ds_read_b128 v[40:43], v84 offset:18464
	ds_read_b128 v[44:47], v84 offset:23072
	ds_read_b128 v[52:55], v83 offset:46112
	s_waitcnt lgkmcnt(3)
	v_mfma_f32_32x32x16_bf16 v[16:31], v[48:51], v[36:39], v[16:31]
	v_mfma_f32_32x32x16_bf16 v[0:15], v[48:51], v[32:35], v[0:15]
	global_load_dwordx4 v[32:35], v135, s[4:5] offset:384
	global_load_dwordx4 v[36:39], v136, s[4:5] offset:384
	global_load_dwordx4 v[48:51], v137, s[4:5] offset:384
	global_load_dwordx4 v[140:143], v138, s[4:5] offset:384
	global_load_dwordx4 v[144:147], v135, s[6:7] offset:384
	global_load_dwordx4 v[148:151], v136, s[6:7] offset:384
	ds_read_b128 v[152:155], v84 offset:18496
	ds_read_b128 v[156:159], v84 offset:23104
	ds_read_b128 v[164:167], v83 offset:46144
	s_waitcnt vmcnt(11)
	ds_write_b128 v82, v[64:67]
	s_waitcnt vmcnt(10)
	ds_write_b128 v82, v[68:71] offset:4608
	s_waitcnt vmcnt(9)
	ds_write_b128 v82, v[72:75] offset:9216
	s_waitcnt vmcnt(8)
	ds_write_b128 v82, v[76:79] offset:13824
	s_waitcnt lgkmcnt(7)
	v_mfma_f32_32x32x16_bf16 v[16:31], v[52:55], v[40:43], v[16:31]
	v_mfma_f32_32x32x16_bf16 v[0:15], v[52:55], v[44:47], v[0:15]
	ds_read_b128 v[40:43], v84 offset:18528
	ds_read_b128 v[44:47], v84 offset:23136
	ds_read_b128 v[52:55], v83 offset:46176
	s_waitcnt vmcnt(7)
	ds_write_b128 v82, v[56:59] offset:36864
	s_waitcnt vmcnt(6)
	ds_write_b128 v82, v[60:63] offset:41472
	s_waitcnt lgkmcnt(0)
	s_barrier
	v_mfma_f32_32x32x16_bf16 v[16:31], v[164:167], v[152:155], v[16:31]
	v_mfma_f32_32x32x16_bf16 v[0:15], v[164:167], v[156:159], v[0:15]
	v_mfma_f32_32x32x16_bf16 v[16:31], v[52:55], v[40:43], v[16:31]
	v_mfma_f32_32x32x16_bf16 v[0:15], v[52:55], v[44:47], v[0:15]
	ds_read_b128 v[40:43], v84 offset:4608
	ds_read_b128 v[44:47], v84
	ds_read_b128 v[60:63], v83 offset:36864
	ds_read_b128 v[52:55], v84 offset:32
	ds_read_b128 v[56:59], v84 offset:4640
	ds_read_b128 v[64:67], v83 offset:36896
	s_waitcnt lgkmcnt(3)
	v_mfma_f32_32x32x16_bf16 v[16:31], v[60:63], v[44:47], v[16:31]
	v_mfma_f32_32x32x16_bf16 v[0:15], v[60:63], v[40:43], v[0:15]
	global_load_dwordx4 v[40:43], v135, s[4:5] offset:512
	global_load_dwordx4 v[44:47], v136, s[4:5] offset:512
	global_load_dwordx4 v[60:63], v137, s[4:5] offset:512
	global_load_dwordx4 v[68:71], v138, s[4:5] offset:512
	global_load_dwordx4 v[72:75], v135, s[6:7] offset:512
	global_load_dwordx4 v[76:79], v136, s[6:7] offset:512
	ds_read_b128 v[152:155], v84 offset:64
	ds_read_b128 v[156:159], v84 offset:4672
	ds_read_b128 v[164:167], v83 offset:36928
	s_waitcnt vmcnt(11)
	ds_write_b128 v82, v[32:35] offset:18432
	s_waitcnt vmcnt(10)
	ds_write_b128 v82, v[36:39] offset:23040
	s_waitcnt vmcnt(9)
	ds_write_b128 v82, v[48:51] offset:27648
	s_waitcnt vmcnt(8)
	ds_write_b128 v82, v[140:143] offset:32256
	s_waitcnt lgkmcnt(7)
	v_mfma_f32_32x32x16_bf16 v[16:31], v[64:67], v[52:55], v[16:31]
	v_mfma_f32_32x32x16_bf16 v[0:15], v[64:67], v[56:59], v[0:15]
	ds_read_b128 v[32:35], v84 offset:96
	ds_read_b128 v[36:39], v84 offset:4704
	ds_read_b128 v[48:51], v83 offset:36960
	s_waitcnt vmcnt(7)
	ds_write_b128 v82, v[144:147] offset:46080
	s_waitcnt vmcnt(6)
	ds_write_b128 v82, v[148:151] offset:50688
	s_waitcnt lgkmcnt(0)
	s_barrier
	v_mfma_f32_32x32x16_bf16 v[16:31], v[164:167], v[152:155], v[16:31]
	v_mfma_f32_32x32x16_bf16 v[0:15], v[164:167], v[156:159], v[0:15]
	v_mfma_f32_32x32x16_bf16 v[16:31], v[48:51], v[32:35], v[16:31]
	v_mfma_f32_32x32x16_bf16 v[0:15], v[48:51], v[36:39], v[0:15]
	ds_read_b128 v[32:35], v84 offset:23040
	ds_read_b128 v[36:39], v84 offset:18432
	ds_read_b128 v[56:59], v83 offset:46080
	ds_read_b128 v[48:51], v84 offset:18464
	ds_read_b128 v[52:55], v84 offset:23072
	ds_read_b128 v[64:67], v83 offset:46112
	s_waitcnt lgkmcnt(3)
	v_mfma_f32_32x32x16_bf16 v[16:31], v[56:59], v[36:39], v[16:31]
	v_mfma_f32_32x32x16_bf16 v[0:15], v[56:59], v[32:35], v[0:15]
	global_load_dwordx4 v[32:35], v135, s[4:5] offset:640
	global_load_dwordx4 v[36:39], v136, s[4:5] offset:640
	global_load_dwordx4 v[56:59], v137, s[4:5] offset:640
	global_load_dwordx4 v[140:143], v138, s[4:5] offset:640
	global_load_dwordx4 v[144:147], v135, s[6:7] offset:640
	global_load_dwordx4 v[148:151], v136, s[6:7] offset:640
	ds_read_b128 v[152:155], v84 offset:18496
	ds_read_b128 v[156:159], v84 offset:23104
	ds_read_b128 v[164:167], v83 offset:46144
	s_waitcnt vmcnt(11)
	ds_write_b128 v82, v[40:43]
	s_waitcnt vmcnt(10)
	ds_write_b128 v82, v[44:47] offset:4608
	s_waitcnt vmcnt(9)
	ds_write_b128 v82, v[60:63] offset:9216
	s_waitcnt vmcnt(8)
	ds_write_b128 v82, v[68:71] offset:13824
	s_waitcnt lgkmcnt(7)
	v_mfma_f32_32x32x16_bf16 v[16:31], v[64:67], v[48:51], v[16:31]
	v_mfma_f32_32x32x16_bf16 v[0:15], v[64:67], v[52:55], v[0:15]
	ds_read_b128 v[40:43], v84 offset:18528
	ds_read_b128 v[44:47], v84 offset:23136
	ds_read_b128 v[48:51], v83 offset:46176
	s_waitcnt vmcnt(7)
	ds_write_b128 v82, v[72:75] offset:36864
	s_waitcnt vmcnt(6)
	ds_write_b128 v82, v[76:79] offset:41472
	s_waitcnt lgkmcnt(0)
	s_barrier
	v_mfma_f32_32x32x16_bf16 v[16:31], v[164:167], v[152:155], v[16:31]
	v_mfma_f32_32x32x16_bf16 v[0:15], v[164:167], v[156:159], v[0:15]
	v_mfma_f32_32x32x16_bf16 v[16:31], v[48:51], v[40:43], v[16:31]
	v_mfma_f32_32x32x16_bf16 v[0:15], v[48:51], v[44:47], v[0:15]
	ds_read_b128 v[40:43], v84 offset:4608
	ds_read_b128 v[44:47], v84
	ds_read_b128 v[60:63], v83 offset:36864
	ds_read_b128 v[48:51], v84 offset:32
	ds_read_b128 v[52:55], v84 offset:4640
	ds_read_b128 v[64:67], v83 offset:36896
	s_waitcnt lgkmcnt(3)
	v_mfma_f32_32x32x16_bf16 v[16:31], v[60:63], v[44:47], v[16:31]
	v_mfma_f32_32x32x16_bf16 v[0:15], v[60:63], v[40:43], v[0:15]
	global_load_dwordx4 v[40:43], v135, s[4:5] offset:768
	global_load_dwordx4 v[44:47], v136, s[4:5] offset:768
	global_load_dwordx4 v[60:63], v137, s[4:5] offset:768
	global_load_dwordx4 v[68:71], v138, s[4:5] offset:768
	global_load_dwordx4 v[72:75], v135, s[6:7] offset:768
	global_load_dwordx4 v[76:79], v136, s[6:7] offset:768
	ds_read_b128 v[152:155], v84 offset:64
	ds_read_b128 v[156:159], v84 offset:4672
	ds_read_b128 v[164:167], v83 offset:36928
	s_waitcnt vmcnt(11)
	ds_write_b128 v82, v[32:35] offset:18432
	s_waitcnt vmcnt(10)
	ds_write_b128 v82, v[36:39] offset:23040
	s_waitcnt vmcnt(9)
	ds_write_b128 v82, v[56:59] offset:27648
	s_waitcnt vmcnt(8)
	ds_write_b128 v82, v[140:143] offset:32256
	s_waitcnt lgkmcnt(7)
	v_mfma_f32_32x32x16_bf16 v[16:31], v[64:67], v[48:51], v[16:31]
	v_mfma_f32_32x32x16_bf16 v[0:15], v[64:67], v[52:55], v[0:15]
	ds_read_b128 v[32:35], v84 offset:96
	ds_read_b128 v[36:39], v84 offset:4704
	ds_read_b128 v[48:51], v83 offset:36960
	s_waitcnt vmcnt(7)
	ds_write_b128 v82, v[144:147] offset:46080
	s_waitcnt vmcnt(6)
	ds_write_b128 v82, v[148:151] offset:50688
	s_waitcnt lgkmcnt(0)
	s_barrier
	v_mfma_f32_32x32x16_bf16 v[16:31], v[164:167], v[152:155], v[16:31]
	v_mfma_f32_32x32x16_bf16 v[0:15], v[164:167], v[156:159], v[0:15]
	v_mfma_f32_32x32x16_bf16 v[16:31], v[48:51], v[32:35], v[16:31]
	v_mfma_f32_32x32x16_bf16 v[0:15], v[48:51], v[36:39], v[0:15]
	ds_read_b128 v[32:35], v84 offset:23040
	ds_read_b128 v[36:39], v84 offset:18432
	ds_read_b128 v[56:59], v83 offset:46080
	ds_read_b128 v[48:51], v84 offset:18464
	ds_read_b128 v[52:55], v84 offset:23072
	ds_read_b128 v[64:67], v83 offset:46112
	s_waitcnt lgkmcnt(3)
	v_mfma_f32_32x32x16_bf16 v[16:31], v[56:59], v[36:39], v[16:31]
	v_mfma_f32_32x32x16_bf16 v[0:15], v[56:59], v[32:35], v[0:15]
	global_load_dwordx4 v[32:35], v135, s[4:5] offset:896
	global_load_dwordx4 v[36:39], v136, s[4:5] offset:896
	global_load_dwordx4 v[56:59], v137, s[4:5] offset:896
	global_load_dwordx4 v[140:143], v138, s[4:5] offset:896
	global_load_dwordx4 v[144:147], v135, s[6:7] offset:896
	global_load_dwordx4 v[148:151], v136, s[6:7] offset:896
	ds_read_b128 v[152:155], v84 offset:18496
	ds_read_b128 v[156:159], v84 offset:23104
	ds_read_b128 v[164:167], v83 offset:46144
	s_waitcnt vmcnt(11)
	ds_write_b128 v82, v[40:43]
	s_waitcnt vmcnt(10)
	ds_write_b128 v82, v[44:47] offset:4608
	s_waitcnt vmcnt(9)
	ds_write_b128 v82, v[60:63] offset:9216
	s_waitcnt vmcnt(8)
	ds_write_b128 v82, v[68:71] offset:13824
	s_waitcnt lgkmcnt(7)
	v_mfma_f32_32x32x16_bf16 v[16:31], v[64:67], v[48:51], v[16:31]
	v_mfma_f32_32x32x16_bf16 v[0:15], v[64:67], v[52:55], v[0:15]
	ds_read_b128 v[40:43], v84 offset:18528
	ds_read_b128 v[44:47], v84 offset:23136
	ds_read_b128 v[48:51], v83 offset:46176
	s_waitcnt vmcnt(7)
	ds_write_b128 v82, v[72:75] offset:36864
	s_waitcnt vmcnt(6)
	ds_write_b128 v82, v[76:79] offset:41472
	s_waitcnt lgkmcnt(0)
	s_barrier
	v_mfma_f32_32x32x16_bf16 v[16:31], v[164:167], v[152:155], v[16:31]
	v_mfma_f32_32x32x16_bf16 v[0:15], v[164:167], v[156:159], v[0:15]
	v_mfma_f32_32x32x16_bf16 v[16:31], v[48:51], v[40:43], v[16:31]
	v_mfma_f32_32x32x16_bf16 v[0:15], v[48:51], v[44:47], v[0:15]
	ds_read_b128 v[40:43], v84 offset:4608
	ds_read_b128 v[44:47], v84
	ds_read_b128 v[60:63], v83 offset:36864
	ds_read_b128 v[48:51], v84 offset:32
	ds_read_b128 v[52:55], v84 offset:4640
	ds_read_b128 v[64:67], v83 offset:36896
	s_waitcnt lgkmcnt(3)
	v_mfma_f32_32x32x16_bf16 v[16:31], v[60:63], v[44:47], v[16:31]
	v_mfma_f32_32x32x16_bf16 v[0:15], v[60:63], v[40:43], v[0:15]
	global_load_dwordx4 v[40:43], v135, s[4:5] offset:1024
	global_load_dwordx4 v[44:47], v136, s[4:5] offset:1024
	global_load_dwordx4 v[60:63], v137, s[4:5] offset:1024
	global_load_dwordx4 v[68:71], v138, s[4:5] offset:1024
	global_load_dwordx4 v[72:75], v135, s[6:7] offset:1024
	global_load_dwordx4 v[76:79], v136, s[6:7] offset:1024
	ds_read_b128 v[152:155], v84 offset:64
	ds_read_b128 v[156:159], v84 offset:4672
	ds_read_b128 v[164:167], v83 offset:36928
	s_waitcnt vmcnt(11)
	ds_write_b128 v82, v[32:35] offset:18432
	s_waitcnt vmcnt(10)
	ds_write_b128 v82, v[36:39] offset:23040
	s_waitcnt vmcnt(9)
	ds_write_b128 v82, v[56:59] offset:27648
	s_waitcnt vmcnt(8)
	ds_write_b128 v82, v[140:143] offset:32256
	s_waitcnt lgkmcnt(7)
	v_mfma_f32_32x32x16_bf16 v[16:31], v[64:67], v[48:51], v[16:31]
	v_mfma_f32_32x32x16_bf16 v[0:15], v[64:67], v[52:55], v[0:15]
	ds_read_b128 v[32:35], v84 offset:96
	ds_read_b128 v[36:39], v84 offset:4704
	ds_read_b128 v[48:51], v83 offset:36960
	s_waitcnt vmcnt(7)
	ds_write_b128 v82, v[144:147] offset:46080
	s_waitcnt vmcnt(6)
	ds_write_b128 v82, v[148:151] offset:50688
	s_waitcnt lgkmcnt(0)
	s_barrier
	v_mfma_f32_32x32x16_bf16 v[16:31], v[164:167], v[152:155], v[16:31]
	v_mfma_f32_32x32x16_bf16 v[0:15], v[164:167], v[156:159], v[0:15]
	v_mfma_f32_32x32x16_bf16 v[16:31], v[48:51], v[32:35], v[16:31]
	v_mfma_f32_32x32x16_bf16 v[0:15], v[48:51], v[36:39], v[0:15]
	ds_read_b128 v[32:35], v84 offset:23040
	ds_read_b128 v[36:39], v84 offset:18432
	ds_read_b128 v[56:59], v83 offset:46080
	ds_read_b128 v[48:51], v84 offset:18464
	ds_read_b128 v[52:55], v84 offset:23072
	ds_read_b128 v[64:67], v83 offset:46112
	s_waitcnt lgkmcnt(3)
	v_mfma_f32_32x32x16_bf16 v[16:31], v[56:59], v[36:39], v[16:31]
	v_mfma_f32_32x32x16_bf16 v[0:15], v[56:59], v[32:35], v[0:15]
	global_load_dwordx4 v[32:35], v135, s[4:5] offset:1152
	global_load_dwordx4 v[36:39], v136, s[4:5] offset:1152
	global_load_dwordx4 v[56:59], v137, s[4:5] offset:1152
	global_load_dwordx4 v[140:143], v138, s[4:5] offset:1152
	global_load_dwordx4 v[144:147], v135, s[6:7] offset:1152
	global_load_dwordx4 v[148:151], v136, s[6:7] offset:1152
	ds_read_b128 v[152:155], v84 offset:18496
	ds_read_b128 v[156:159], v84 offset:23104
	ds_read_b128 v[164:167], v83 offset:46144
	s_waitcnt vmcnt(11)
	ds_write_b128 v82, v[40:43]
	s_waitcnt vmcnt(10)
	ds_write_b128 v82, v[44:47] offset:4608
	s_waitcnt vmcnt(9)
	ds_write_b128 v82, v[60:63] offset:9216
	s_waitcnt vmcnt(8)
	ds_write_b128 v82, v[68:71] offset:13824
	s_waitcnt lgkmcnt(7)
	v_mfma_f32_32x32x16_bf16 v[16:31], v[64:67], v[48:51], v[16:31]
	v_mfma_f32_32x32x16_bf16 v[0:15], v[64:67], v[52:55], v[0:15]
	ds_read_b128 v[40:43], v84 offset:18528
	ds_read_b128 v[44:47], v84 offset:23136
	ds_read_b128 v[48:51], v83 offset:46176
	s_waitcnt vmcnt(7)
	ds_write_b128 v82, v[72:75] offset:36864
	s_waitcnt vmcnt(6)
	ds_write_b128 v82, v[76:79] offset:41472
	s_waitcnt lgkmcnt(0)
	s_barrier
	v_mfma_f32_32x32x16_bf16 v[16:31], v[164:167], v[152:155], v[16:31]
	v_mfma_f32_32x32x16_bf16 v[0:15], v[164:167], v[156:159], v[0:15]
	v_mfma_f32_32x32x16_bf16 v[16:31], v[48:51], v[40:43], v[16:31]
	v_mfma_f32_32x32x16_bf16 v[0:15], v[48:51], v[44:47], v[0:15]
	ds_read_b128 v[40:43], v84 offset:4608
	ds_read_b128 v[44:47], v84
	ds_read_b128 v[60:63], v83 offset:36864
	ds_read_b128 v[48:51], v84 offset:32
	ds_read_b128 v[52:55], v84 offset:4640
	ds_read_b128 v[64:67], v83 offset:36896
	s_waitcnt lgkmcnt(3)
	v_mfma_f32_32x32x16_bf16 v[16:31], v[60:63], v[44:47], v[16:31]
	v_mfma_f32_32x32x16_bf16 v[0:15], v[60:63], v[40:43], v[0:15]
	global_load_dwordx4 v[40:43], v135, s[4:5] offset:1280
	global_load_dwordx4 v[44:47], v136, s[4:5] offset:1280
	global_load_dwordx4 v[60:63], v137, s[4:5] offset:1280
	global_load_dwordx4 v[68:71], v138, s[4:5] offset:1280
	global_load_dwordx4 v[72:75], v135, s[6:7] offset:1280
	global_load_dwordx4 v[76:79], v136, s[6:7] offset:1280
	ds_read_b128 v[152:155], v84 offset:64
	ds_read_b128 v[156:159], v84 offset:4672
	ds_read_b128 v[164:167], v83 offset:36928
	s_waitcnt vmcnt(11)
	ds_write_b128 v82, v[32:35] offset:18432
	s_waitcnt vmcnt(10)
	ds_write_b128 v82, v[36:39] offset:23040
	s_waitcnt vmcnt(9)
	ds_write_b128 v82, v[56:59] offset:27648
	s_waitcnt vmcnt(8)
	ds_write_b128 v82, v[140:143] offset:32256
	s_waitcnt lgkmcnt(7)
	v_mfma_f32_32x32x16_bf16 v[16:31], v[64:67], v[48:51], v[16:31]
	v_mfma_f32_32x32x16_bf16 v[0:15], v[64:67], v[52:55], v[0:15]
	ds_read_b128 v[32:35], v84 offset:96
	ds_read_b128 v[36:39], v84 offset:4704
	ds_read_b128 v[48:51], v83 offset:36960
	s_waitcnt vmcnt(7)
	ds_write_b128 v82, v[144:147] offset:46080
	s_waitcnt vmcnt(6)
	ds_write_b128 v82, v[148:151] offset:50688
	s_waitcnt lgkmcnt(0)
	s_barrier
	v_mfma_f32_32x32x16_bf16 v[16:31], v[164:167], v[152:155], v[16:31]
	v_mfma_f32_32x32x16_bf16 v[0:15], v[164:167], v[156:159], v[0:15]
	v_mfma_f32_32x32x16_bf16 v[16:31], v[48:51], v[32:35], v[16:31]
	v_mfma_f32_32x32x16_bf16 v[0:15], v[48:51], v[36:39], v[0:15]
	ds_read_b128 v[32:35], v84 offset:23040
	ds_read_b128 v[36:39], v84 offset:18432
	ds_read_b128 v[56:59], v83 offset:46080
	ds_read_b128 v[48:51], v84 offset:18464
	ds_read_b128 v[52:55], v84 offset:23072
	ds_read_b128 v[64:67], v83 offset:46112
	s_waitcnt lgkmcnt(3)
	v_mfma_f32_32x32x16_bf16 v[16:31], v[56:59], v[36:39], v[16:31]
	v_mfma_f32_32x32x16_bf16 v[0:15], v[56:59], v[32:35], v[0:15]
	global_load_dwordx4 v[32:35], v135, s[4:5] offset:1408
	global_load_dwordx4 v[36:39], v136, s[4:5] offset:1408
	global_load_dwordx4 v[56:59], v137, s[4:5] offset:1408
	global_load_dwordx4 v[140:143], v138, s[4:5] offset:1408
	global_load_dwordx4 v[144:147], v135, s[6:7] offset:1408
	global_load_dwordx4 v[148:151], v136, s[6:7] offset:1408
	ds_read_b128 v[152:155], v84 offset:18496
	ds_read_b128 v[156:159], v84 offset:23104
	ds_read_b128 v[164:167], v83 offset:46144
	s_waitcnt vmcnt(11)
	ds_write_b128 v82, v[40:43]
	s_waitcnt vmcnt(10)
	ds_write_b128 v82, v[44:47] offset:4608
	s_waitcnt vmcnt(9)
	ds_write_b128 v82, v[60:63] offset:9216
	s_waitcnt vmcnt(8)
	ds_write_b128 v82, v[68:71] offset:13824
	s_waitcnt lgkmcnt(7)
	v_mfma_f32_32x32x16_bf16 v[16:31], v[64:67], v[48:51], v[16:31]
	v_mfma_f32_32x32x16_bf16 v[0:15], v[64:67], v[52:55], v[0:15]
	ds_read_b128 v[40:43], v84 offset:18528
	ds_read_b128 v[44:47], v84 offset:23136
	ds_read_b128 v[48:51], v83 offset:46176
	s_waitcnt vmcnt(7)
	ds_write_b128 v82, v[72:75] offset:36864
	s_waitcnt vmcnt(6)
	ds_write_b128 v82, v[76:79] offset:41472
	s_waitcnt lgkmcnt(0)
	s_barrier
	v_mfma_f32_32x32x16_bf16 v[16:31], v[164:167], v[152:155], v[16:31]
	v_mfma_f32_32x32x16_bf16 v[0:15], v[164:167], v[156:159], v[0:15]
	v_mfma_f32_32x32x16_bf16 v[16:31], v[48:51], v[40:43], v[16:31]
	v_mfma_f32_32x32x16_bf16 v[0:15], v[48:51], v[44:47], v[0:15]
	ds_read_b128 v[40:43], v84 offset:4608
	ds_read_b128 v[44:47], v84
	ds_read_b128 v[60:63], v83 offset:36864
	ds_read_b128 v[48:51], v84 offset:32
	ds_read_b128 v[52:55], v84 offset:4640
	ds_read_b128 v[64:67], v83 offset:36896
	s_waitcnt lgkmcnt(3)
	v_mfma_f32_32x32x16_bf16 v[16:31], v[60:63], v[44:47], v[16:31]
	v_mfma_f32_32x32x16_bf16 v[0:15], v[60:63], v[40:43], v[0:15]
	global_load_dwordx4 v[40:43], v135, s[4:5] offset:1536
	global_load_dwordx4 v[44:47], v136, s[4:5] offset:1536
	global_load_dwordx4 v[60:63], v137, s[4:5] offset:1536
	global_load_dwordx4 v[68:71], v138, s[4:5] offset:1536
	global_load_dwordx4 v[72:75], v135, s[6:7] offset:1536
	global_load_dwordx4 v[76:79], v136, s[6:7] offset:1536
	ds_read_b128 v[152:155], v84 offset:64
	ds_read_b128 v[156:159], v84 offset:4672
	ds_read_b128 v[164:167], v83 offset:36928
	s_waitcnt vmcnt(11)
	ds_write_b128 v82, v[32:35] offset:18432
	s_waitcnt vmcnt(10)
	ds_write_b128 v82, v[36:39] offset:23040
	s_waitcnt vmcnt(9)
	ds_write_b128 v82, v[56:59] offset:27648
	s_waitcnt vmcnt(8)
	ds_write_b128 v82, v[140:143] offset:32256
	s_waitcnt lgkmcnt(7)
	v_mfma_f32_32x32x16_bf16 v[16:31], v[64:67], v[48:51], v[16:31]
	v_mfma_f32_32x32x16_bf16 v[0:15], v[64:67], v[52:55], v[0:15]
	ds_read_b128 v[32:35], v84 offset:96
	ds_read_b128 v[36:39], v84 offset:4704
	ds_read_b128 v[48:51], v83 offset:36960
	s_waitcnt vmcnt(7)
	ds_write_b128 v82, v[144:147] offset:46080
	s_waitcnt vmcnt(6)
	ds_write_b128 v82, v[148:151] offset:50688
	s_waitcnt lgkmcnt(0)
	s_barrier
	v_mfma_f32_32x32x16_bf16 v[16:31], v[164:167], v[152:155], v[16:31]
	v_mfma_f32_32x32x16_bf16 v[0:15], v[164:167], v[156:159], v[0:15]
	v_mfma_f32_32x32x16_bf16 v[16:31], v[48:51], v[32:35], v[16:31]
	v_mfma_f32_32x32x16_bf16 v[0:15], v[48:51], v[36:39], v[0:15]
	ds_read_b128 v[32:35], v84 offset:23040
	ds_read_b128 v[36:39], v84 offset:18432
	ds_read_b128 v[56:59], v83 offset:46080
	ds_read_b128 v[48:51], v84 offset:18464
	ds_read_b128 v[52:55], v84 offset:23072
	ds_read_b128 v[64:67], v83 offset:46112
	s_waitcnt lgkmcnt(3)
	v_mfma_f32_32x32x16_bf16 v[16:31], v[56:59], v[36:39], v[16:31]
	v_mfma_f32_32x32x16_bf16 v[0:15], v[56:59], v[32:35], v[0:15]
	global_load_dwordx4 v[32:35], v135, s[4:5] offset:1664
	global_load_dwordx4 v[36:39], v136, s[4:5] offset:1664
	global_load_dwordx4 v[56:59], v137, s[4:5] offset:1664
	global_load_dwordx4 v[140:143], v138, s[4:5] offset:1664
	global_load_dwordx4 v[144:147], v135, s[6:7] offset:1664
	global_load_dwordx4 v[148:151], v136, s[6:7] offset:1664
	ds_read_b128 v[152:155], v84 offset:18496
	ds_read_b128 v[156:159], v84 offset:23104
	ds_read_b128 v[164:167], v83 offset:46144
	s_waitcnt vmcnt(11)
	ds_write_b128 v82, v[40:43]
	s_waitcnt vmcnt(10)
	ds_write_b128 v82, v[44:47] offset:4608
	s_waitcnt vmcnt(9)
	ds_write_b128 v82, v[60:63] offset:9216
	s_waitcnt vmcnt(8)
	ds_write_b128 v82, v[68:71] offset:13824
	s_waitcnt lgkmcnt(7)
	v_mfma_f32_32x32x16_bf16 v[16:31], v[64:67], v[48:51], v[16:31]
	v_mfma_f32_32x32x16_bf16 v[0:15], v[64:67], v[52:55], v[0:15]
	ds_read_b128 v[40:43], v84 offset:18528
	ds_read_b128 v[44:47], v84 offset:23136
	ds_read_b128 v[48:51], v83 offset:46176
	s_waitcnt vmcnt(7)
	ds_write_b128 v82, v[72:75] offset:36864
	s_waitcnt vmcnt(6)
	ds_write_b128 v82, v[76:79] offset:41472
	s_waitcnt lgkmcnt(0)
	s_barrier
	v_mfma_f32_32x32x16_bf16 v[16:31], v[164:167], v[152:155], v[16:31]
	ds_read_b128 v[60:63], v83 offset:36864
	ds_read_b128 v[52:55], v84 offset:4640
	global_load_dwordx4 v[68:71], v138, s[4:5] offset:1792
	ds_read_b128 v[64:67], v83 offset:36896
	ds_read_b128 v[152:155], v84 offset:64
	global_load_dwordx4 v[72:75], v135, s[6:7] offset:1792
	v_mfma_f32_32x32x16_bf16 v[0:15], v[164:167], v[156:159], v[0:15]
	ds_read_b128 v[156:159], v84 offset:4672
	global_load_dwordx4 v[76:79], v136, s[6:7] offset:1792
	ds_read_b128 v[164:167], v83 offset:36928
	v_mfma_f32_32x32x16_bf16 v[16:31], v[48:51], v[40:43], v[16:31]
	ds_read_b128 v[40:43], v84 offset:4608
	v_mfma_f32_32x32x16_bf16 v[0:15], v[48:51], v[44:47], v[0:15]
	ds_read_b128 v[44:47], v84
	ds_read_b128 v[48:51], v84 offset:32
	s_waitcnt vmcnt(8)
	ds_write_b128 v82, v[32:35] offset:18432
	s_waitcnt lgkmcnt(2)
	v_mfma_f32_32x32x16_bf16 v[16:31], v[60:63], v[44:47], v[16:31]
	global_load_dwordx4 v[44:47], v136, s[4:5] offset:1792
	s_waitcnt vmcnt(8)
	ds_write_b128 v82, v[36:39] offset:23040
	s_waitcnt vmcnt(7)
	ds_write_b128 v82, v[56:59] offset:27648
	s_waitcnt vmcnt(6)
	ds_write_b128 v82, v[140:143] offset:32256
	ds_read_b128 v[32:35], v84 offset:96
	ds_read_b128 v[36:39], v84 offset:4704
	v_mfma_f32_32x32x16_bf16 v[0:15], v[60:63], v[40:43], v[0:15]
	global_load_dwordx4 v[40:43], v135, s[4:5] offset:1792
	global_load_dwordx4 v[60:63], v137, s[4:5] offset:1792
	s_waitcnt lgkmcnt(6)
	v_mfma_f32_32x32x16_bf16 v[16:31], v[64:67], v[48:51], v[16:31]
	ds_read_b128 v[48:51], v83 offset:36960
	s_waitcnt vmcnt(7)
	ds_write_b128 v82, v[144:147] offset:46080
	s_waitcnt vmcnt(6)
	ds_write_b128 v82, v[148:151] offset:50688
	s_waitcnt lgkmcnt(0)
	s_barrier
	ds_read_b128 v[56:59], v83 offset:46080
	v_mfma_f32_32x32x16_bf16 v[0:15], v[64:67], v[52:55], v[0:15]
	global_load_dwordx4 v[138:141], v138, s[4:5] offset:1920
	ds_read_b128 v[52:55], v84 offset:23072
	global_load_dwordx4 v[142:145], v135, s[6:7] offset:1920
	global_load_dwordx4 v[146:149], v136, s[6:7] offset:1920
	ds_read_b128 v[64:67], v83 offset:46112
	v_mfma_f32_32x32x16_bf16 v[16:31], v[164:167], v[152:155], v[16:31]
	ds_read_b128 v[150:153], v84 offset:18496
	v_mfma_f32_32x32x16_bf16 v[0:15], v[164:167], v[156:159], v[0:15]
	ds_read_b128 v[154:157], v84 offset:23104
	ds_read_b128 v[164:167], v83 offset:46144
	v_mfma_f32_32x32x16_bf16 v[16:31], v[48:51], v[32:35], v[16:31]
	ds_read_b128 v[32:35], v84 offset:23040
	v_mfma_f32_32x32x16_bf16 v[0:15], v[48:51], v[36:39], v[0:15]
	ds_read_b128 v[36:39], v84 offset:18432
	ds_read_b128 v[48:51], v84 offset:18464
	s_waitcnt vmcnt(8)
	ds_write_b128 v82, v[68:71] offset:13824
	s_waitcnt vmcnt(5)
	ds_write_b128 v82, v[44:47] offset:4608
	s_waitcnt lgkmcnt(3)
	v_mfma_f32_32x32x16_bf16 v[16:31], v[56:59], v[36:39], v[16:31]
	global_load_dwordx4 v[36:39], v136, s[4:5] offset:1920
	s_waitcnt vmcnt(5)
	ds_write_b128 v82, v[40:43]
	v_mfma_f32_32x32x16_bf16 v[0:15], v[56:59], v[32:35], v[0:15]
	global_load_dwordx4 v[32:35], v135, s[4:5] offset:1920
	global_load_dwordx4 v[56:59], v137, s[4:5] offset:1920
	s_waitcnt vmcnt(6)
	ds_write_b128 v82, v[60:63] offset:9216
	ds_read_b128 v[40:43], v84 offset:18528
	ds_read_b128 v[44:47], v84 offset:23136
	s_waitcnt lgkmcnt(6)
	v_mfma_f32_32x32x16_bf16 v[16:31], v[64:67], v[48:51], v[16:31]
	ds_read_b128 v[48:51], v83 offset:46176
	ds_write_b128 v82, v[72:75] offset:36864
	ds_write_b128 v82, v[76:79] offset:41472
	s_waitcnt lgkmcnt(0)
	s_barrier
	ds_read_b128 v[60:63], v84 offset:32
	v_mfma_f32_32x32x16_bf16 v[0:15], v[64:67], v[52:55], v[0:15]
	ds_read_b128 v[52:55], v84
	ds_read_b128 v[64:67], v83 offset:36928
	v_mfma_f32_32x32x16_bf16 v[16:31], v[164:167], v[150:153], v[16:31]
	v_mfma_f32_32x32x16_bf16 v[0:15], v[164:167], v[154:157], v[0:15]
	v_mfma_f32_32x32x16_bf16 v[16:31], v[48:51], v[40:43], v[16:31]
	ds_read_b128 v[40:43], v84 offset:4608
	v_mfma_f32_32x32x16_bf16 v[0:15], v[48:51], v[44:47], v[0:15]
	ds_read_b128 v[44:47], v83 offset:36864
	ds_read_b128 v[48:51], v83 offset:36896
	s_waitcnt lgkmcnt(1)
	v_mfma_f32_32x32x16_bf16 v[0:15], v[44:47], v[40:43], v[0:15]
	ds_read_b128 v[40:43], v84 offset:4640
	v_mfma_f32_32x32x16_bf16 v[16:31], v[44:47], v[52:55], v[16:31]
	ds_read_b128 v[52:55], v84 offset:4672
	ds_read_b128 v[44:47], v84 offset:64
	s_waitcnt vmcnt(5)
	ds_write_b128 v82, v[138:141] offset:32256
	s_waitcnt vmcnt(2)
	ds_write_b128 v82, v[36:39] offset:23040
	s_waitcnt lgkmcnt(4)
	v_mfma_f32_32x32x16_bf16 v[0:15], v[48:51], v[40:43], v[0:15]
	s_waitcnt vmcnt(1)
	ds_write_b128 v82, v[32:35] offset:18432
	v_mfma_f32_32x32x16_bf16 v[16:31], v[48:51], v[60:63], v[16:31]
	s_waitcnt vmcnt(0)
	ds_write_b128 v82, v[56:59] offset:27648
	ds_read_b128 v[36:39], v84 offset:4704
	ds_read_b128 v[32:35], v84 offset:96
	ds_read_b128 v[40:43], v83 offset:36960
	ds_write_b128 v82, v[142:145] offset:46080
	ds_write_b128 v82, v[146:149] offset:50688
	s_waitcnt lgkmcnt(0)
	v_mfma_f32_32x32x16_bf16 v[0:15], v[64:67], v[52:55], v[0:15]
	s_barrier
	ds_read_b128 v[48:51], v83 offset:46080
	ds_read_b128 v[52:55], v83 offset:46112
	ds_read_b128 v[56:59], v84 offset:18528
	ds_read_b128 v[60:63], v84 offset:23136
	v_mfma_f32_32x32x16_bf16 v[16:31], v[64:67], v[44:47], v[16:31]
	ds_read_b128 v[64:67], v83 offset:46176
	ds_read_b128 v[44:47], v84 offset:23072
	v_mfma_f32_32x32x16_bf16 v[0:15], v[40:43], v[36:39], v[0:15]
	ds_read_b128 v[36:39], v84 offset:18432
	v_mfma_f32_32x32x16_bf16 v[16:31], v[40:43], v[32:35], v[16:31]
	ds_read_b128 v[32:35], v84 offset:23040
	ds_read_b128 v[40:43], v84 offset:18464
	s_waitcnt lgkmcnt(2)
	v_mfma_f32_32x32x16_bf16 v[16:31], v[48:51], v[36:39], v[16:31]
	ds_read_b128 v[36:39], v84 offset:23104
	s_waitcnt lgkmcnt(2)
	v_mfma_f32_32x32x16_bf16 v[0:15], v[48:51], v[32:35], v[0:15]
	ds_read_b128 v[32:35], v84 offset:18496
	ds_read_b128 v[48:51], v83 offset:46144
	s_waitcnt lgkmcnt(0)
	s_barrier
	v_mfma_f32_32x32x16_bf16 v[16:31], v[52:55], v[40:43], v[16:31]
	v_mfma_f32_32x32x16_bf16 v[16:31], v[48:51], v[32:35], v[16:31]
	v_mfma_f32_32x32x16_bf16 v[16:31], v[64:67], v[56:59], v[16:31]
	v_mfma_f32_32x32x16_bf16 v[0:15], v[52:55], v[44:47], v[0:15]
	v_mfma_f32_32x32x16_bf16 v[0:15], v[48:51], v[36:39], v[0:15]
	v_mfma_f32_32x32x16_bf16 v[0:15], v[64:67], v[60:63], v[0:15]
	s_waitcnt vmcnt(0)
	v_add_f32_e32 v210, v210, v211
	v_add_f32_e32 v212, v212, v213
	v_add_f32_e32 v214, v214, v215
	v_add_f32_e32 v216, v216, v217
	v_add_f32_e32 v210, v210, v212
	v_add_f32_e32 v214, v214, v216
	v_add_f32_e32 v210, v210, v214
	v_fmamk_f32 v250, v210, 0x3a800000, v187
	v_add_f32_e32 v226, v226, v227
	v_add_f32_e32 v228, v228, v229
	v_add_f32_e32 v230, v230, v231
	v_add_f32_e32 v232, v232, v233
	v_add_f32_e32 v226, v226, v228
	v_add_f32_e32 v230, v230, v232
	v_add_f32_e32 v226, v226, v230
	v_fmamk_f32 v249, v226, 0x3a800000, v187
	v_rsq_f32_e32 v250, v250
	v_rsq_f32_e32 v249, v249
	s_nop 0
	v_readfirstlane_b32 s18, v186
	v_and_b32_e32 v64, 31, v186
	v_bfe_u32 v65, v186, 5, 1
	s_lshr_b32 s18, s18, 6
	s_and_b32 s19, s18, 1
	s_lshr_b32 s18, s18, 1
	s_lshl_b32 s18, s18, 6
	v_add_u32_e32 v64, s18, v64
	v_lshlrev_b32_e32 v64, 12, v64
	v_lshl_add_u32 v64, v65, 4, v64
	s_lshl_b32 s19, s19, 7
	v_add_u32_e32 v64, s19, v64
	v_add_u32_e32 v65, 0x20000, v64
	s_lshl_b32 s18, s0, 12
	s_lshl_b32 s19, s2, 2
	s_add_u32 s18, s18, s19
	s_add_u32 s20, s86, s18
	s_addc_u32 s21, s87, 0
	global_load_dwordx4 v[68:71], v64, s[20:21]
	global_load_dwordx4 v[72:75], v64, s[20:21] offset:32
	global_load_dwordx4 v[76:79], v64, s[20:21] offset:64
	global_load_dwordx4 v[80:83], v64, s[20:21] offset:96
	global_load_dwordx4 v[84:87], v65, s[20:21]
	global_load_dwordx4 v[88:91], v65, s[20:21] offset:32
	global_load_dwordx4 v[92:95], v65, s[20:21] offset:64
	global_load_dwordx4 v[96:99], v65, s[20:21] offset:96
	v_mul_f32_e32 v16, v250, v16
	v_mul_f32_e32 v17, v250, v17
	v_mul_f32_e32 v18, v250, v18
	v_mul_f32_e32 v19, v250, v19
	v_mul_f32_e32 v100, 0xbfb8aa3b, v16
	v_mul_f32_e32 v101, 0xbfb8aa3b, v17
	v_mul_f32_e32 v102, 0xbfb8aa3b, v18
	v_mul_f32_e32 v103, 0xbfb8aa3b, v19
	v_exp_f32_e32 v100, v100
	v_exp_f32_e32 v101, v101
	v_exp_f32_e32 v102, v102
	v_exp_f32_e32 v103, v103
	v_lshlrev_b32_e32 v104, 16, v134
	v_and_b32_e32 v105, 0xffff0000, v134
	v_lshlrev_b32_e32 v106, 16, v133
	v_and_b32_e32 v107, 0xffff0000, v133
	v_add_f32_e32 v100, 1.0, v100
	v_add_f32_e32 v101, 1.0, v101
	v_add_f32_e32 v102, 1.0, v102
	v_add_f32_e32 v103, 1.0, v103
	v_rcp_f32_e32 v100, v100
	v_rcp_f32_e32 v101, v101
	v_rcp_f32_e32 v102, v102
	v_rcp_f32_e32 v103, v103
	s_waitcnt vmcnt(7)
	v_fmac_f32_e32 v68, v100, v104
	v_fmac_f32_e32 v69, v101, v105
	v_fmac_f32_e32 v70, v102, v106
	v_fmac_f32_e32 v71, v103, v107
	global_store_dwordx4 v64, v[68:71], s[20:21]
	v_mul_f32_e32 v20, v250, v20
	v_mul_f32_e32 v21, v250, v21
	v_mul_f32_e32 v22, v250, v22
	v_mul_f32_e32 v23, v250, v23
	v_mul_f32_e32 v100, 0xbfb8aa3b, v20
	v_mul_f32_e32 v101, 0xbfb8aa3b, v21
	v_mul_f32_e32 v102, 0xbfb8aa3b, v22
	v_mul_f32_e32 v103, 0xbfb8aa3b, v23
	v_exp_f32_e32 v100, v100
	v_exp_f32_e32 v101, v101
	v_exp_f32_e32 v102, v102
	v_exp_f32_e32 v103, v103
	v_lshlrev_b32_e32 v104, 16, v132
	v_and_b32_e32 v105, 0xffff0000, v132
	v_lshlrev_b32_e32 v106, 16, v131
	v_and_b32_e32 v107, 0xffff0000, v131
	v_add_f32_e32 v100, 1.0, v100
	v_add_f32_e32 v101, 1.0, v101
	v_add_f32_e32 v102, 1.0, v102
	v_add_f32_e32 v103, 1.0, v103
	v_rcp_f32_e32 v100, v100
	v_rcp_f32_e32 v101, v101
	v_rcp_f32_e32 v102, v102
	v_rcp_f32_e32 v103, v103
	s_waitcnt vmcnt(7)
	v_fmac_f32_e32 v72, v100, v104
	v_fmac_f32_e32 v73, v101, v105
	v_fmac_f32_e32 v74, v102, v106
	v_fmac_f32_e32 v75, v103, v107
	global_store_dwordx4 v64, v[72:75], s[20:21] offset:32
	v_mul_f32_e32 v24, v250, v24
	v_mul_f32_e32 v25, v250, v25
	v_mul_f32_e32 v26, v250, v26
	v_mul_f32_e32 v27, v250, v27
	v_mul_f32_e32 v100, 0xbfb8aa3b, v24
	v_mul_f32_e32 v101, 0xbfb8aa3b, v25
	v_mul_f32_e32 v102, 0xbfb8aa3b, v26
	v_mul_f32_e32 v103, 0xbfb8aa3b, v27
	v_exp_f32_e32 v100, v100
	v_exp_f32_e32 v101, v101
	v_exp_f32_e32 v102, v102
	v_exp_f32_e32 v103, v103
	v_lshlrev_b32_e32 v104, 16, v130
	v_and_b32_e32 v105, 0xffff0000, v130
	v_lshlrev_b32_e32 v106, 16, v129
	v_and_b32_e32 v107, 0xffff0000, v129
	v_add_f32_e32 v100, 1.0, v100
	v_add_f32_e32 v101, 1.0, v101
	v_add_f32_e32 v102, 1.0, v102
	v_add_f32_e32 v103, 1.0, v103
	v_rcp_f32_e32 v100, v100
	v_rcp_f32_e32 v101, v101
	v_rcp_f32_e32 v102, v102
	v_rcp_f32_e32 v103, v103
	s_waitcnt vmcnt(7)
	v_fmac_f32_e32 v76, v100, v104
	v_fmac_f32_e32 v77, v101, v105
	v_fmac_f32_e32 v78, v102, v106
	v_fmac_f32_e32 v79, v103, v107
	global_store_dwordx4 v64, v[76:79], s[20:21] offset:64
	v_mul_f32_e32 v28, v250, v28
	v_mul_f32_e32 v29, v250, v29
	v_mul_f32_e32 v30, v250, v30
	v_mul_f32_e32 v31, v250, v31
	v_mul_f32_e32 v100, 0xbfb8aa3b, v28
	v_mul_f32_e32 v101, 0xbfb8aa3b, v29
	v_mul_f32_e32 v102, 0xbfb8aa3b, v30
	v_mul_f32_e32 v103, 0xbfb8aa3b, v31
	v_exp_f32_e32 v100, v100
	v_exp_f32_e32 v101, v101
	v_exp_f32_e32 v102, v102
	v_exp_f32_e32 v103, v103
	v_lshlrev_b32_e32 v104, 16, v128
	v_and_b32_e32 v105, 0xffff0000, v128
	v_lshlrev_b32_e32 v106, 16, v127
	v_and_b32_e32 v107, 0xffff0000, v127
	v_add_f32_e32 v100, 1.0, v100
	v_add_f32_e32 v101, 1.0, v101
	v_add_f32_e32 v102, 1.0, v102
	v_add_f32_e32 v103, 1.0, v103
	v_rcp_f32_e32 v100, v100
	v_rcp_f32_e32 v101, v101
	v_rcp_f32_e32 v102, v102
	v_rcp_f32_e32 v103, v103
	s_waitcnt vmcnt(7)
	v_fmac_f32_e32 v80, v100, v104
	v_fmac_f32_e32 v81, v101, v105
	v_fmac_f32_e32 v82, v102, v106
	v_fmac_f32_e32 v83, v103, v107
	global_store_dwordx4 v64, v[80:83], s[20:21] offset:96
	v_mul_f32_e32 v0, v249, v0
	v_mul_f32_e32 v1, v249, v1
	v_mul_f32_e32 v2, v249, v2
	v_mul_f32_e32 v3, v249, v3
	v_mul_f32_e32 v100, 0xbfb8aa3b, v0
	v_mul_f32_e32 v101, 0xbfb8aa3b, v1
	v_mul_f32_e32 v102, 0xbfb8aa3b, v2
	v_mul_f32_e32 v103, 0xbfb8aa3b, v3
	v_exp_f32_e32 v100, v100
	v_exp_f32_e32 v101, v101
	v_exp_f32_e32 v102, v102
	v_exp_f32_e32 v103, v103
	v_lshlrev_b32_e32 v104, 16, v126
	v_and_b32_e32 v105, 0xffff0000, v126
	v_lshlrev_b32_e32 v106, 16, v125
	v_and_b32_e32 v107, 0xffff0000, v125
	v_add_f32_e32 v100, 1.0, v100
	v_add_f32_e32 v101, 1.0, v101
	v_add_f32_e32 v102, 1.0, v102
	v_add_f32_e32 v103, 1.0, v103
	v_rcp_f32_e32 v100, v100
	v_rcp_f32_e32 v101, v101
	v_rcp_f32_e32 v102, v102
	v_rcp_f32_e32 v103, v103
	s_waitcnt vmcnt(7)
	v_fmac_f32_e32 v84, v100, v104
	v_fmac_f32_e32 v85, v101, v105
	v_fmac_f32_e32 v86, v102, v106
	v_fmac_f32_e32 v87, v103, v107
	global_store_dwordx4 v65, v[84:87], s[20:21]
	v_mul_f32_e32 v4, v249, v4
	v_mul_f32_e32 v5, v249, v5
	v_mul_f32_e32 v6, v249, v6
	v_mul_f32_e32 v7, v249, v7
	v_mul_f32_e32 v100, 0xbfb8aa3b, v4
	v_mul_f32_e32 v101, 0xbfb8aa3b, v5
	v_mul_f32_e32 v102, 0xbfb8aa3b, v6
	v_mul_f32_e32 v103, 0xbfb8aa3b, v7
	v_exp_f32_e32 v100, v100
	v_exp_f32_e32 v101, v101
	v_exp_f32_e32 v102, v102
	v_exp_f32_e32 v103, v103
	v_lshlrev_b32_e32 v104, 16, v124
	v_and_b32_e32 v105, 0xffff0000, v124
	v_lshlrev_b32_e32 v106, 16, v123
	v_and_b32_e32 v107, 0xffff0000, v123
	v_add_f32_e32 v100, 1.0, v100
	v_add_f32_e32 v101, 1.0, v101
	v_add_f32_e32 v102, 1.0, v102
	v_add_f32_e32 v103, 1.0, v103
	v_rcp_f32_e32 v100, v100
	v_rcp_f32_e32 v101, v101
	v_rcp_f32_e32 v102, v102
	v_rcp_f32_e32 v103, v103
	s_waitcnt vmcnt(7)
	v_fmac_f32_e32 v88, v100, v104
	v_fmac_f32_e32 v89, v101, v105
	v_fmac_f32_e32 v90, v102, v106
	v_fmac_f32_e32 v91, v103, v107
	global_store_dwordx4 v65, v[88:91], s[20:21] offset:32
	v_mul_f32_e32 v8, v249, v8
	v_mul_f32_e32 v9, v249, v9
	v_mul_f32_e32 v10, v249, v10
	v_mul_f32_e32 v11, v249, v11
	v_mul_f32_e32 v100, 0xbfb8aa3b, v8
	v_mul_f32_e32 v101, 0xbfb8aa3b, v9
	v_mul_f32_e32 v102, 0xbfb8aa3b, v10
	v_mul_f32_e32 v103, 0xbfb8aa3b, v11
	v_exp_f32_e32 v100, v100
	v_exp_f32_e32 v101, v101
	v_exp_f32_e32 v102, v102
	v_exp_f32_e32 v103, v103
	v_lshlrev_b32_e32 v104, 16, v122
	v_and_b32_e32 v105, 0xffff0000, v122
	v_lshlrev_b32_e32 v106, 16, v121
	v_and_b32_e32 v107, 0xffff0000, v121
	v_add_f32_e32 v100, 1.0, v100
	v_add_f32_e32 v101, 1.0, v101
	v_add_f32_e32 v102, 1.0, v102
	v_add_f32_e32 v103, 1.0, v103
	v_rcp_f32_e32 v100, v100
	v_rcp_f32_e32 v101, v101
	v_rcp_f32_e32 v102, v102
	v_rcp_f32_e32 v103, v103
	s_waitcnt vmcnt(7)
	v_fmac_f32_e32 v92, v100, v104
	v_fmac_f32_e32 v93, v101, v105
	v_fmac_f32_e32 v94, v102, v106
	v_fmac_f32_e32 v95, v103, v107
	global_store_dwordx4 v65, v[92:95], s[20:21] offset:64
	v_mul_f32_e32 v12, v249, v12
	v_mul_f32_e32 v13, v249, v13
	v_mul_f32_e32 v14, v249, v14
	v_mul_f32_e32 v15, v249, v15
	v_mul_f32_e32 v100, 0xbfb8aa3b, v12
	v_mul_f32_e32 v101, 0xbfb8aa3b, v13
	v_mul_f32_e32 v102, 0xbfb8aa3b, v14
	v_mul_f32_e32 v103, 0xbfb8aa3b, v15
	v_exp_f32_e32 v100, v100
	v_exp_f32_e32 v101, v101
	v_exp_f32_e32 v102, v102
	v_exp_f32_e32 v103, v103
	v_lshlrev_b32_e32 v104, 16, v120
	v_and_b32_e32 v105, 0xffff0000, v120
	v_lshlrev_b32_e32 v106, 16, v119
	v_and_b32_e32 v107, 0xffff0000, v119
	v_add_f32_e32 v100, 1.0, v100
	v_add_f32_e32 v101, 1.0, v101
	v_add_f32_e32 v102, 1.0, v102
	v_add_f32_e32 v103, 1.0, v103
	v_rcp_f32_e32 v100, v100
	v_rcp_f32_e32 v101, v101
	v_rcp_f32_e32 v102, v102
	v_rcp_f32_e32 v103, v103
	s_waitcnt vmcnt(7)
	v_fmac_f32_e32 v96, v100, v104
	v_fmac_f32_e32 v97, v101, v105
	v_fmac_f32_e32 v98, v102, v106
	v_fmac_f32_e32 v99, v103, v107
	global_store_dwordx4 v65, v[96:99], s[20:21] offset:96
	v_readlane_b32 s0, v252, 22
	s_nop 3
	s_add_i32 s16, s16, s0
	s_cmp_ge_i32 s16, s41
	s_cbranch_scc1 .LBB0_2461
